# GEMM loops: saddr-form LDS-DMA for throw-away addresses (24 VALU 64-bit adds removed per iteration set), no setprio flips
# speedup vs baseline: 1.0187x; 1.0082x over previous
; #define PG8_STAGE(bufoff, gbase, voff) do { _Pragma("unroll") for (int _i = 0; _i < 2; ++_i) \
;         __builtin_amdgcn_global_load_lds((const unsigned*)((const char*)(gbase) + (voff)[_i]), (LAS unsigned*)(lds + (bufoff) + ldsw + _i * 8192), 16, 0, 0); } while (0)
; #define PG8_LDA(dst, b, h) do { _Pragma("unroll") for (int m = 0; m < 4; ++m) _Pragma("unroll") for (int k = 0; k < 2; ++k) dst[m][k] = *(const LAS h8*)(lds + PG8_SA(b, h) + aoff + m * 2048 + k * 1024); } while (0)
; #define PG8_LDB(dst, b, h) do { _Pragma("unroll") for (int n = 0; n < 2; ++n) _Pragma("unroll") for (int k = 0; k < 2; ++k) dst[n][k] = *(const LAS h8*)(lds + PG8_SB(b, h) + boff + n * 2048 + k * 1024); } while (0)
; #define PG8_WAIT_L(n) asm volatile("s_waitcnt lgkmcnt(" #n ")" ::: "memory")
; #define PG8_BAR __builtin_amdgcn_s_barrier()
; #define PG8_SCHED __builtin_amdgcn_sched_barrier(0)
; template <class Epi>
; __device__ __forceinline__ void gemm_phase(LAS unsigned char* lds, const Gemm g, const StaticOrder& S, const Epi& E, const int tid) {
;     ...
;         const bool has_next = S.next(ui + 1, nxt);
;         const char* nA = has_next ? (const char*)g.A + (size_t)nxt.pm * tstep : cA; const char* nB = has_next ? (const char*)g.Bt + (size_t)nxt.pn * tstep : cB;
;         for (int t = 0; t < nt; t += 2) {
;             const bool last = (t == nt - 2);
;             const char* a1 = cA + (size_t)(t + 1) * kstep;
;             const char* a2 = last ? nA : cA + (size_t)(t + 2) * kstep; const char* b2 = last ? nB : cB + (size_t)(t + 2) * kstep;
;             const char* a3 = a2 + kstep; const char* b3 = b2 + kstep;
;             if constexpr (Epi::HAS_MID) { if (t == (nt >> 1)) E.mid(acc, cur, wr, wc, fr, fq); }
;             PG8_LDB(B0, 0, 0); PG8_SCHED; PG8_LDA(At, 0, 0); PG8_STAGE(PG8_SA(1, 1), a1 + hstep, voffA);
;             PG8_WAIT_L(8); PG8_BAR; PG8_WAIT_L(0); PG8_MMA(0, 0, At, B0); PG8_BAR; PG8_SCHED;
;             PG8_LDB(B1, 0, 1); PG8_STAGE(PG8_SB(0, 0), b2, voffB);
;             PG8_BAR; PG8_WAIT_L(0); PG8_MMA(0, 1, At, B1); PG8_BAR;
;             PG8_LDA(At, 0, 1); PG8_STAGE(PG8_SA(0, 0), a2, voffA);
;             PG8_BAR; PG8_WAIT_L(0); PG8_MMA(1, 0, At, B0); PG8_BAR; PG8_SCHED;
.LBB0_332:
	s_add_u32 s18, s14, 0xfff80080
	s_addc_u32 s19, s15, -1
	s_add_i32 s55, 0, 0x10000
	v_add_u32_e32 v157, s55, v140
	ds_read_b128 v[144:147], v157
	ds_read_b128 v[162:165], v157 offset:1024
	ds_read_b128 v[166:169], v157 offset:2048
	ds_read_b128 v[170:173], v157 offset:3072
	s_cmp_eq_u32 s54, 28
	s_cselect_b32 s23, s9, s19
	s_cselect_b32 s22, s50, s18
	s_cselect_b32 s19, s1, s53
	s_cselect_b32 s18, s51, s52
	s_add_i32 m0, s39, 0xc000
	ds_read_b128 v[174:177], v143
	ds_read_b128 v[190:193], v143 offset:1024
	ds_read_b128 v[194:197], v143 offset:2048
	ds_read_b128 v[198:201], v143 offset:3072
	ds_read_b128 v[202:205], v143 offset:4096
	ds_read_b128 v[206:209], v143 offset:5120
	ds_read_b128 v[210:213], v143 offset:6144
	ds_read_b128 v[214:217], v143 offset:7168
	global_load_lds_dwordx4 v136, s[14:15]
	s_add_i32 m0, s39, 0xe000
	s_nop 0
	global_load_lds_dwordx4 v138, s[14:15]
	s_waitcnt lgkmcnt(8)
	s_barrier
	s_waitcnt lgkmcnt(0)
	s_waitcnt lgkmcnt(0)
	v_mfma_f32_16x16x32_bf16 v[124:127], v[144:147], v[174:177], v[124:127]
	v_mfma_f32_16x16x32_bf16 v[128:131], v[166:169], v[174:177], v[128:131]
	v_mfma_f32_16x16x32_bf16 v[108:111], v[144:147], v[194:197], v[108:111]
	v_mfma_f32_16x16x32_bf16 v[112:115], v[166:169], v[194:197], v[112:115]
	v_mfma_f32_16x16x32_bf16 v[92:95], v[144:147], v[202:205], v[92:95]
	v_mfma_f32_16x16x32_bf16 v[96:99], v[166:169], v[202:205], v[96:99]
	v_mfma_f32_16x16x32_bf16 v[76:79], v[144:147], v[210:213], v[76:79]
	v_mfma_f32_16x16x32_bf16 v[80:83], v[166:169], v[210:213], v[80:83]
	v_mfma_f32_16x16x32_bf16 v[124:127], v[162:165], v[190:193], v[124:127]
	v_mfma_f32_16x16x32_bf16 v[128:131], v[170:173], v[190:193], v[128:131]
	v_mfma_f32_16x16x32_bf16 v[108:111], v[162:165], v[198:201], v[108:111]
	v_mfma_f32_16x16x32_bf16 v[112:115], v[170:173], v[198:201], v[112:115]
	v_mfma_f32_16x16x32_bf16 v[92:95], v[162:165], v[206:209], v[92:95]
	v_mfma_f32_16x16x32_bf16 v[96:99], v[170:173], v[206:209], v[96:99]
	v_mfma_f32_16x16x32_bf16 v[76:79], v[162:165], v[214:217], v[76:79]
	v_mfma_f32_16x16x32_bf16 v[80:83], v[170:173], v[214:217], v[80:83]
	s_barrier
	s_add_i32 s58, 0, 0x14000
	s_add_i32 s55, s55, s38
	v_add_u32_e32 v157, s58, v140
	v_lshl_add_u64 v[178:179], s[18:19], 0, v[2:3]
	s_mov_b32 m0, s55
	ds_read_b128 v[218:221], v157
	ds_read_b128 v[222:225], v157 offset:1024
	ds_read_b128 v[226:229], v157 offset:2048
	ds_read_b128 v[230:233], v157 offset:3072
	global_load_lds_dwordx4 v[178:179], off
	v_lshl_add_u64 v[234:235], s[18:19], 0, v[0:1]
	s_add_i32 m0, s55, 0x2000
	s_nop 0
	global_load_lds_dwordx4 v[234:235], off
	s_barrier
	s_waitcnt lgkmcnt(0)
	s_waitcnt lgkmcnt(0)
	v_mfma_f32_16x16x32_bf16 v[116:119], v[218:221], v[174:177], v[116:119]
	v_mfma_f32_16x16x32_bf16 v[120:123], v[226:229], v[174:177], v[120:123]
	v_mfma_f32_16x16x32_bf16 v[100:103], v[218:221], v[194:197], v[100:103]
	v_mfma_f32_16x16x32_bf16 v[104:107], v[226:229], v[194:197], v[104:107]
	v_mfma_f32_16x16x32_bf16 v[84:87], v[218:221], v[202:205], v[84:87]
	v_mfma_f32_16x16x32_bf16 v[88:91], v[226:229], v[202:205], v[88:91]
	v_mfma_f32_16x16x32_bf16 v[68:71], v[218:221], v[210:213], v[68:71]
	v_mfma_f32_16x16x32_bf16 v[72:75], v[226:229], v[210:213], v[72:75]
	v_mfma_f32_16x16x32_bf16 v[116:119], v[222:225], v[190:193], v[116:119]
	v_mfma_f32_16x16x32_bf16 v[120:123], v[230:233], v[190:193], v[120:123]
	v_mfma_f32_16x16x32_bf16 v[100:103], v[222:225], v[198:201], v[100:103]
	v_mfma_f32_16x16x32_bf16 v[104:107], v[230:233], v[198:201], v[104:107]
	v_mfma_f32_16x16x32_bf16 v[84:87], v[222:225], v[206:209], v[84:87]
	v_mfma_f32_16x16x32_bf16 v[88:91], v[230:233], v[206:209], v[88:91]
	v_mfma_f32_16x16x32_bf16 v[68:71], v[222:225], v[214:217], v[68:71]
	v_mfma_f32_16x16x32_bf16 v[72:75], v[230:233], v[214:217], v[72:75]
	s_mov_b32 m0, s39
	v_lshl_add_u64 v[236:237], s[22:23], 0, v[134:135]
	s_barrier
	ds_read_b128 v[174:177], v143 offset:16384
	ds_read_b128 v[190:193], v143 offset:17408
	ds_read_b128 v[194:197], v143 offset:18432
	ds_read_b128 v[198:201], v143 offset:19456
	ds_read_b128 v[202:205], v143 offset:20480
	ds_read_b128 v[206:209], v143 offset:21504
	ds_read_b128 v[210:213], v143 offset:22528
	ds_read_b128 v[214:217], v143 offset:23552
	global_load_lds_dwordx4 v[236:237], off
	v_lshl_add_u64 v[238:239], s[22:23], 0, v[132:133]
	s_mov_b32 m0, s40
	s_nop 0
	global_load_lds_dwordx4 v[238:239], off
	s_barrier
	s_waitcnt lgkmcnt(0)
	s_waitcnt lgkmcnt(0)
	v_mfma_f32_16x16x32_bf16 v[60:63], v[144:147], v[174:177], v[60:63]
	v_mfma_f32_16x16x32_bf16 v[64:67], v[166:169], v[174:177], v[64:67]
	v_mfma_f32_16x16x32_bf16 v[44:47], v[144:147], v[194:197], v[44:47]
	v_mfma_f32_16x16x32_bf16 v[48:51], v[166:169], v[194:197], v[48:51]
	v_mfma_f32_16x16x32_bf16 v[28:31], v[144:147], v[202:205], v[28:31]
	v_mfma_f32_16x16x32_bf16 v[32:35], v[166:169], v[202:205], v[32:35]
	v_mfma_f32_16x16x32_bf16 v[12:15], v[144:147], v[210:213], v[12:15]
	v_mfma_f32_16x16x32_bf16 v[16:19], v[166:169], v[210:213], v[16:19]
	v_mfma_f32_16x16x32_bf16 v[60:63], v[162:165], v[190:193], v[60:63]
	v_mfma_f32_16x16x32_bf16 v[64:67], v[170:173], v[190:193], v[64:67]
	v_mfma_f32_16x16x32_bf16 v[44:47], v[162:165], v[198:201], v[44:47]
	v_mfma_f32_16x16x32_bf16 v[48:51], v[170:173], v[198:201], v[48:51]
	v_mfma_f32_16x16x32_bf16 v[28:31], v[162:165], v[206:209], v[28:31]
	v_mfma_f32_16x16x32_bf16 v[32:35], v[170:173], v[206:209], v[32:35]
	v_mfma_f32_16x16x32_bf16 v[12:15], v[162:165], v[214:217], v[12:15]
	v_mfma_f32_16x16x32_bf16 v[16:19], v[170:173], v[214:217], v[16:19]
	s_barrier
; #define PG8_STAGE(bufoff, gbase, voff) do { _Pragma("unroll") for (int _i = 0; _i < 2; ++_i) \
;         __builtin_amdgcn_global_load_lds((const unsigned*)((const char*)(gbase) + (voff)[_i]), (LAS unsigned*)(lds + (bufoff) + ldsw + _i * 8192), 16, 0, 0); } while (0)
; #define PG8_LDA(dst, b, h) do { _Pragma("unroll") for (int m = 0; m < 4; ++m) _Pragma("unroll") for (int k = 0; k < 2; ++k) dst[m][k] = *(const LAS h8*)(lds + PG8_SA(b, h) + aoff + m * 2048 + k * 1024); } while (0)
; #define PG8_LDB(dst, b, h) do { _Pragma("unroll") for (int n = 0; n < 2; ++n) _Pragma("unroll") for (int k = 0; k < 2; ++k) dst[n][k] = *(const LAS h8*)(lds + PG8_SB(b, h) + boff + n * 2048 + k * 1024); } while (0)
; #define PG8_WAIT_V(n) asm volatile("s_waitcnt vmcnt(" #n ")" ::: "memory")
; #define PG8_WAIT_L(n) asm volatile("s_waitcnt lgkmcnt(" #n ")" ::: "memory")
; #define PG8_BAR __builtin_amdgcn_s_barrier()
; #define PG8_SCHED __builtin_amdgcn_sched_barrier(0)
; template <class Epi>
; __device__ __forceinline__ void gemm_phase(LAS unsigned char* lds, const Gemm g, const StaticOrder& S, const Epi& E, const int tid) {
;     ...
;             PG8_STAGE(PG8_SB(0, 1), b2 + hstepB, voffB);
;             PG8_WAIT_V(6); PG8_BAR; PG8_MMA(1, 1, At, B1); PG8_BAR;
;             PG8_LDB(B0, 1, 0); PG8_SCHED; PG8_LDA(At, 1, 0); PG8_STAGE(PG8_SA(0, 1), a2 + hstep, voffA);
;             PG8_WAIT_L(8); PG8_BAR; PG8_WAIT_L(0); PG8_MMA(0, 0, At, B0); PG8_BAR; PG8_SCHED;
;             PG8_LDB(B1, 1, 1); PG8_STAGE(PG8_SB(1, 0), b3, voffB);
;             PG8_BAR; PG8_WAIT_L(0); PG8_MMA(0, 1, At, B1); PG8_BAR;
;             PG8_LDA(At, 1, 1); PG8_STAGE(PG8_SA(1, 0), a3, voffA);
	s_add_u32 s56, s18, 0x20000
	s_addc_u32 s57, s19, 0
	s_add_i32 s55, s58, s38
	s_mov_b32 m0, s55
	s_nop 0
	global_load_lds_dwordx4 v2, s[56:57]
	s_add_i32 m0, s55, 0x2000
	s_nop 0
	global_load_lds_dwordx4 v0, s[56:57]
	s_waitcnt vmcnt(6)
	s_barrier
	v_mfma_f32_16x16x32_bf16 v[52:55], v[218:221], v[174:177], v[52:55]
	v_mfma_f32_16x16x32_bf16 v[56:59], v[226:229], v[174:177], v[56:59]
	v_mfma_f32_16x16x32_bf16 v[36:39], v[218:221], v[194:197], v[36:39]
	v_mfma_f32_16x16x32_bf16 v[40:43], v[226:229], v[194:197], v[40:43]
	v_mfma_f32_16x16x32_bf16 v[20:23], v[218:221], v[202:205], v[20:23]
	v_mfma_f32_16x16x32_bf16 v[24:27], v[226:229], v[202:205], v[24:27]
	v_mfma_f32_16x16x32_bf16 v[8:11], v[218:221], v[210:213], v[8:11]
	v_mfma_f32_16x16x32_bf16 v[4:7], v[226:229], v[210:213], v[4:7]
	v_mfma_f32_16x16x32_bf16 v[52:55], v[222:225], v[190:193], v[52:55]
	v_mfma_f32_16x16x32_bf16 v[56:59], v[230:233], v[190:193], v[56:59]
	v_mfma_f32_16x16x32_bf16 v[36:39], v[222:225], v[198:201], v[36:39]
	v_mfma_f32_16x16x32_bf16 v[40:43], v[230:233], v[198:201], v[40:43]
	v_mfma_f32_16x16x32_bf16 v[20:23], v[222:225], v[206:209], v[20:23]
	v_mfma_f32_16x16x32_bf16 v[24:27], v[230:233], v[206:209], v[24:27]
	v_mfma_f32_16x16x32_bf16 v[8:11], v[222:225], v[214:217], v[8:11]
	v_mfma_f32_16x16x32_bf16 v[4:7], v[230:233], v[214:217], v[4:7]
	s_add_i32 s55, 0, 0x18000
	v_add_u32_e32 v157, s55, v140
	s_barrier
	ds_read_b128 v[144:147], v157
	ds_read_b128 v[162:165], v157 offset:1024
	ds_read_b128 v[166:169], v157 offset:2048
	ds_read_b128 v[170:173], v157 offset:3072
	s_add_u32 s22, s22, 0x80000
	s_addc_u32 s23, s23, 0
	s_mov_b32 m0, s41
	ds_read_b128 v[174:177], v143 offset:32768
	ds_read_b128 v[190:193], v143 offset:33792
	ds_read_b128 v[194:197], v143 offset:34816
	ds_read_b128 v[198:201], v143 offset:35840
	ds_read_b128 v[202:205], v143 offset:36864
	ds_read_b128 v[206:209], v143 offset:37888
	ds_read_b128 v[210:213], v143 offset:38912
	ds_read_b128 v[214:217], v143 offset:39936
	global_load_lds_dwordx4 v134, s[22:23]
	s_mov_b32 m0, s42
	s_nop 0
	global_load_lds_dwordx4 v132, s[22:23]
	s_waitcnt lgkmcnt(8)
	s_barrier
	s_waitcnt lgkmcnt(0)
	s_waitcnt lgkmcnt(0)
	v_mfma_f32_16x16x32_bf16 v[124:127], v[144:147], v[174:177], v[124:127]
	v_mfma_f32_16x16x32_bf16 v[128:131], v[166:169], v[174:177], v[128:131]
	v_mfma_f32_16x16x32_bf16 v[108:111], v[144:147], v[194:197], v[108:111]
	v_mfma_f32_16x16x32_bf16 v[112:115], v[166:169], v[194:197], v[112:115]
	v_mfma_f32_16x16x32_bf16 v[92:95], v[144:147], v[202:205], v[92:95]
	v_mfma_f32_16x16x32_bf16 v[96:99], v[166:169], v[202:205], v[96:99]
	v_mfma_f32_16x16x32_bf16 v[76:79], v[144:147], v[210:213], v[76:79]
	v_mfma_f32_16x16x32_bf16 v[80:83], v[166:169], v[210:213], v[80:83]
	v_mfma_f32_16x16x32_bf16 v[124:127], v[162:165], v[190:193], v[124:127]
	v_mfma_f32_16x16x32_bf16 v[128:131], v[170:173], v[190:193], v[128:131]
	v_mfma_f32_16x16x32_bf16 v[108:111], v[162:165], v[198:201], v[108:111]
	v_mfma_f32_16x16x32_bf16 v[112:115], v[170:173], v[198:201], v[112:115]
	v_mfma_f32_16x16x32_bf16 v[92:95], v[162:165], v[206:209], v[92:95]
	v_mfma_f32_16x16x32_bf16 v[96:99], v[170:173], v[206:209], v[96:99]
	v_mfma_f32_16x16x32_bf16 v[76:79], v[162:165], v[214:217], v[76:79]
	v_mfma_f32_16x16x32_bf16 v[80:83], v[170:173], v[214:217], v[80:83]
	s_barrier
	s_add_i32 s22, 0, 0x1c000
	s_add_i32 s23, s55, s38
	v_add_u32_e32 v157, s22, v140
	v_lshl_add_u64 v[178:179], v[178:179], 0, s[30:31]
	s_mov_b32 m0, s23
	ds_read_b128 v[218:221], v157
	ds_read_b128 v[222:225], v157 offset:1024
	ds_read_b128 v[226:229], v157 offset:2048
	ds_read_b128 v[230:233], v157 offset:3072
	global_load_lds_dwordx4 v[178:179], off
	v_lshl_add_u64 v[178:179], v[234:235], 0, s[30:31]
	s_add_i32 m0, s23, 0x2000
	s_nop 0
	global_load_lds_dwordx4 v[178:179], off
	s_barrier
	s_waitcnt lgkmcnt(0)
	s_waitcnt lgkmcnt(0)
	v_mfma_f32_16x16x32_bf16 v[116:119], v[218:221], v[174:177], v[116:119]
	v_mfma_f32_16x16x32_bf16 v[120:123], v[226:229], v[174:177], v[120:123]
	v_mfma_f32_16x16x32_bf16 v[100:103], v[218:221], v[194:197], v[100:103]
	v_mfma_f32_16x16x32_bf16 v[104:107], v[226:229], v[194:197], v[104:107]
	v_mfma_f32_16x16x32_bf16 v[84:87], v[218:221], v[202:205], v[84:87]
	v_mfma_f32_16x16x32_bf16 v[88:91], v[226:229], v[202:205], v[88:91]
	v_mfma_f32_16x16x32_bf16 v[68:71], v[218:221], v[210:213], v[68:71]
	v_mfma_f32_16x16x32_bf16 v[72:75], v[226:229], v[210:213], v[72:75]
	v_mfma_f32_16x16x32_bf16 v[116:119], v[222:225], v[190:193], v[116:119]
	v_mfma_f32_16x16x32_bf16 v[120:123], v[230:233], v[190:193], v[120:123]
	v_mfma_f32_16x16x32_bf16 v[100:103], v[222:225], v[198:201], v[100:103]
	v_mfma_f32_16x16x32_bf16 v[104:107], v[230:233], v[198:201], v[104:107]
	v_mfma_f32_16x16x32_bf16 v[84:87], v[222:225], v[206:209], v[84:87]
	v_mfma_f32_16x16x32_bf16 v[88:91], v[230:233], v[206:209], v[88:91]
	v_mfma_f32_16x16x32_bf16 v[68:71], v[222:225], v[214:217], v[68:71]
	v_mfma_f32_16x16x32_bf16 v[72:75], v[230:233], v[214:217], v[72:75]
	s_mov_b32 m0, s43
	v_lshl_add_u64 v[178:179], v[236:237], 0, s[30:31]
	s_barrier
	ds_read_b128 v[174:177], v143 offset:49152
	ds_read_b128 v[190:193], v143 offset:50176
	ds_read_b128 v[194:197], v143 offset:51200
	ds_read_b128 v[198:201], v143 offset:52224
	ds_read_b128 v[202:205], v143 offset:53248
	ds_read_b128 v[206:209], v143 offset:54272
	ds_read_b128 v[210:213], v143 offset:55296
	ds_read_b128 v[214:217], v143 offset:56320
	global_load_lds_dwordx4 v[178:179], off
	v_lshl_add_u64 v[178:179], v[238:239], 0, s[30:31]
	s_mov_b32 m0, s46
	s_nop 0
	global_load_lds_dwordx4 v[178:179], off
	s_barrier
; #define PG8_STAGE(bufoff, gbase, voff) do { _Pragma("unroll") for (int _i = 0; _i < 2; ++_i) \
;         __builtin_amdgcn_global_load_lds((const unsigned*)((const char*)(gbase) + (voff)[_i]), (LAS unsigned*)(lds + (bufoff) + ldsw + _i * 8192), 16, 0, 0); } while (0)
; #define PG8_WAIT_V(n) asm volatile("s_waitcnt vmcnt(" #n ")" ::: "memory")
; #define PG8_WAIT_L(n) asm volatile("s_waitcnt lgkmcnt(" #n ")" ::: "memory")
; #define PG8_BAR __builtin_amdgcn_s_barrier()
; #define PG8_SCHED __builtin_amdgcn_sched_barrier(0)
; template <class Epi>
; __device__ __forceinline__ void gemm_phase(LAS unsigned char* lds, const Gemm g, const StaticOrder& S, const Epi& E, const int tid) {
;     ...
;             PG8_BAR; PG8_WAIT_L(0); PG8_MMA(1, 0, At, B0); PG8_BAR; PG8_SCHED;
;             PG8_STAGE(PG8_SB(1, 1), b3 + hstepB, voffB);
;             PG8_WAIT_V(6); PG8_BAR; PG8_MMA(1, 1, At, B1); PG8_BAR;
;     __device__ __forceinline__ void operator()(f32x4 (&acc)[2][2][4][2], const pg8::Unit& u, int wr, int wc, int fr, int fq) const {
;         const bool hi = fr >= 8;
;         const int row0 = u.pm * 256 + wr * 64 + (fr & 7), col = u.pn * 256 + wc * 64 + fq * 8 + (hi ? 32 : 0);
; #pragma unroll
;         for (int ai = 0; ai < 2; ++ai)
; #pragma unroll
;             for (int m = 0; m < 4; ++m) {
;                 const h8 x0 = pack8(acc[ai][0][m][0], acc[ai][0][m][1]), x1 = pack8(acc[ai][1][m][0], acc[ai][1][m][1]);
;                 const i32x4 snd = hi ? __builtin_bit_cast(i32x4, x0) : __builtin_bit_cast(i32x4, x1);
;                 i32x4 rcv;
; #pragma unroll
;                 for (int d = 0; d < 4; ++d) rcv[d] = __builtin_amdgcn_update_dpp(0, snd[d], 0x128  , 0xF, 0xF, false);
;                 const h8 rv = __builtin_bit_cast(h8, rcv);
;                 const h8 vA = hi ? rv : x0;
;                 const h8 vB = hi ? x1 : rv;
;                 half_t* rowp = O + (size_t)(row0 + ai * 128 + m * 16) * NIN + col;
;                 __builtin_nontemporal_store(vA, (h8*)rowp); __builtin_nontemporal_store(vB, (h8*)(rowp + (size_t)8 * NIN)); }
	s_waitcnt lgkmcnt(0)
	s_waitcnt lgkmcnt(0)
	v_mfma_f32_16x16x32_bf16 v[60:63], v[144:147], v[174:177], v[60:63]
	v_mfma_f32_16x16x32_bf16 v[64:67], v[166:169], v[174:177], v[64:67]
	v_mfma_f32_16x16x32_bf16 v[44:47], v[144:147], v[194:197], v[44:47]
	v_mfma_f32_16x16x32_bf16 v[48:51], v[166:169], v[194:197], v[48:51]
	v_mfma_f32_16x16x32_bf16 v[28:31], v[144:147], v[202:205], v[28:31]
	v_mfma_f32_16x16x32_bf16 v[32:35], v[166:169], v[202:205], v[32:35]
	v_mfma_f32_16x16x32_bf16 v[12:15], v[144:147], v[210:213], v[12:15]
	v_mfma_f32_16x16x32_bf16 v[16:19], v[166:169], v[210:213], v[16:19]
	v_mfma_f32_16x16x32_bf16 v[60:63], v[162:165], v[190:193], v[60:63]
	v_mfma_f32_16x16x32_bf16 v[64:67], v[170:173], v[190:193], v[64:67]
	v_mfma_f32_16x16x32_bf16 v[44:47], v[162:165], v[198:201], v[44:47]
	v_mfma_f32_16x16x32_bf16 v[48:51], v[170:173], v[198:201], v[48:51]
	v_mfma_f32_16x16x32_bf16 v[28:31], v[162:165], v[206:209], v[28:31]
	v_mfma_f32_16x16x32_bf16 v[32:35], v[170:173], v[206:209], v[32:35]
	v_mfma_f32_16x16x32_bf16 v[12:15], v[162:165], v[214:217], v[12:15]
	v_mfma_f32_16x16x32_bf16 v[16:19], v[170:173], v[214:217], v[16:19]
	s_barrier
	s_add_u32 s18, s18, 0x20080
	s_addc_u32 s19, s19, 0
	s_add_i32 s22, s22, s38
	s_mov_b32 m0, s22
	s_nop 0
	global_load_lds_dwordx4 v2, s[18:19]
	v_lshl_add_u64 v[144:145], s[18:19], 0, v[0:1]
	s_add_i32 m0, s22, 0x2000
	s_nop 0
	global_load_lds_dwordx4 v[144:145], off
	s_waitcnt vmcnt(6)
	s_barrier
	v_mfma_f32_16x16x32_bf16 v[52:55], v[218:221], v[174:177], v[52:55]
	v_mfma_f32_16x16x32_bf16 v[56:59], v[226:229], v[174:177], v[56:59]
	v_mfma_f32_16x16x32_bf16 v[36:39], v[218:221], v[194:197], v[36:39]
	v_mfma_f32_16x16x32_bf16 v[40:43], v[226:229], v[194:197], v[40:43]
	v_mfma_f32_16x16x32_bf16 v[20:23], v[218:221], v[202:205], v[20:23]
	v_mfma_f32_16x16x32_bf16 v[24:27], v[226:229], v[202:205], v[24:27]
	v_mfma_f32_16x16x32_bf16 v[8:11], v[218:221], v[210:213], v[8:11]
	v_mfma_f32_16x16x32_bf16 v[4:7], v[226:229], v[210:213], v[4:7]
	v_mfma_f32_16x16x32_bf16 v[52:55], v[222:225], v[190:193], v[52:55]
	v_mfma_f32_16x16x32_bf16 v[56:59], v[230:233], v[190:193], v[56:59]
	v_mfma_f32_16x16x32_bf16 v[36:39], v[222:225], v[198:201], v[36:39]
	v_mfma_f32_16x16x32_bf16 v[40:43], v[230:233], v[198:201], v[40:43]
	v_mfma_f32_16x16x32_bf16 v[20:23], v[222:225], v[206:209], v[20:23]
	v_mfma_f32_16x16x32_bf16 v[24:27], v[230:233], v[206:209], v[24:27]
	v_mfma_f32_16x16x32_bf16 v[8:11], v[222:225], v[214:217], v[8:11]
	v_mfma_f32_16x16x32_bf16 v[4:7], v[230:233], v[214:217], v[4:7]
	s_add_i32 s54, s54, 2
	s_add_u32 s14, s14, 0x100
	s_addc_u32 s15, s15, 0
	s_add_u32 s52, s52, 0x100
	s_addc_u32 s53, s53, 0
	s_cmp_gt_u32 s54, 29
	s_barrier
	s_cbranch_scc0 .LBB0_332
	v_cvt_pk_f16_f32 v124, v124, v125
	v_cvt_pk_f16_f32 v116, v116, v117
	v_cvt_pk_f16_f32 v130, v130, v131
	v_cvt_pk_f16_f32 v131, v122, v123
	v_cvt_pk_f16_f32 v128, v128, v129
	v_cvt_pk_f16_f32 v129, v120, v121
	v_cvt_pk_f16_f32 v121, v126, v127
	v_cvt_pk_f16_f32 v118, v118, v119
	v_cndmask_b32_e64 v117, v116, v124, s[4:5]
	v_mov_b32_e32 v147, v3
	v_cndmask_b32_e64 v122, v131, v130, s[4:5]
	v_cndmask_b32_e64 v119, v118, v121, s[4:5]
	v_mov_b32_dpp v147, v117 row_ror:8 row_mask:0xf bank_mask:0xf
	v_mov_b32_e32 v117, v3
	v_mov_b32_e32 v125, v3
	v_lshl_or_b32 v144, s48, 8, v142
	v_cndmask_b32_e64 v120, v129, v128, s[4:5]
	v_mov_b32_dpp v117, v119 row_ror:8 row_mask:0xf bank_mask:0xf
	v_mov_b32_e32 v119, v3
	v_mov_b32_dpp v125, v122 row_ror:8 row_mask:0xf bank_mask:0xf
	v_lshl_add_u32 v146, s49, 8, v141
	v_ashrrev_i32_e32 v145, 31, v144
	v_mov_b32_dpp v119, v120 row_ror:8 row_mask:0xf bank_mask:0xf
	v_cndmask_b32_e64 v123, v130, v125, s[4:5]
	v_cndmask_b32_e64 v121, v121, v117, s[4:5]
	v_cndmask_b32_e64 v120, v124, v147, s[4:5]
	v_cndmask_b32_e64 v127, v125, v131, s[4:5]
	v_cndmask_b32_e64 v125, v117, v118, s[4:5]
	v_cndmask_b32_e64 v124, v147, v116, s[4:5]
	v_mov_b64_e32 v[116:117], s[36:37]
	v_cndmask_b32_e64 v122, v128, v119, s[4:5]
	v_cndmask_b32_e64 v126, v119, v129, s[4:5]
	v_mad_i64_i32 v[128:129], s[14:15], v146, s35, v[116:117]
	v_lshlrev_b64 v[118:119], 1, v[144:145]
	v_lshl_add_u64 v[128:129], v[128:129], 0, v[118:119]
	s_mov_b32 s1, 0x3c000
	global_store_dwordx4 v[128:129], v[120:123], off nt
	v_cvt_pk_f16_f32 v112, v112, v113
	v_cvt_pk_f16_f32 v104, v104, v105
	v_add_co_u32_e32 v120, vcc, s1, v128
	v_cvt_pk_f16_f32 v108, v108, v109
	s_nop 0
	v_addc_co_u32_e32 v121, vcc, 0, v129, vcc
	v_cvt_pk_f16_f32 v109, v100, v101
	global_store_dwordx4 v[120:121], v[124:127], off nt
	v_cvt_pk_f16_f32 v114, v114, v115
	v_cvt_pk_f16_f32 v106, v106, v107
	v_cndmask_b32_e64 v105, v104, v112, s[4:5]
	v_cndmask_b32_e64 v100, v109, v108, s[4:5]
	v_mov_b32_e32 v113, v3
	v_mov_b32_e32 v120, v3
	v_cndmask_b32_e64 v107, v106, v114, s[4:5]
	v_cvt_pk_f16_f32 v110, v110, v111
	v_cvt_pk_f16_f32 v111, v102, v103
	v_mov_b32_dpp v113, v100 row_ror:8 row_mask:0xf bank_mask:0xf
	v_mov_b32_dpp v120, v105 row_ror:8 row_mask:0xf bank_mask:0xf
	v_mov_b32_e32 v105, v3
	v_cndmask_b32_e64 v102, v111, v110, s[4:5]
	v_mov_b32_e32 v115, v3
	v_mov_b32_dpp v105, v107 row_ror:8 row_mask:0xf bank_mask:0xf
	v_cndmask_b32_e64 v100, v108, v113, s[4:5]
	v_or_b32_e32 v108, 16, v146
	v_mov_b32_dpp v115, v102 row_ror:8 row_mask:0xf bank_mask:0xf
	v_cndmask_b32_e64 v107, v105, v106, s[4:5]
	v_cndmask_b32_e64 v106, v120, v104, s[4:5]
	v_cndmask_b32_e64 v104, v113, v109, s[4:5]
	v_mad_i64_i32 v[108:109], s[14:15], v108, s35, v[116:117]
	v_cndmask_b32_e64 v103, v114, v105, s[4:5]
	v_cndmask_b32_e64 v102, v112, v120, s[4:5]
	v_cndmask_b32_e64 v101, v110, v115, s[4:5]
	v_lshl_add_u64 v[108:109], v[108:109], 0, v[118:119]
;     __device__ __forceinline__ void operator()(f32x4 (&acc)[2][2][4][2], const pg8::Unit& u, int wr, int wc, int fr, int fq) const {
;     ...
;         for (int ai = 0; ai < 2; ++ai)
; #pragma unroll
;             for (int m = 0; m < 4; ++m) {
;                 const h8 x0 = pack8(acc[ai][0][m][0], acc[ai][0][m][1]), x1 = pack8(acc[ai][1][m][0], acc[ai][1][m][1]);
;                 const i32x4 snd = hi ? __builtin_bit_cast(i32x4, x0) : __builtin_bit_cast(i32x4, x1);
;                 i32x4 rcv;
; #pragma unroll
;                 for (int d = 0; d < 4; ++d) rcv[d] = __builtin_amdgcn_update_dpp(0, snd[d], 0x128  , 0xF, 0xF, false);
;                 const h8 rv = __builtin_bit_cast(h8, rcv);
;                 const h8 vA = hi ? rv : x0;
;                 const h8 vB = hi ? x1 : rv;
;                 half_t* rowp = O + (size_t)(row0 + ai * 128 + m * 16) * NIN + col;
;                 __builtin_nontemporal_store(vA, (h8*)rowp); __builtin_nontemporal_store(vB, (h8*)(rowp + (size_t)8 * NIN)); }
	global_store_dwordx4 v[108:109], v[100:103], off nt
	v_cndmask_b32_e64 v105, v115, v111, s[4:5]
	v_cvt_pk_f16_f32 v96, v96, v97
	v_add_co_u32_e32 v100, vcc, s1, v108
	v_cvt_pk_f16_f32 v88, v88, v89
	s_nop 0
	v_addc_co_u32_e32 v101, vcc, 0, v109, vcc
	v_cvt_pk_f16_f32 v92, v92, v93
	v_cvt_pk_f16_f32 v93, v84, v85
	global_store_dwordx4 v[100:101], v[104:107], off nt
	v_cvt_pk_f16_f32 v98, v98, v99
	v_cvt_pk_f16_f32 v90, v90, v91
	v_cndmask_b32_e64 v89, v88, v96, s[4:5]
	v_cndmask_b32_e64 v84, v93, v92, s[4:5]
	v_mov_b32_e32 v97, v3
	v_mov_b32_e32 v100, v3
	v_cndmask_b32_e64 v91, v90, v98, s[4:5]
	v_cvt_pk_f16_f32 v94, v94, v95
	v_cvt_pk_f16_f32 v95, v86, v87
	v_mov_b32_dpp v97, v84 row_ror:8 row_mask:0xf bank_mask:0xf
	v_mov_b32_dpp v100, v89 row_ror:8 row_mask:0xf bank_mask:0xf
	v_mov_b32_e32 v89, v3
	v_cndmask_b32_e64 v86, v95, v94, s[4:5]
	v_mov_b32_e32 v99, v3
	v_mov_b32_dpp v89, v91 row_ror:8 row_mask:0xf bank_mask:0xf
	v_cndmask_b32_e64 v84, v92, v97, s[4:5]
	v_or_b32_e32 v92, 32, v146
	v_mov_b32_dpp v99, v86 row_ror:8 row_mask:0xf bank_mask:0xf
	v_cndmask_b32_e64 v91, v89, v90, s[4:5]
	v_cndmask_b32_e64 v90, v100, v88, s[4:5]
	v_cndmask_b32_e64 v88, v97, v93, s[4:5]
	v_mad_i64_i32 v[92:93], s[14:15], v92, s35, v[116:117]
	v_cndmask_b32_e64 v87, v98, v89, s[4:5]
	v_cndmask_b32_e64 v86, v96, v100, s[4:5]
	v_cndmask_b32_e64 v85, v94, v99, s[4:5]
	v_lshl_add_u64 v[92:93], v[92:93], 0, v[118:119]
	global_store_dwordx4 v[92:93], v[84:87], off nt
	v_cndmask_b32_e64 v89, v99, v95, s[4:5]
	v_cvt_pk_f16_f32 v80, v80, v81
	v_add_co_u32_e32 v84, vcc, s1, v92
	v_cvt_pk_f16_f32 v72, v72, v73
	s_nop 0
	v_addc_co_u32_e32 v85, vcc, 0, v93, vcc
	v_cvt_pk_f16_f32 v76, v76, v77
	v_cvt_pk_f16_f32 v77, v68, v69
	global_store_dwordx4 v[84:85], v[88:91], off nt
	v_cvt_pk_f16_f32 v82, v82, v83
	v_cvt_pk_f16_f32 v74, v74, v75
	v_cndmask_b32_e64 v73, v72, v80, s[4:5]
	v_cndmask_b32_e64 v68, v77, v76, s[4:5]
	v_mov_b32_e32 v81, v3
	v_mov_b32_e32 v84, v3
	v_cndmask_b32_e64 v75, v74, v82, s[4:5]
	v_cvt_pk_f16_f32 v78, v78, v79
	v_cvt_pk_f16_f32 v79, v70, v71
	v_mov_b32_dpp v81, v68 row_ror:8 row_mask:0xf bank_mask:0xf
	v_mov_b32_dpp v84, v73 row_ror:8 row_mask:0xf bank_mask:0xf
	v_mov_b32_e32 v73, v3
	v_cndmask_b32_e64 v70, v79, v78, s[4:5]
	v_mov_b32_e32 v83, v3
	v_mov_b32_dpp v73, v75 row_ror:8 row_mask:0xf bank_mask:0xf
	v_cndmask_b32_e64 v68, v76, v81, s[4:5]
	v_or_b32_e32 v76, 48, v146
	v_mov_b32_dpp v83, v70 row_ror:8 row_mask:0xf bank_mask:0xf
	v_cndmask_b32_e64 v75, v73, v74, s[4:5]
	v_cndmask_b32_e64 v74, v84, v72, s[4:5]
	v_cndmask_b32_e64 v72, v81, v77, s[4:5]
	v_mad_i64_i32 v[76:77], s[14:15], v76, s35, v[116:117]
	v_cndmask_b32_e64 v71, v82, v73, s[4:5]
	v_cndmask_b32_e64 v70, v80, v84, s[4:5]
	v_cndmask_b32_e64 v69, v78, v83, s[4:5]
	v_lshl_add_u64 v[76:77], v[76:77], 0, v[118:119]
	global_store_dwordx4 v[76:77], v[68:71], off nt
	v_cndmask_b32_e64 v73, v83, v79, s[4:5]
	v_cvt_pk_f16_f32 v64, v64, v65
	v_add_co_u32_e32 v68, vcc, s1, v76
	v_cvt_pk_f16_f32 v56, v56, v57
	s_nop 0
	v_addc_co_u32_e32 v69, vcc, 0, v77, vcc
	global_store_dwordx4 v[68:69], v[72:75], off nt
	v_cvt_pk_f16_f32 v66, v66, v67
	v_cvt_pk_f16_f32 v58, v58, v59
	v_cndmask_b32_e64 v57, v56, v64, s[4:5]
	v_cvt_pk_f16_f32 v60, v60, v61
	v_cvt_pk_f16_f32 v61, v52, v53
	v_mov_b32_e32 v69, v3
	v_cndmask_b32_e64 v59, v58, v66, s[4:5]
	v_cvt_pk_f16_f32 v62, v62, v63
	v_cvt_pk_f16_f32 v63, v54, v55
	v_cndmask_b32_e64 v52, v61, v60, s[4:5]
	v_mov_b32_e32 v65, v3
	v_mov_b32_dpp v69, v57 row_ror:8 row_mask:0xf bank_mask:0xf
	v_mov_b32_e32 v57, v3
	v_add_u32_e32 v68, 0x80, v146
	v_cndmask_b32_e64 v54, v63, v62, s[4:5]
	v_mov_b32_dpp v65, v52 row_ror:8 row_mask:0xf bank_mask:0xf
	v_mov_b32_e32 v67, v3
	v_mov_b32_dpp v57, v59 row_ror:8 row_mask:0xf bank_mask:0xf
	v_cndmask_b32_e64 v52, v60, v65, s[4:5]
	v_mov_b32_dpp v67, v54 row_ror:8 row_mask:0xf bank_mask:0xf
	v_cndmask_b32_e64 v59, v57, v58, s[4:5]
	v_cndmask_b32_e64 v58, v69, v56, s[4:5]
	v_cndmask_b32_e64 v56, v65, v61, s[4:5]
	v_mad_i64_i32 v[60:61], s[14:15], v68, s35, v[116:117]
	v_cndmask_b32_e64 v55, v66, v57, s[4:5]
	v_cndmask_b32_e64 v54, v64, v69, s[4:5]
	v_cndmask_b32_e64 v53, v62, v67, s[4:5]
	v_lshl_add_u64 v[60:61], v[60:61], 0, v[118:119]
	global_store_dwordx4 v[60:61], v[52:55], off nt
	v_cndmask_b32_e64 v57, v67, v63, s[4:5]
	v_cvt_pk_f16_f32 v48, v48, v49
	v_add_co_u32_e32 v52, vcc, s1, v60
	v_cvt_pk_f16_f32 v40, v40, v41
	s_nop 0
	v_addc_co_u32_e32 v53, vcc, 0, v61, vcc
	v_cvt_pk_f16_f32 v44, v44, v45
	v_cvt_pk_f16_f32 v45, v36, v37
; #define PG8_WAIT_V(n) asm volatile("s_waitcnt vmcnt(" #n ")" ::: "memory")
; #define PG8_BAR __builtin_amdgcn_s_barrier()
; template <class Epi>
; __device__ __forceinline__ void gemm_phase(LAS unsigned char* lds, const Gemm g, const StaticOrder& S, const Epi& E, const int tid) {
;     ...
;         if (!has_next) break;
; #pragma unroll
;         for (int a = 0; a < 2; ++a)
; #pragma unroll
;             for (int b = 0; b < 2; ++b)
; #pragma unroll
;                 for (int m = 0; m < 4; ++m)
; #pragma unroll
;                     for (int n = 0; n < 2; ++n) acc[a][b][m][n] = (f32x4){0.f, 0.f, 0.f, 0.f};
;         cur = nxt; cA = nA; cB = nB; ++ui;
;     }
;     PG8_WAIT_V(0);
;     if (wr == 0) PG8_BAR;
;     PG8_BAR;
;     __device__ __forceinline__ void operator()(f32x4 (&acc)[2][2][4][2], const pg8::Unit& u, int wr, int wc, int fr, int fq) const {
;     ...
;         for (int ai = 0; ai < 2; ++ai)
; #pragma unroll
;             for (int m = 0; m < 4; ++m) {
;                 const h8 x0 = pack8(acc[ai][0][m][0], acc[ai][0][m][1]), x1 = pack8(acc[ai][1][m][0], acc[ai][1][m][1]);
;                 const i32x4 snd = hi ? __builtin_bit_cast(i32x4, x0) : __builtin_bit_cast(i32x4, x1);
;                 i32x4 rcv;
; #pragma unroll
;                 for (int d = 0; d < 4; ++d) rcv[d] = __builtin_amdgcn_update_dpp(0, snd[d], 0x128  , 0xF, 0xF, false);
;                 const h8 rv = __builtin_bit_cast(h8, rcv);
;                 const h8 vA = hi ? rv : x0;
;                 const h8 vB = hi ? x1 : rv;
;                 half_t* rowp = O + (size_t)(row0 + ai * 128 + m * 16) * NIN + col;
;                 __builtin_nontemporal_store(vA, (h8*)rowp); __builtin_nontemporal_store(vB, (h8*)(rowp + (size_t)8 * NIN)); }
	global_store_dwordx4 v[52:53], v[56:59], off nt
	v_cvt_pk_f16_f32 v50, v50, v51
	v_cvt_pk_f16_f32 v42, v42, v43
	v_cndmask_b32_e64 v41, v40, v48, s[4:5]
	v_cndmask_b32_e64 v36, v45, v44, s[4:5]
	v_mov_b32_e32 v49, v3
	v_mov_b32_e32 v52, v3
	v_cndmask_b32_e64 v43, v42, v50, s[4:5]
	v_cvt_pk_f16_f32 v46, v46, v47
	v_cvt_pk_f16_f32 v47, v38, v39
	v_mov_b32_dpp v49, v36 row_ror:8 row_mask:0xf bank_mask:0xf
	v_mov_b32_dpp v52, v41 row_ror:8 row_mask:0xf bank_mask:0xf
	v_mov_b32_e32 v41, v3
	v_cndmask_b32_e64 v38, v47, v46, s[4:5]
	v_mov_b32_e32 v51, v3
	v_mov_b32_dpp v41, v43 row_ror:8 row_mask:0xf bank_mask:0xf
	v_cndmask_b32_e64 v36, v44, v49, s[4:5]
	v_add_u32_e32 v44, 0x90, v146
	v_mov_b32_dpp v51, v38 row_ror:8 row_mask:0xf bank_mask:0xf
	v_cndmask_b32_e64 v43, v41, v42, s[4:5]
	v_cndmask_b32_e64 v42, v52, v40, s[4:5]
	v_cndmask_b32_e64 v40, v49, v45, s[4:5]
	v_mad_i64_i32 v[44:45], s[14:15], v44, s35, v[116:117]
	v_cndmask_b32_e64 v39, v50, v41, s[4:5]
	v_cndmask_b32_e64 v38, v48, v52, s[4:5]
	v_cndmask_b32_e64 v37, v46, v51, s[4:5]
	v_lshl_add_u64 v[44:45], v[44:45], 0, v[118:119]
	global_store_dwordx4 v[44:45], v[36:39], off nt
	v_cndmask_b32_e64 v41, v51, v47, s[4:5]
	v_cvt_pk_f16_f32 v32, v32, v33
	v_add_co_u32_e32 v36, vcc, s1, v44
	v_cvt_pk_f16_f32 v24, v24, v25
	s_nop 0
	v_addc_co_u32_e32 v37, vcc, 0, v45, vcc
	v_cvt_pk_f16_f32 v28, v28, v29
	v_cvt_pk_f16_f32 v29, v20, v21
	global_store_dwordx4 v[36:37], v[40:43], off nt
	v_cvt_pk_f16_f32 v34, v34, v35
	v_cvt_pk_f16_f32 v26, v26, v27
	v_cndmask_b32_e64 v25, v24, v32, s[4:5]
	v_cndmask_b32_e64 v20, v29, v28, s[4:5]
	v_mov_b32_e32 v33, v3
	v_mov_b32_e32 v36, v3
	v_cndmask_b32_e64 v27, v26, v34, s[4:5]
	v_cvt_pk_f16_f32 v30, v30, v31
	v_cvt_pk_f16_f32 v31, v22, v23
	v_mov_b32_dpp v33, v20 row_ror:8 row_mask:0xf bank_mask:0xf
	v_mov_b32_dpp v36, v25 row_ror:8 row_mask:0xf bank_mask:0xf
	v_mov_b32_e32 v25, v3
	v_cvt_pk_f16_f32 v16, v16, v17
	v_cvt_pk_f16_f32 v17, v4, v5
	v_cvt_pk_f16_f32 v5, v14, v15
	v_cvt_pk_f16_f32 v14, v10, v11
	v_cvt_pk_f16_f32 v10, v12, v13
	v_cvt_pk_f16_f32 v8, v8, v9
	v_cndmask_b32_e64 v22, v31, v30, s[4:5]
	v_mov_b32_e32 v35, v3
	v_mov_b32_dpp v25, v27 row_ror:8 row_mask:0xf bank_mask:0xf
	v_cndmask_b32_e64 v20, v28, v33, s[4:5]
	v_add_u32_e32 v28, 0xa0, v146
	v_cndmask_b32_e64 v9, v8, v10, s[4:5]
	v_mov_b32_e32 v12, v3
	v_mov_b32_dpp v35, v22 row_ror:8 row_mask:0xf bank_mask:0xf
	v_cndmask_b32_e64 v27, v25, v26, s[4:5]
	v_cndmask_b32_e64 v26, v36, v24, s[4:5]
	v_cndmask_b32_e64 v24, v33, v29, s[4:5]
	v_mad_i64_i32 v[28:29], s[14:15], v28, s35, v[116:117]
	v_cvt_pk_f16_f32 v18, v18, v19
	v_cvt_pk_f16_f32 v19, v6, v7
	v_cndmask_b32_e64 v4, v17, v16, s[4:5]
	v_mov_b32_dpp v12, v9 row_ror:8 row_mask:0xf bank_mask:0xf
	v_mov_b32_e32 v13, v3
	v_cndmask_b32_e64 v23, v34, v25, s[4:5]
	v_cndmask_b32_e64 v22, v32, v36, s[4:5]
	v_cndmask_b32_e64 v21, v30, v35, s[4:5]
	v_lshl_add_u64 v[28:29], v[28:29], 0, v[118:119]
	v_cndmask_b32_e64 v6, v19, v18, s[4:5]
	v_cndmask_b32_e64 v7, v14, v5, s[4:5]
	v_mov_b32_e32 v9, v3
	v_mov_b32_dpp v13, v4 row_ror:8 row_mask:0xf bank_mask:0xf
	v_mov_b32_e32 v11, v3
	v_cndmask_b32_e64 v4, v10, v12, s[4:5]
	v_cndmask_b32_e64 v8, v12, v8, s[4:5]
	v_add_u32_e32 v12, 0xb0, v146
	global_store_dwordx4 v[28:29], v[20:23], off nt
	v_mov_b32_dpp v9, v7 row_ror:8 row_mask:0xf bank_mask:0xf
	v_mov_b32_dpp v11, v6 row_ror:8 row_mask:0xf bank_mask:0xf
	v_add_co_u32_e32 v20, vcc, s1, v28
	v_cndmask_b32_e64 v6, v16, v13, s[4:5]
	v_cndmask_b32_e64 v10, v13, v17, s[4:5]
	v_mad_i64_i32 v[12:13], s[14:15], v12, s35, v[116:117]
	v_addc_co_u32_e32 v21, vcc, 0, v29, vcc
	v_cndmask_b32_e64 v7, v18, v11, s[4:5]
	v_cndmask_b32_e64 v5, v5, v9, s[4:5]
	v_lshl_add_u64 v[12:13], v[12:13], 0, v[118:119]
	global_store_dwordx4 v[12:13], v[4:7], off nt
	v_cndmask_b32_e64 v25, v35, v31, s[4:5]
	v_cndmask_b32_e64 v11, v11, v19, s[4:5]
	v_add_co_u32_e32 v4, vcc, 0x3c000, v12
	v_cndmask_b32_e64 v9, v9, v14, s[4:5]
	s_nop 0
	v_addc_co_u32_e32 v5, vcc, 0, v13, vcc
	s_and_b64 vcc, exec, s[6:7]
	s_mov_b32 s48, s0
	s_mov_b32 s49, s8
	s_mov_b64 s[18:19], s[12:13]
	s_mov_b64 s[14:15], s[10:11]
	global_store_dwordx4 v[20:21], v[24:27], off nt
	global_store_dwordx4 v[4:5], v[8:11], off nt
	s_cbranch_vccz .LBB0_329
	s_waitcnt vmcnt(0)
	v_readlane_b32 s42, v251, 7
	v_readlane_b32 s46, v251, 9
	v_readlane_b32 s48, v251, 13
	s_cmpk_gt_u32 s20, 0xff
	v_readlane_b32 s43, v251, 8
	v_readlane_b32 s47, v251, 10
	v_readlane_b32 s49, v251, 14
	s_cbranch_scc1 .LBB0_336
	s_barrier

; #define PG8_STAGE(bufoff, gbase, voff) do { _Pragma("unroll") for (int _i = 0; _i < 2; ++_i) \
;         __builtin_amdgcn_global_load_lds((const unsigned*)((const char*)(gbase) + (voff)[_i]), (LAS unsigned*)(lds + (bufoff) + ldsw + _i * 8192), 16, 0, 0); } while (0)
; #define PG8_LDA(dst, b, h) do { _Pragma("unroll") for (int m = 0; m < 4; ++m) _Pragma("unroll") for (int k = 0; k < 2; ++k) dst[m][k] = *(const LAS h8*)(lds + PG8_SA(b, h) + aoff + m * 2048 + k * 1024); } while (0)
; #define PG8_LDB(dst, b, h) do { _Pragma("unroll") for (int n = 0; n < 2; ++n) _Pragma("unroll") for (int k = 0; k < 2; ++k) dst[n][k] = *(const LAS h8*)(lds + PG8_SB(b, h) + boff + n * 2048 + k * 1024); } while (0)
; #define PG8_WAIT_L(n) asm volatile("s_waitcnt lgkmcnt(" #n ")" ::: "memory")
; #define PG8_BAR __builtin_amdgcn_s_barrier()
; #define PG8_SCHED __builtin_amdgcn_sched_barrier(0)
; template <class Epi>
; __device__ __forceinline__ void gemm_phase(LAS unsigned char* lds, const Gemm g, const StaticOrder& S, const Epi& E, const int tid) {
;     ...
;         const bool has_next = S.next(ui + 1, nxt);
;         const char* nA = has_next ? (const char*)g.A + (size_t)nxt.pm * tstep : cA; const char* nB = has_next ? (const char*)g.Bt + (size_t)nxt.pn * tstep : cB;
;         for (int t = 0; t < nt; t += 2) {
;             const bool last = (t == nt - 2);
;             const char* a1 = cA + (size_t)(t + 1) * kstep;
;             const char* a2 = last ? nA : cA + (size_t)(t + 2) * kstep; const char* b2 = last ? nB : cB + (size_t)(t + 2) * kstep;
;             const char* a3 = a2 + kstep; const char* b3 = b2 + kstep;
;             if constexpr (Epi::HAS_MID) { if (t == (nt >> 1)) E.mid(acc, cur, wr, wc, fr, fq); }
;             PG8_LDB(B0, 0, 0); PG8_SCHED; PG8_LDA(At, 0, 0); PG8_STAGE(PG8_SA(1, 1), a1 + hstep, voffA);
;             PG8_WAIT_L(8); PG8_BAR; PG8_WAIT_L(0); PG8_MMA(0, 0, At, B0); PG8_BAR; PG8_SCHED;
;             PG8_LDB(B1, 0, 1); PG8_STAGE(PG8_SB(0, 0), b2, voffB);
;             PG8_BAR; PG8_WAIT_L(0); PG8_MMA(0, 1, At, B1); PG8_BAR;
;             PG8_LDA(At, 0, 1); PG8_STAGE(PG8_SA(0, 0), a2, voffA);
;             PG8_BAR; PG8_WAIT_L(0); PG8_MMA(1, 0, At, B0); PG8_BAR; PG8_SCHED;
.LBB0_594:
	s_add_u32 s14, s10, s12
	s_addc_u32 s15, s11, s13
	s_add_u32 s14, s14, 0x100
	s_addc_u32 s15, s15, 0
	s_add_u32 s55, s52, s12
	s_addc_u32 s56, s53, s13
	s_cmpk_eq_i32 s12, 0x1f00
	s_cselect_b32 s19, s5, s15
	s_cselect_b32 s18, s50, s14
	s_cselect_b32 s15, s1, s56
	s_cselect_b32 s14, s51, s55
	s_add_i32 s55, 0, 0x10000
	v_add_u32_e32 v0, s55, v189
	ds_read_b128 v[132:135], v0
	ds_read_b128 v[136:139], v0 offset:1024
	ds_read_b128 v[176:179], v0 offset:2048
	ds_read_b128 v[192:195], v0 offset:3072
	v_lshl_add_u64 v[0:1], v[172:173], 0, s[12:13]
	s_add_i32 m0, s25, 0xc000
	ds_read_b128 v[196:199], v191
	ds_read_b128 v[200:203], v191 offset:1024
	ds_read_b128 v[204:207], v191 offset:2048
	ds_read_b128 v[208:211], v191 offset:3072
	ds_read_b128 v[212:215], v191 offset:4096
	ds_read_b128 v[216:219], v191 offset:5120
	ds_read_b128 v[220:223], v191 offset:6144
	ds_read_b128 v[224:227], v191 offset:7168
	global_load_lds_dwordx4 v[0:1], off
	v_lshl_add_u64 v[0:1], v[174:175], 0, s[12:13]
	s_add_i32 m0, s25, 0xe000
	s_nop 0
	global_load_lds_dwordx4 v[0:1], off
	s_waitcnt lgkmcnt(8)
	s_barrier
	s_waitcnt lgkmcnt(0)
	s_waitcnt lgkmcnt(0)
	v_mfma_f32_16x16x32_bf16 v[128:131], v[132:135], v[196:199], v[128:131]
	v_mfma_f32_16x16x32_bf16 v[124:127], v[176:179], v[196:199], v[124:127]
	v_mfma_f32_16x16x32_bf16 v[112:115], v[132:135], v[204:207], v[112:115]
	v_mfma_f32_16x16x32_bf16 v[108:111], v[176:179], v[204:207], v[108:111]
	v_mfma_f32_16x16x32_bf16 v[96:99], v[132:135], v[212:215], v[96:99]
	v_mfma_f32_16x16x32_bf16 v[92:95], v[176:179], v[212:215], v[92:95]
	v_mfma_f32_16x16x32_bf16 v[80:83], v[132:135], v[220:223], v[80:83]
	v_mfma_f32_16x16x32_bf16 v[76:79], v[176:179], v[220:223], v[76:79]
	v_mfma_f32_16x16x32_bf16 v[128:131], v[136:139], v[200:203], v[128:131]
	v_mfma_f32_16x16x32_bf16 v[124:127], v[192:195], v[200:203], v[124:127]
	v_mfma_f32_16x16x32_bf16 v[112:115], v[136:139], v[208:211], v[112:115]
	v_mfma_f32_16x16x32_bf16 v[108:111], v[192:195], v[208:211], v[108:111]
	v_mfma_f32_16x16x32_bf16 v[96:99], v[136:139], v[216:219], v[96:99]
	v_mfma_f32_16x16x32_bf16 v[92:95], v[192:195], v[216:219], v[92:95]
	v_mfma_f32_16x16x32_bf16 v[80:83], v[136:139], v[224:227], v[80:83]
	v_mfma_f32_16x16x32_bf16 v[76:79], v[192:195], v[224:227], v[76:79]
	s_barrier
	s_add_i32 s58, 0, 0x14000
	v_add_u32_e32 v0, s58, v189
	s_add_i32 s55, s55, s24
	ds_read_b128 v[228:231], v0
	ds_read_b128 v[232:235], v0 offset:1024
	ds_read_b128 v[236:239], v0 offset:2048
	ds_read_b128 v[240:243], v0 offset:3072
	v_lshl_add_u64 v[0:1], s[14:15], 0, v[144:145]
	s_mov_b32 m0, s55
	v_lshl_add_u64 v[244:245], s[14:15], 0, v[140:141]
	global_load_lds_dwordx4 v[0:1], off
	s_add_i32 m0, s55, 0x2000
	s_nop 0
	global_load_lds_dwordx4 v[244:245], off
	s_barrier
	s_waitcnt lgkmcnt(0)
	s_waitcnt lgkmcnt(0)
	v_mfma_f32_16x16x32_bf16 v[120:123], v[228:231], v[196:199], v[120:123]
	v_mfma_f32_16x16x32_bf16 v[116:119], v[236:239], v[196:199], v[116:119]
	v_mfma_f32_16x16x32_bf16 v[104:107], v[228:231], v[204:207], v[104:107]
	v_mfma_f32_16x16x32_bf16 v[100:103], v[236:239], v[204:207], v[100:103]
	v_mfma_f32_16x16x32_bf16 v[88:91], v[228:231], v[212:215], v[88:91]
	v_mfma_f32_16x16x32_bf16 v[84:87], v[236:239], v[212:215], v[84:87]
	v_mfma_f32_16x16x32_bf16 v[72:75], v[228:231], v[220:223], v[72:75]
	v_mfma_f32_16x16x32_bf16 v[68:71], v[236:239], v[220:223], v[68:71]
	v_mfma_f32_16x16x32_bf16 v[120:123], v[232:235], v[200:203], v[120:123]
	v_mfma_f32_16x16x32_bf16 v[116:119], v[240:243], v[200:203], v[116:119]
	v_mfma_f32_16x16x32_bf16 v[104:107], v[232:235], v[208:211], v[104:107]
	v_mfma_f32_16x16x32_bf16 v[100:103], v[240:243], v[208:211], v[100:103]
	v_mfma_f32_16x16x32_bf16 v[88:91], v[232:235], v[216:219], v[88:91]
	v_mfma_f32_16x16x32_bf16 v[84:87], v[240:243], v[216:219], v[84:87]
	v_mfma_f32_16x16x32_bf16 v[72:75], v[232:235], v[224:227], v[72:75]
	v_mfma_f32_16x16x32_bf16 v[68:71], v[240:243], v[224:227], v[68:71]
	s_mov_b32 m0, s25
	v_lshl_add_u64 v[246:247], s[18:19], 0, v[146:147]
	s_barrier
	ds_read_b128 v[196:199], v191 offset:16384
	ds_read_b128 v[200:203], v191 offset:17408
	ds_read_b128 v[204:207], v191 offset:18432
	ds_read_b128 v[208:211], v191 offset:19456
	ds_read_b128 v[212:215], v191 offset:20480
	ds_read_b128 v[216:219], v191 offset:21504
	ds_read_b128 v[220:223], v191 offset:22528
	ds_read_b128 v[224:227], v191 offset:23552
	global_load_lds_dwordx4 v[246:247], off
	v_lshl_add_u64 v[248:249], s[18:19], 0, v[142:143]
	s_mov_b32 m0, s42
	s_nop 0
	global_load_lds_dwordx4 v[248:249], off
	s_barrier
	s_waitcnt lgkmcnt(0)
	s_waitcnt lgkmcnt(0)
	v_mfma_f32_16x16x32_bf16 v[64:67], v[132:135], v[196:199], v[64:67]
	v_mfma_f32_16x16x32_bf16 v[60:63], v[176:179], v[196:199], v[60:63]
	v_mfma_f32_16x16x32_bf16 v[48:51], v[132:135], v[204:207], v[48:51]
	v_mfma_f32_16x16x32_bf16 v[44:47], v[176:179], v[204:207], v[44:47]
	v_mfma_f32_16x16x32_bf16 v[32:35], v[132:135], v[212:215], v[32:35]
	v_mfma_f32_16x16x32_bf16 v[28:31], v[176:179], v[212:215], v[28:31]
	v_mfma_f32_16x16x32_bf16 v[16:19], v[132:135], v[220:223], v[16:19]
	v_mfma_f32_16x16x32_bf16 v[12:15], v[176:179], v[220:223], v[12:15]
	v_mfma_f32_16x16x32_bf16 v[64:67], v[136:139], v[200:203], v[64:67]
	v_mfma_f32_16x16x32_bf16 v[60:63], v[192:195], v[200:203], v[60:63]
	v_mfma_f32_16x16x32_bf16 v[48:51], v[136:139], v[208:211], v[48:51]
	v_mfma_f32_16x16x32_bf16 v[44:47], v[192:195], v[208:211], v[44:47]
	v_mfma_f32_16x16x32_bf16 v[32:35], v[136:139], v[216:219], v[32:35]
	v_mfma_f32_16x16x32_bf16 v[28:31], v[192:195], v[216:219], v[28:31]
	v_mfma_f32_16x16x32_bf16 v[16:19], v[136:139], v[224:227], v[16:19]
	v_mfma_f32_16x16x32_bf16 v[12:15], v[192:195], v[224:227], v[12:15]
	s_barrier
; #define PG8_STAGE(bufoff, gbase, voff) do { _Pragma("unroll") for (int _i = 0; _i < 2; ++_i) \
;         __builtin_amdgcn_global_load_lds((const unsigned*)((const char*)(gbase) + (voff)[_i]), (LAS unsigned*)(lds + (bufoff) + ldsw + _i * 8192), 16, 0, 0); } while (0)
; #define PG8_LDA(dst, b, h) do { _Pragma("unroll") for (int m = 0; m < 4; ++m) _Pragma("unroll") for (int k = 0; k < 2; ++k) dst[m][k] = *(const LAS h8*)(lds + PG8_SA(b, h) + aoff + m * 2048 + k * 1024); } while (0)
; #define PG8_LDB(dst, b, h) do { _Pragma("unroll") for (int n = 0; n < 2; ++n) _Pragma("unroll") for (int k = 0; k < 2; ++k) dst[n][k] = *(const LAS h8*)(lds + PG8_SB(b, h) + boff + n * 2048 + k * 1024); } while (0)
; #define PG8_WAIT_V(n) asm volatile("s_waitcnt vmcnt(" #n ")" ::: "memory")
; #define PG8_WAIT_L(n) asm volatile("s_waitcnt lgkmcnt(" #n ")" ::: "memory")
; #define PG8_BAR __builtin_amdgcn_s_barrier()
; #define PG8_SCHED __builtin_amdgcn_sched_barrier(0)
; template <class Epi>
; __device__ __forceinline__ void gemm_phase(LAS unsigned char* lds, const Gemm g, const StaticOrder& S, const Epi& E, const int tid) {
;     ...
;             PG8_STAGE(PG8_SB(0, 1), b2 + hstepB, voffB);
;             PG8_WAIT_V(6); PG8_BAR; PG8_MMA(1, 1, At, B1); PG8_BAR;
;             PG8_LDB(B0, 1, 0); PG8_SCHED; PG8_LDA(At, 1, 0); PG8_STAGE(PG8_SA(0, 1), a2 + hstep, voffA);
;             PG8_WAIT_L(8); PG8_BAR; PG8_WAIT_L(0); PG8_MMA(0, 0, At, B0); PG8_BAR; PG8_SCHED;
;             PG8_LDB(B1, 1, 1); PG8_STAGE(PG8_SB(1, 0), b3, voffB);
;             PG8_BAR; PG8_WAIT_L(0); PG8_MMA(0, 1, At, B1); PG8_BAR;
;             PG8_LDA(At, 1, 1); PG8_STAGE(PG8_SA(1, 0), a3, voffA);
	s_add_u32 s56, s14, 0x100000
	s_addc_u32 s57, s15, 0
	s_add_i32 s55, s58, s24
	s_mov_b32 m0, s55
	s_nop 0
	global_load_lds_dwordx4 v144, s[56:57]
	s_add_i32 m0, s55, 0x2000
	s_nop 0
	global_load_lds_dwordx4 v140, s[56:57]
	s_waitcnt vmcnt(6)
	s_barrier
	v_mfma_f32_16x16x32_bf16 v[56:59], v[228:231], v[196:199], v[56:59]
	v_mfma_f32_16x16x32_bf16 v[52:55], v[236:239], v[196:199], v[52:55]
	v_mfma_f32_16x16x32_bf16 v[40:43], v[228:231], v[204:207], v[40:43]
	v_mfma_f32_16x16x32_bf16 v[36:39], v[236:239], v[204:207], v[36:39]
	v_mfma_f32_16x16x32_bf16 v[24:27], v[228:231], v[212:215], v[24:27]
	v_mfma_f32_16x16x32_bf16 v[20:23], v[236:239], v[212:215], v[20:23]
	v_mfma_f32_16x16x32_bf16 v[8:11], v[228:231], v[220:223], v[8:11]
	v_mfma_f32_16x16x32_bf16 v[4:7], v[236:239], v[220:223], v[4:7]
	v_mfma_f32_16x16x32_bf16 v[56:59], v[232:235], v[200:203], v[56:59]
	v_mfma_f32_16x16x32_bf16 v[52:55], v[240:243], v[200:203], v[52:55]
	v_mfma_f32_16x16x32_bf16 v[40:43], v[232:235], v[208:211], v[40:43]
	v_mfma_f32_16x16x32_bf16 v[36:39], v[240:243], v[208:211], v[36:39]
	v_mfma_f32_16x16x32_bf16 v[24:27], v[232:235], v[216:219], v[24:27]
	v_mfma_f32_16x16x32_bf16 v[20:23], v[240:243], v[216:219], v[20:23]
	v_mfma_f32_16x16x32_bf16 v[8:11], v[232:235], v[224:227], v[8:11]
	v_mfma_f32_16x16x32_bf16 v[4:7], v[240:243], v[224:227], v[4:7]
	s_add_i32 s55, 0, 0x18000
	v_add_u32_e32 v2, s55, v189
	s_barrier
	ds_read_b128 v[132:135], v2
	ds_read_b128 v[136:139], v2 offset:1024
	ds_read_b128 v[176:179], v2 offset:2048
	ds_read_b128 v[192:195], v2 offset:3072
	s_add_u32 s18, s18, 0x100000
	s_addc_u32 s19, s19, 0
	s_mov_b32 m0, s43
	ds_read_b128 v[196:199], v191 offset:32768
	ds_read_b128 v[200:203], v191 offset:33792
	ds_read_b128 v[204:207], v191 offset:34816
	ds_read_b128 v[208:211], v191 offset:35840
	ds_read_b128 v[212:215], v191 offset:36864
	ds_read_b128 v[216:219], v191 offset:37888
	ds_read_b128 v[220:223], v191 offset:38912
	ds_read_b128 v[224:227], v191 offset:39936
	global_load_lds_dwordx4 v146, s[18:19]
	s_mov_b32 m0, s46
	s_nop 0
	global_load_lds_dwordx4 v142, s[18:19]
	s_waitcnt lgkmcnt(8)
	s_barrier
	s_waitcnt lgkmcnt(0)
	s_waitcnt lgkmcnt(0)
	v_mfma_f32_16x16x32_bf16 v[128:131], v[132:135], v[196:199], v[128:131]
	v_mfma_f32_16x16x32_bf16 v[124:127], v[176:179], v[196:199], v[124:127]
	v_mfma_f32_16x16x32_bf16 v[112:115], v[132:135], v[204:207], v[112:115]
	v_mfma_f32_16x16x32_bf16 v[108:111], v[176:179], v[204:207], v[108:111]
	v_mfma_f32_16x16x32_bf16 v[96:99], v[132:135], v[212:215], v[96:99]
	v_mfma_f32_16x16x32_bf16 v[92:95], v[176:179], v[212:215], v[92:95]
	v_mfma_f32_16x16x32_bf16 v[80:83], v[132:135], v[220:223], v[80:83]
	v_mfma_f32_16x16x32_bf16 v[76:79], v[176:179], v[220:223], v[76:79]
	v_mfma_f32_16x16x32_bf16 v[128:131], v[136:139], v[200:203], v[128:131]
	v_mfma_f32_16x16x32_bf16 v[124:127], v[192:195], v[200:203], v[124:127]
	v_mfma_f32_16x16x32_bf16 v[112:115], v[136:139], v[208:211], v[112:115]
	v_mfma_f32_16x16x32_bf16 v[108:111], v[192:195], v[208:211], v[108:111]
	v_mfma_f32_16x16x32_bf16 v[96:99], v[136:139], v[216:219], v[96:99]
	v_mfma_f32_16x16x32_bf16 v[92:95], v[192:195], v[216:219], v[92:95]
	v_mfma_f32_16x16x32_bf16 v[80:83], v[136:139], v[224:227], v[80:83]
	v_mfma_f32_16x16x32_bf16 v[76:79], v[192:195], v[224:227], v[76:79]
	s_barrier
	s_add_i32 s18, 0, 0x1c000
	s_add_i32 s19, s55, s24
	v_add_u32_e32 v2, s18, v189
	v_lshl_add_u64 v[0:1], v[0:1], 0, s[30:31]
	s_mov_b32 m0, s19
	ds_read_b128 v[228:231], v2
	ds_read_b128 v[232:235], v2 offset:1024
	ds_read_b128 v[236:239], v2 offset:2048
	ds_read_b128 v[240:243], v2 offset:3072
	global_load_lds_dwordx4 v[0:1], off
	v_lshl_add_u64 v[0:1], v[244:245], 0, s[30:31]
	s_add_i32 m0, s19, 0x2000
	s_nop 0
	global_load_lds_dwordx4 v[0:1], off
	s_barrier
; #define PG8_STAGE(bufoff, gbase, voff) do { _Pragma("unroll") for (int _i = 0; _i < 2; ++_i) \
;         __builtin_amdgcn_global_load_lds((const unsigned*)((const char*)(gbase) + (voff)[_i]), (LAS unsigned*)(lds + (bufoff) + ldsw + _i * 8192), 16, 0, 0); } while (0)
; #define PG8_LDA(dst, b, h) do { _Pragma("unroll") for (int m = 0; m < 4; ++m) _Pragma("unroll") for (int k = 0; k < 2; ++k) dst[m][k] = *(const LAS h8*)(lds + PG8_SA(b, h) + aoff + m * 2048 + k * 1024); } while (0)
; #define PG8_WAIT_V(n) asm volatile("s_waitcnt vmcnt(" #n ")" ::: "memory")
; #define PG8_WAIT_L(n) asm volatile("s_waitcnt lgkmcnt(" #n ")" ::: "memory")
; #define PG8_BAR __builtin_amdgcn_s_barrier()
; #define PG8_SCHED __builtin_amdgcn_sched_barrier(0)
; template <class Epi>
; __device__ __forceinline__ void gemm_phase(LAS unsigned char* lds, const Gemm g, const StaticOrder& S, const Epi& E, const int tid) {
;     ...
;             PG8_LDA(At, 1, 1); PG8_STAGE(PG8_SA(1, 0), a3, voffA);
;             PG8_BAR; PG8_WAIT_L(0); PG8_MMA(1, 0, At, B0); PG8_BAR; PG8_SCHED;
;             PG8_STAGE(PG8_SB(1, 1), b3 + hstepB, voffB);
;             PG8_WAIT_V(6); PG8_BAR; PG8_MMA(1, 1, At, B1); PG8_BAR;
;         }
	s_waitcnt lgkmcnt(0)
	s_waitcnt lgkmcnt(0)
	v_mfma_f32_16x16x32_bf16 v[120:123], v[228:231], v[196:199], v[120:123]
	v_mfma_f32_16x16x32_bf16 v[116:119], v[236:239], v[196:199], v[116:119]
	v_mfma_f32_16x16x32_bf16 v[104:107], v[228:231], v[204:207], v[104:107]
	v_mfma_f32_16x16x32_bf16 v[100:103], v[236:239], v[204:207], v[100:103]
	v_mfma_f32_16x16x32_bf16 v[88:91], v[228:231], v[212:215], v[88:91]
	v_mfma_f32_16x16x32_bf16 v[84:87], v[236:239], v[212:215], v[84:87]
	v_mfma_f32_16x16x32_bf16 v[72:75], v[228:231], v[220:223], v[72:75]
	v_mfma_f32_16x16x32_bf16 v[68:71], v[236:239], v[220:223], v[68:71]
	v_mfma_f32_16x16x32_bf16 v[120:123], v[232:235], v[200:203], v[120:123]
	v_mfma_f32_16x16x32_bf16 v[116:119], v[240:243], v[200:203], v[116:119]
	v_mfma_f32_16x16x32_bf16 v[104:107], v[232:235], v[208:211], v[104:107]
	v_mfma_f32_16x16x32_bf16 v[100:103], v[240:243], v[208:211], v[100:103]
	v_mfma_f32_16x16x32_bf16 v[88:91], v[232:235], v[216:219], v[88:91]
	v_mfma_f32_16x16x32_bf16 v[84:87], v[240:243], v[216:219], v[84:87]
	v_mfma_f32_16x16x32_bf16 v[72:75], v[232:235], v[224:227], v[72:75]
	v_mfma_f32_16x16x32_bf16 v[68:71], v[240:243], v[224:227], v[68:71]
	s_mov_b32 m0, s47
	v_lshl_add_u64 v[0:1], v[246:247], 0, s[30:31]
	s_barrier
	ds_read_b128 v[196:199], v191 offset:49152
	ds_read_b128 v[200:203], v191 offset:50176
	ds_read_b128 v[204:207], v191 offset:51200
	ds_read_b128 v[208:211], v191 offset:52224
	ds_read_b128 v[212:215], v191 offset:53248
	ds_read_b128 v[216:219], v191 offset:54272
	ds_read_b128 v[220:223], v191 offset:55296
	ds_read_b128 v[224:227], v191 offset:56320
	global_load_lds_dwordx4 v[0:1], off
	v_lshl_add_u64 v[0:1], v[248:249], 0, s[30:31]
	s_mov_b32 m0, s48
	s_nop 0
	global_load_lds_dwordx4 v[0:1], off
	s_barrier
	s_waitcnt lgkmcnt(0)
	s_waitcnt lgkmcnt(0)
	v_mfma_f32_16x16x32_bf16 v[64:67], v[132:135], v[196:199], v[64:67]
	v_mfma_f32_16x16x32_bf16 v[60:63], v[176:179], v[196:199], v[60:63]
	v_mfma_f32_16x16x32_bf16 v[48:51], v[132:135], v[204:207], v[48:51]
	v_mfma_f32_16x16x32_bf16 v[44:47], v[176:179], v[204:207], v[44:47]
	v_mfma_f32_16x16x32_bf16 v[32:35], v[132:135], v[212:215], v[32:35]
	v_mfma_f32_16x16x32_bf16 v[28:31], v[176:179], v[212:215], v[28:31]
	v_mfma_f32_16x16x32_bf16 v[16:19], v[132:135], v[220:223], v[16:19]
	v_mfma_f32_16x16x32_bf16 v[12:15], v[176:179], v[220:223], v[12:15]
	v_mfma_f32_16x16x32_bf16 v[64:67], v[136:139], v[200:203], v[64:67]
	v_mfma_f32_16x16x32_bf16 v[60:63], v[192:195], v[200:203], v[60:63]
	v_mfma_f32_16x16x32_bf16 v[48:51], v[136:139], v[208:211], v[48:51]
	v_mfma_f32_16x16x32_bf16 v[44:47], v[192:195], v[208:211], v[44:47]
	v_mfma_f32_16x16x32_bf16 v[32:35], v[136:139], v[216:219], v[32:35]
	v_mfma_f32_16x16x32_bf16 v[28:31], v[192:195], v[216:219], v[28:31]
	v_mfma_f32_16x16x32_bf16 v[16:19], v[136:139], v[224:227], v[16:19]
	v_mfma_f32_16x16x32_bf16 v[12:15], v[192:195], v[224:227], v[12:15]
	s_barrier
	s_add_u32 s14, s14, 0x100080
	s_addc_u32 s15, s15, 0
	s_add_i32 s18, s18, s24
	s_mov_b32 m0, s18
	s_nop 0
	global_load_lds_dwordx4 v144, s[14:15]
	s_add_i32 m0, s18, 0x2000
	s_nop 0
	global_load_lds_dwordx4 v140, s[14:15]
	s_waitcnt vmcnt(6)
	s_barrier
	v_mfma_f32_16x16x32_bf16 v[56:59], v[228:231], v[196:199], v[56:59]
	v_mfma_f32_16x16x32_bf16 v[52:55], v[236:239], v[196:199], v[52:55]
	v_mfma_f32_16x16x32_bf16 v[40:43], v[228:231], v[204:207], v[40:43]
	v_mfma_f32_16x16x32_bf16 v[36:39], v[236:239], v[204:207], v[36:39]
	v_mfma_f32_16x16x32_bf16 v[24:27], v[228:231], v[212:215], v[24:27]
	v_mfma_f32_16x16x32_bf16 v[20:23], v[236:239], v[212:215], v[20:23]
	v_mfma_f32_16x16x32_bf16 v[8:11], v[228:231], v[220:223], v[8:11]
	v_mfma_f32_16x16x32_bf16 v[4:7], v[236:239], v[220:223], v[4:7]
	v_mfma_f32_16x16x32_bf16 v[56:59], v[232:235], v[200:203], v[56:59]
	v_mfma_f32_16x16x32_bf16 v[52:55], v[240:243], v[200:203], v[52:55]
	v_mfma_f32_16x16x32_bf16 v[40:43], v[232:235], v[208:211], v[40:43]
	v_mfma_f32_16x16x32_bf16 v[36:39], v[240:243], v[208:211], v[36:39]
	v_mfma_f32_16x16x32_bf16 v[24:27], v[232:235], v[216:219], v[24:27]
	v_mfma_f32_16x16x32_bf16 v[20:23], v[240:243], v[216:219], v[20:23]
	v_mfma_f32_16x16x32_bf16 v[8:11], v[232:235], v[224:227], v[8:11]
	v_mfma_f32_16x16x32_bf16 v[4:7], v[240:243], v[224:227], v[4:7]
	s_add_i32 s54, s54, 2
	s_add_u32 s12, s12, 0x100
	s_addc_u32 s13, s13, 0
	s_cmp_gt_u32 s54, 61
	s_barrier
	s_cbranch_scc1 .LBB0_586

; #define PG8_STAGE(bufoff, gbase, voff) do { _Pragma("unroll") for (int _i = 0; _i < 2; ++_i) \
;         __builtin_amdgcn_global_load_lds((const unsigned*)((const char*)(gbase) + (voff)[_i]), (LAS unsigned*)(lds + (bufoff) + ldsw + _i * 8192), 16, 0, 0); } while (0)
; #define PG8_LDA(dst, b, h) do { _Pragma("unroll") for (int m = 0; m < 4; ++m) _Pragma("unroll") for (int k = 0; k < 2; ++k) dst[m][k] = *(const LAS h8*)(lds + PG8_SA(b, h) + aoff + m * 2048 + k * 1024); } while (0)
; #define PG8_LDB(dst, b, h) do { _Pragma("unroll") for (int n = 0; n < 2; ++n) _Pragma("unroll") for (int k = 0; k < 2; ++k) dst[n][k] = *(const LAS h8*)(lds + PG8_SB(b, h) + boff + n * 2048 + k * 1024); } while (0)
; #define PG8_WAIT_L(n) asm volatile("s_waitcnt lgkmcnt(" #n ")" ::: "memory")
; #define PG8_BAR __builtin_amdgcn_s_barrier()
; #define PG8_SCHED __builtin_amdgcn_sched_barrier(0)
; template <class Epi>
; __device__ __forceinline__ void gemm_phase(LAS unsigned char* lds, const Gemm g, const StaticOrder& S, const Epi& E, const int tid) {
;     ...
;         const bool has_next = S.next(ui + 1, nxt);
;         const char* nA = has_next ? (const char*)g.A + (size_t)nxt.pm * tstep : cA; const char* nB = has_next ? (const char*)g.Bt + (size_t)nxt.pn * tstep : cB;
;         for (int t = 0; t < nt; t += 2) {
;             const bool last = (t == nt - 2);
;             const char* a1 = cA + (size_t)(t + 1) * kstep;
;             const char* a2 = last ? nA : cA + (size_t)(t + 2) * kstep; const char* b2 = last ? nB : cB + (size_t)(t + 2) * kstep;
;             const char* a3 = a2 + kstep; const char* b3 = b2 + kstep;
;             if constexpr (Epi::HAS_MID) { if (t == (nt >> 1)) E.mid(acc, cur, wr, wc, fr, fq); }
;             PG8_LDB(B0, 0, 0); PG8_SCHED; PG8_LDA(At, 0, 0); PG8_STAGE(PG8_SA(1, 1), a1 + hstep, voffA);
;             PG8_WAIT_L(8); PG8_BAR; PG8_WAIT_L(0); PG8_MMA(0, 0, At, B0); PG8_BAR; PG8_SCHED;
;             PG8_LDB(B1, 0, 1); PG8_STAGE(PG8_SB(0, 0), b2, voffB);
;             PG8_BAR; PG8_WAIT_L(0); PG8_MMA(0, 1, At, B1); PG8_BAR;
;             PG8_LDA(At, 0, 1); PG8_STAGE(PG8_SA(0, 0), a2, voffA);
;             PG8_BAR; PG8_WAIT_L(0); PG8_MMA(1, 0, At, B0); PG8_BAR; PG8_SCHED;
.LBB0_660:
	s_add_u32 s14, s12, 0xfff80080
	s_addc_u32 s15, s13, -1
	s_add_i32 s57, 0, 0x10000
	v_add_u32_e32 v64, s57, v190
	ds_read_b128 v[28:31], v64
	ds_read_b128 v[32:35], v64 offset:1024
	ds_read_b128 v[60:63], v64 offset:2048
	ds_read_b128 v[64:67], v64 offset:3072
	s_cmp_eq_u32 s56, 28
	s_cselect_b32 s19, s7, s15
	s_cselect_b32 s18, s52, s14
	s_cselect_b32 s15, s1, s55
	s_cselect_b32 s14, s53, s54
	s_add_i32 m0, s41, 0xc000
	ds_read_b128 v[170:173], v192
	ds_read_b128 v[194:197], v192 offset:1024
	ds_read_b128 v[198:201], v192 offset:2048
	ds_read_b128 v[202:205], v192 offset:3072
	ds_read_b128 v[206:209], v192 offset:4096
	ds_read_b128 v[210:213], v192 offset:5120
	ds_read_b128 v[214:217], v192 offset:6144
	ds_read_b128 v[218:221], v192 offset:7168
	global_load_lds_dwordx4 v166, s[12:13]
	v_lshl_add_u64 v[174:175], s[12:13], 0, v[168:169]
	s_add_i32 m0, s41, 0xe000
	s_nop 0
	global_load_lds_dwordx4 v[174:175], off
	s_waitcnt lgkmcnt(8)
	s_barrier
	s_waitcnt lgkmcnt(0)
	s_waitcnt lgkmcnt(0)
	v_mfma_f32_16x16x32_bf16 v[144:147], v[28:31], v[170:173], v[144:147]
	v_mfma_f32_16x16x32_bf16 v[140:143], v[60:63], v[170:173], v[140:143]
	v_mfma_f32_16x16x32_bf16 v[128:131], v[28:31], v[198:201], v[128:131]
	v_mfma_f32_16x16x32_bf16 v[124:127], v[60:63], v[198:201], v[124:127]
	v_mfma_f32_16x16x32_bf16 v[112:115], v[28:31], v[206:209], v[112:115]
	v_mfma_f32_16x16x32_bf16 v[108:111], v[60:63], v[206:209], v[108:111]
	v_mfma_f32_16x16x32_bf16 v[96:99], v[28:31], v[214:217], v[96:99]
	v_mfma_f32_16x16x32_bf16 v[92:95], v[60:63], v[214:217], v[92:95]
	v_mfma_f32_16x16x32_bf16 v[144:147], v[32:35], v[194:197], v[144:147]
	v_mfma_f32_16x16x32_bf16 v[140:143], v[64:67], v[194:197], v[140:143]
	v_mfma_f32_16x16x32_bf16 v[128:131], v[32:35], v[202:205], v[128:131]
	v_mfma_f32_16x16x32_bf16 v[124:127], v[64:67], v[202:205], v[124:127]
	v_mfma_f32_16x16x32_bf16 v[112:115], v[32:35], v[210:213], v[112:115]
	v_mfma_f32_16x16x32_bf16 v[108:111], v[64:67], v[210:213], v[108:111]
	v_mfma_f32_16x16x32_bf16 v[96:99], v[32:35], v[218:221], v[96:99]
	v_mfma_f32_16x16x32_bf16 v[92:95], v[64:67], v[218:221], v[92:95]
	s_barrier
	s_add_i32 s60, 0, 0x14000
	v_add_u32_e32 v174, s60, v190
	s_add_i32 s57, s57, s40
	ds_read_b128 v[222:225], v174
	ds_read_b128 v[226:229], v174 offset:1024
	ds_read_b128 v[230:233], v174 offset:2048
	ds_read_b128 v[234:237], v174 offset:3072
	v_lshl_add_u64 v[174:175], s[14:15], 0, v[2:3]
	s_mov_b32 m0, s57
	v_lshl_add_u64 v[238:239], s[14:15], 0, v[0:1]
	global_load_lds_dwordx4 v[174:175], off
	s_add_i32 m0, s57, 0x2000
	s_nop 0
	global_load_lds_dwordx4 v[238:239], off
	s_barrier
	s_waitcnt lgkmcnt(0)
	s_waitcnt lgkmcnt(0)
	v_mfma_f32_16x16x32_bf16 v[136:139], v[222:225], v[170:173], v[136:139]
	v_mfma_f32_16x16x32_bf16 v[132:135], v[230:233], v[170:173], v[132:135]
	v_mfma_f32_16x16x32_bf16 v[120:123], v[222:225], v[198:201], v[120:123]
	v_mfma_f32_16x16x32_bf16 v[116:119], v[230:233], v[198:201], v[116:119]
	v_mfma_f32_16x16x32_bf16 v[104:107], v[222:225], v[206:209], v[104:107]
	v_mfma_f32_16x16x32_bf16 v[100:103], v[230:233], v[206:209], v[100:103]
	v_mfma_f32_16x16x32_bf16 v[88:91], v[222:225], v[214:217], v[88:91]
	v_mfma_f32_16x16x32_bf16 v[84:87], v[230:233], v[214:217], v[84:87]
	v_mfma_f32_16x16x32_bf16 v[136:139], v[226:229], v[194:197], v[136:139]
	v_mfma_f32_16x16x32_bf16 v[132:135], v[234:237], v[194:197], v[132:135]
	v_mfma_f32_16x16x32_bf16 v[120:123], v[226:229], v[202:205], v[120:123]
	v_mfma_f32_16x16x32_bf16 v[116:119], v[234:237], v[202:205], v[116:119]
	v_mfma_f32_16x16x32_bf16 v[104:107], v[226:229], v[210:213], v[104:107]
	v_mfma_f32_16x16x32_bf16 v[100:103], v[234:237], v[210:213], v[100:103]
	v_mfma_f32_16x16x32_bf16 v[88:91], v[226:229], v[218:221], v[88:91]
	v_mfma_f32_16x16x32_bf16 v[84:87], v[234:237], v[218:221], v[84:87]
	s_mov_b32 m0, s41
	v_lshl_add_u64 v[240:241], s[18:19], 0, v[164:165]
	s_barrier
	ds_read_b128 v[170:173], v192 offset:16384
	ds_read_b128 v[194:197], v192 offset:17408
	ds_read_b128 v[198:201], v192 offset:18432
	ds_read_b128 v[202:205], v192 offset:19456
	ds_read_b128 v[206:209], v192 offset:20480
	ds_read_b128 v[210:213], v192 offset:21504
	ds_read_b128 v[214:217], v192 offset:22528
	ds_read_b128 v[218:221], v192 offset:23552
	global_load_lds_dwordx4 v[240:241], off
	v_lshl_add_u64 v[242:243], s[18:19], 0, v[162:163]
	s_mov_b32 m0, s42
	s_nop 0
	global_load_lds_dwordx4 v[242:243], off
	s_barrier
	s_waitcnt lgkmcnt(0)
	s_waitcnt lgkmcnt(0)
	v_mfma_f32_16x16x32_bf16 v[80:83], v[28:31], v[170:173], v[80:83]
	v_mfma_f32_16x16x32_bf16 v[76:79], v[60:63], v[170:173], v[76:79]
	v_mfma_f32_16x16x32_bf16 v[56:59], v[28:31], v[198:201], v[56:59]
	v_mfma_f32_16x16x32_bf16 v[52:55], v[60:63], v[198:201], v[52:55]
	v_mfma_f32_16x16x32_bf16 v[40:43], v[28:31], v[206:209], v[40:43]
	v_mfma_f32_16x16x32_bf16 v[36:39], v[60:63], v[206:209], v[36:39]
	v_mfma_f32_16x16x32_bf16 v[16:19], v[28:31], v[214:217], v[16:19]
	v_mfma_f32_16x16x32_bf16 v[12:15], v[60:63], v[214:217], v[12:15]
	v_mfma_f32_16x16x32_bf16 v[80:83], v[32:35], v[194:197], v[80:83]
	v_mfma_f32_16x16x32_bf16 v[76:79], v[64:67], v[194:197], v[76:79]
	v_mfma_f32_16x16x32_bf16 v[56:59], v[32:35], v[202:205], v[56:59]
	v_mfma_f32_16x16x32_bf16 v[52:55], v[64:67], v[202:205], v[52:55]
	v_mfma_f32_16x16x32_bf16 v[40:43], v[32:35], v[210:213], v[40:43]
	v_mfma_f32_16x16x32_bf16 v[36:39], v[64:67], v[210:213], v[36:39]
	v_mfma_f32_16x16x32_bf16 v[16:19], v[32:35], v[218:221], v[16:19]
	v_mfma_f32_16x16x32_bf16 v[12:15], v[64:67], v[218:221], v[12:15]
	s_barrier
; #define PG8_STAGE(bufoff, gbase, voff) do { _Pragma("unroll") for (int _i = 0; _i < 2; ++_i) \
;         __builtin_amdgcn_global_load_lds((const unsigned*)((const char*)(gbase) + (voff)[_i]), (LAS unsigned*)(lds + (bufoff) + ldsw + _i * 8192), 16, 0, 0); } while (0)
; #define PG8_LDA(dst, b, h) do { _Pragma("unroll") for (int m = 0; m < 4; ++m) _Pragma("unroll") for (int k = 0; k < 2; ++k) dst[m][k] = *(const LAS h8*)(lds + PG8_SA(b, h) + aoff + m * 2048 + k * 1024); } while (0)
; #define PG8_LDB(dst, b, h) do { _Pragma("unroll") for (int n = 0; n < 2; ++n) _Pragma("unroll") for (int k = 0; k < 2; ++k) dst[n][k] = *(const LAS h8*)(lds + PG8_SB(b, h) + boff + n * 2048 + k * 1024); } while (0)
; #define PG8_WAIT_V(n) asm volatile("s_waitcnt vmcnt(" #n ")" ::: "memory")
; #define PG8_WAIT_L(n) asm volatile("s_waitcnt lgkmcnt(" #n ")" ::: "memory")
; #define PG8_BAR __builtin_amdgcn_s_barrier()
; #define PG8_SCHED __builtin_amdgcn_sched_barrier(0)
; template <class Epi>
; __device__ __forceinline__ void gemm_phase(LAS unsigned char* lds, const Gemm g, const StaticOrder& S, const Epi& E, const int tid) {
;     ...
;             PG8_STAGE(PG8_SB(0, 1), b2 + hstepB, voffB);
;             PG8_WAIT_V(6); PG8_BAR; PG8_MMA(1, 1, At, B1); PG8_BAR;
;             PG8_LDB(B0, 1, 0); PG8_SCHED; PG8_LDA(At, 1, 0); PG8_STAGE(PG8_SA(0, 1), a2 + hstep, voffA);
;             PG8_WAIT_L(8); PG8_BAR; PG8_WAIT_L(0); PG8_MMA(0, 0, At, B0); PG8_BAR; PG8_SCHED;
;             PG8_LDB(B1, 1, 1); PG8_STAGE(PG8_SB(1, 0), b3, voffB);
;             PG8_BAR; PG8_WAIT_L(0); PG8_MMA(0, 1, At, B1); PG8_BAR;
;             PG8_LDA(At, 1, 1); PG8_STAGE(PG8_SA(1, 0), a3, voffA);
	s_add_u32 s58, s14, 0x80000
	s_addc_u32 s59, s15, 0
	s_add_i32 s57, s60, s40
	s_mov_b32 m0, s57
	s_nop 0
	global_load_lds_dwordx4 v2, s[58:59]
	v_lshl_add_u64 v[28:29], s[58:59], 0, v[0:1]
	s_add_i32 m0, s57, 0x2000
	s_nop 0
	global_load_lds_dwordx4 v[28:29], off
	s_waitcnt vmcnt(6)
	s_barrier
	v_mfma_f32_16x16x32_bf16 v[48:51], v[222:225], v[198:201], v[48:51]
	v_mfma_f32_16x16x32_bf16 v[44:47], v[230:233], v[198:201], v[44:47]
	v_mfma_f32_16x16x32_bf16 v[24:27], v[222:225], v[206:209], v[24:27]
	v_mfma_f32_16x16x32_bf16 v[20:23], v[230:233], v[206:209], v[20:23]
	v_mfma_f32_16x16x32_bf16 v[8:11], v[222:225], v[214:217], v[8:11]
	v_mfma_f32_16x16x32_bf16 v[4:7], v[230:233], v[214:217], v[4:7]
	v_mfma_f32_16x16x32_bf16 v[28:31], v[222:225], v[170:173], v[72:75]
	v_mfma_f32_16x16x32_bf16 v[32:35], v[230:233], v[170:173], v[68:71]
	v_mfma_f32_16x16x32_bf16 v[48:51], v[226:229], v[202:205], v[48:51]
	v_mfma_f32_16x16x32_bf16 v[44:47], v[234:237], v[202:205], v[44:47]
	v_mfma_f32_16x16x32_bf16 v[24:27], v[226:229], v[210:213], v[24:27]
	v_mfma_f32_16x16x32_bf16 v[20:23], v[234:237], v[210:213], v[20:23]
	v_mfma_f32_16x16x32_bf16 v[8:11], v[226:229], v[218:221], v[8:11]
	v_mfma_f32_16x16x32_bf16 v[4:7], v[234:237], v[218:221], v[4:7]
	v_mfma_f32_16x16x32_bf16 v[28:31], v[226:229], v[194:197], v[28:31]
	v_mfma_f32_16x16x32_bf16 v[32:35], v[234:237], v[194:197], v[32:35]
	s_add_i32 s57, 0, 0x18000
	v_add_u32_e32 v72, s57, v190
	s_barrier
	ds_read_b128 v[60:63], v72
	ds_read_b128 v[64:67], v72 offset:1024
	ds_read_b128 v[68:71], v72 offset:2048
	ds_read_b128 v[72:75], v72 offset:3072
	s_add_u32 s18, s18, 0x80000
	s_addc_u32 s19, s19, 0
	s_mov_b32 m0, s43
	ds_read_b128 v[170:173], v192 offset:32768
	ds_read_b128 v[194:197], v192 offset:33792
	ds_read_b128 v[198:201], v192 offset:34816
	ds_read_b128 v[202:205], v192 offset:35840
	ds_read_b128 v[206:209], v192 offset:36864
	ds_read_b128 v[210:213], v192 offset:37888
	ds_read_b128 v[214:217], v192 offset:38912
	ds_read_b128 v[218:221], v192 offset:39936
	global_load_lds_dwordx4 v164, s[18:19]
	s_mov_b32 m0, s46
	s_nop 0
	global_load_lds_dwordx4 v162, s[18:19]
	s_waitcnt lgkmcnt(8)
	s_barrier
	s_waitcnt lgkmcnt(0)
	s_waitcnt lgkmcnt(0)
	v_mfma_f32_16x16x32_bf16 v[144:147], v[60:63], v[170:173], v[144:147]
	v_mfma_f32_16x16x32_bf16 v[140:143], v[68:71], v[170:173], v[140:143]
	v_mfma_f32_16x16x32_bf16 v[128:131], v[60:63], v[198:201], v[128:131]
	v_mfma_f32_16x16x32_bf16 v[124:127], v[68:71], v[198:201], v[124:127]
	v_mfma_f32_16x16x32_bf16 v[112:115], v[60:63], v[206:209], v[112:115]
	v_mfma_f32_16x16x32_bf16 v[108:111], v[68:71], v[206:209], v[108:111]
	v_mfma_f32_16x16x32_bf16 v[96:99], v[60:63], v[214:217], v[96:99]
	v_mfma_f32_16x16x32_bf16 v[92:95], v[68:71], v[214:217], v[92:95]
	v_mfma_f32_16x16x32_bf16 v[144:147], v[64:67], v[194:197], v[144:147]
	v_mfma_f32_16x16x32_bf16 v[140:143], v[72:75], v[194:197], v[140:143]
	v_mfma_f32_16x16x32_bf16 v[128:131], v[64:67], v[202:205], v[128:131]
	v_mfma_f32_16x16x32_bf16 v[124:127], v[72:75], v[202:205], v[124:127]
	v_mfma_f32_16x16x32_bf16 v[112:115], v[64:67], v[210:213], v[112:115]
	v_mfma_f32_16x16x32_bf16 v[108:111], v[72:75], v[210:213], v[108:111]
	v_mfma_f32_16x16x32_bf16 v[96:99], v[64:67], v[218:221], v[96:99]
	v_mfma_f32_16x16x32_bf16 v[92:95], v[72:75], v[218:221], v[92:95]
	s_barrier
	s_add_i32 s18, 0, 0x1c000
	s_add_i32 s19, s57, s40
	v_add_u32_e32 v193, s18, v190
	v_lshl_add_u64 v[174:175], v[174:175], 0, s[30:31]
	s_mov_b32 m0, s19
	ds_read_b128 v[222:225], v193
	ds_read_b128 v[226:229], v193 offset:1024
	ds_read_b128 v[230:233], v193 offset:2048
	ds_read_b128 v[234:237], v193 offset:3072
	global_load_lds_dwordx4 v[174:175], off
	v_lshl_add_u64 v[174:175], v[238:239], 0, s[30:31]
	s_add_i32 m0, s19, 0x2000
	s_nop 0
	global_load_lds_dwordx4 v[174:175], off
	s_barrier
	s_waitcnt lgkmcnt(0)
	s_waitcnt lgkmcnt(0)
	v_mfma_f32_16x16x32_bf16 v[136:139], v[222:225], v[170:173], v[136:139]
	v_mfma_f32_16x16x32_bf16 v[132:135], v[230:233], v[170:173], v[132:135]
	v_mfma_f32_16x16x32_bf16 v[120:123], v[222:225], v[198:201], v[120:123]
	v_mfma_f32_16x16x32_bf16 v[116:119], v[230:233], v[198:201], v[116:119]
	v_mfma_f32_16x16x32_bf16 v[104:107], v[222:225], v[206:209], v[104:107]
	v_mfma_f32_16x16x32_bf16 v[100:103], v[230:233], v[206:209], v[100:103]
	v_mfma_f32_16x16x32_bf16 v[88:91], v[222:225], v[214:217], v[88:91]
	v_mfma_f32_16x16x32_bf16 v[84:87], v[230:233], v[214:217], v[84:87]
	v_mfma_f32_16x16x32_bf16 v[136:139], v[226:229], v[194:197], v[136:139]
	v_mfma_f32_16x16x32_bf16 v[132:135], v[234:237], v[194:197], v[132:135]
	v_mfma_f32_16x16x32_bf16 v[120:123], v[226:229], v[202:205], v[120:123]
	v_mfma_f32_16x16x32_bf16 v[116:119], v[234:237], v[202:205], v[116:119]
	v_mfma_f32_16x16x32_bf16 v[104:107], v[226:229], v[210:213], v[104:107]
	v_mfma_f32_16x16x32_bf16 v[100:103], v[234:237], v[210:213], v[100:103]
	v_mfma_f32_16x16x32_bf16 v[88:91], v[226:229], v[218:221], v[88:91]
	v_mfma_f32_16x16x32_bf16 v[84:87], v[234:237], v[218:221], v[84:87]
	s_mov_b32 m0, s47
	v_lshl_add_u64 v[174:175], v[240:241], 0, s[30:31]
	s_barrier
	ds_read_b128 v[170:173], v192 offset:49152
	ds_read_b128 v[194:197], v192 offset:50176
	ds_read_b128 v[198:201], v192 offset:51200
	ds_read_b128 v[202:205], v192 offset:52224
	ds_read_b128 v[206:209], v192 offset:53248
	ds_read_b128 v[210:213], v192 offset:54272
	ds_read_b128 v[214:217], v192 offset:55296
	ds_read_b128 v[218:221], v192 offset:56320
	global_load_lds_dwordx4 v[174:175], off
	v_lshl_add_u64 v[174:175], v[242:243], 0, s[30:31]
	s_mov_b32 m0, s48
	s_nop 0
	global_load_lds_dwordx4 v[174:175], off
	s_barrier
; #define PG8_STAGE(bufoff, gbase, voff) do { _Pragma("unroll") for (int _i = 0; _i < 2; ++_i) \
;         __builtin_amdgcn_global_load_lds((const unsigned*)((const char*)(gbase) + (voff)[_i]), (LAS unsigned*)(lds + (bufoff) + ldsw + _i * 8192), 16, 0, 0); } while (0)
; #define PG8_WAIT_V(n) asm volatile("s_waitcnt vmcnt(" #n ")" ::: "memory")
; #define PG8_WAIT_L(n) asm volatile("s_waitcnt lgkmcnt(" #n ")" ::: "memory")
; #define PG8_BAR __builtin_amdgcn_s_barrier()
; #define PG8_SCHED __builtin_amdgcn_sched_barrier(0)
; template <class Epi>
; __device__ __forceinline__ void gemm_phase(LAS unsigned char* lds, const Gemm g, const StaticOrder& S, const Epi& E, const int tid) {
;     ...
;             PG8_BAR; PG8_WAIT_L(0); PG8_MMA(1, 0, At, B0); PG8_BAR; PG8_SCHED;
;             PG8_STAGE(PG8_SB(1, 1), b3 + hstepB, voffB);
;             PG8_WAIT_V(6); PG8_BAR; PG8_MMA(1, 1, At, B1); PG8_BAR;
;         }
;         E(acc, cur, wr, wc, fr, fq);
;     __device__ __forceinline__ void operator()(const f32x4 (&acc)[2][2][4][2], const pg8::Unit& u, int wr, int wc, int fr, int fq) const {
;         const int row0 = u.pm * 256 + wr * 64 + fr, col0 = u.pn * 256 + wc * 32 + 8 * fq;
;         const float* gp = gate + (size_t)((u.pm * 256) >> 12) * 6144 + col0;
;         f32x4 gv[2][2];
; #pragma unroll
;         for (int bj = 0; bj < 2; ++bj)
; #pragma unroll
;             for (int n = 0; n < 2; ++n) gv[bj][n] = *(const f32x4*)(gp + bj * 128 + 4 * n);
; #pragma unroll
;         for (int ai = 0; ai < 2; ++ai)
; #pragma unroll
;             for (int m = 0; m < 4; ++m) { const size_t ro = (size_t)(row0 + ai * 128 + m * 16) * DM + col0;
	s_waitcnt lgkmcnt(0)
	s_waitcnt lgkmcnt(0)
	v_mfma_f32_16x16x32_bf16 v[80:83], v[60:63], v[170:173], v[80:83]
	v_mfma_f32_16x16x32_bf16 v[76:79], v[68:71], v[170:173], v[76:79]
	v_mfma_f32_16x16x32_bf16 v[56:59], v[60:63], v[198:201], v[56:59]
	v_mfma_f32_16x16x32_bf16 v[52:55], v[68:71], v[198:201], v[52:55]
	v_mfma_f32_16x16x32_bf16 v[40:43], v[60:63], v[206:209], v[40:43]
	v_mfma_f32_16x16x32_bf16 v[36:39], v[68:71], v[206:209], v[36:39]
	v_mfma_f32_16x16x32_bf16 v[16:19], v[60:63], v[214:217], v[16:19]
	v_mfma_f32_16x16x32_bf16 v[12:15], v[68:71], v[214:217], v[12:15]
	v_mfma_f32_16x16x32_bf16 v[80:83], v[64:67], v[194:197], v[80:83]
	v_mfma_f32_16x16x32_bf16 v[76:79], v[72:75], v[194:197], v[76:79]
	v_mfma_f32_16x16x32_bf16 v[56:59], v[64:67], v[202:205], v[56:59]
	v_mfma_f32_16x16x32_bf16 v[52:55], v[72:75], v[202:205], v[52:55]
	v_mfma_f32_16x16x32_bf16 v[40:43], v[64:67], v[210:213], v[40:43]
	v_mfma_f32_16x16x32_bf16 v[36:39], v[72:75], v[210:213], v[36:39]
	v_mfma_f32_16x16x32_bf16 v[16:19], v[64:67], v[218:221], v[16:19]
	v_mfma_f32_16x16x32_bf16 v[12:15], v[72:75], v[218:221], v[12:15]
	s_barrier
	s_add_u32 s14, s14, 0x80080
	s_addc_u32 s15, s15, 0
	s_add_i32 s18, s18, s40
	s_mov_b32 m0, s18
	s_nop 0
	global_load_lds_dwordx4 v2, s[14:15]
	v_lshl_add_u64 v[60:61], s[14:15], 0, v[0:1]
	s_add_i32 m0, s18, 0x2000
	s_nop 0
	global_load_lds_dwordx4 v[60:61], off
	s_waitcnt vmcnt(6)
	s_barrier
	v_mfma_f32_16x16x32_bf16 v[28:31], v[222:225], v[170:173], v[28:31]
	v_mfma_f32_16x16x32_bf16 v[72:75], v[226:229], v[194:197], v[28:31]
	v_mfma_f32_16x16x32_bf16 v[28:31], v[230:233], v[170:173], v[32:35]
	v_mfma_f32_16x16x32_bf16 v[68:71], v[234:237], v[194:197], v[28:31]
	v_mfma_f32_16x16x32_bf16 v[28:31], v[222:225], v[198:201], v[48:51]
	v_mfma_f32_16x16x32_bf16 v[48:51], v[226:229], v[202:205], v[28:31]
	v_mfma_f32_16x16x32_bf16 v[28:31], v[230:233], v[198:201], v[44:47]
	v_mfma_f32_16x16x32_bf16 v[24:27], v[222:225], v[206:209], v[24:27]
	v_mfma_f32_16x16x32_bf16 v[20:23], v[230:233], v[206:209], v[20:23]
	v_mfma_f32_16x16x32_bf16 v[8:11], v[222:225], v[214:217], v[8:11]
	v_mfma_f32_16x16x32_bf16 v[4:7], v[230:233], v[214:217], v[4:7]
	v_mfma_f32_16x16x32_bf16 v[44:47], v[234:237], v[202:205], v[28:31]
	v_mfma_f32_16x16x32_bf16 v[24:27], v[226:229], v[210:213], v[24:27]
	v_mfma_f32_16x16x32_bf16 v[20:23], v[234:237], v[210:213], v[20:23]
	v_mfma_f32_16x16x32_bf16 v[8:11], v[226:229], v[218:221], v[8:11]
	v_mfma_f32_16x16x32_bf16 v[4:7], v[234:237], v[218:221], v[4:7]
	s_add_i32 s56, s56, 2
	s_add_u32 s12, s12, 0x100
	s_addc_u32 s13, s13, 0
	s_add_u32 s54, s54, 0x100
	s_addc_u32 s55, s55, 0
	s_cmp_gt_u32 s56, 29
	s_barrier
	s_cbranch_scc0 .LBB0_660
	s_ashr_i32 s1, s50, 4
	v_lshl_add_u32 v172, s50, 8, v189
	v_lshl_or_b32 v170, s51, 8, v191
	s_mul_hi_i32 s7, s1, 0x6000
	s_mulk_i32 s1, 0x6000
	v_ashrrev_i32_e32 v173, 31, v172
	s_add_u32 s12, s23, s1
	v_ashrrev_i32_e32 v171, 31, v170
	v_lshlrev_b64 v[174:175], 12, v[172:173]
	s_addc_u32 s13, s24, s7
	v_lshl_add_u64 v[194:195], s[16:17], 0, v[174:175]
	v_lshlrev_b64 v[174:175], 1, v[170:171]
	v_lshl_add_u64 v[32:33], v[170:171], 2, s[12:13]
	v_lshl_add_u64 v[170:171], v[194:195], 0, v[174:175]
	global_load_dwordx4 v[60:63], v[32:33], off offset:16
	global_load_dwordx4 v[64:67], v[32:33], off
	global_load_dwordx4 v[28:31], v[32:33], off offset:528
	s_nop 0
	global_load_dwordx4 v[32:35], v[32:33], off offset:512
	v_add_co_u32_e32 v242, vcc, 0, v170
	s_nop 1
	v_addc_co_u32_e32 v243, vcc, 0, v171, vcc
	global_load_dwordx4 v[202:205], v[242:243], off
	v_add_co_u32_e32 v242, vcc, 0, v170
	s_nop 1
	v_addc_co_u32_e32 v243, vcc, 0, v171, vcc
	global_load_dwordx4 v[206:209], v[242:243], off offset:256
	v_add_co_u32_e32 v242, vcc, 0x10000, v170
	s_nop 1
	v_addc_co_u32_e32 v243, vcc, 0, v171, vcc
	global_load_dwordx4 v[210:213], v[242:243], off
	v_add_co_u32_e32 v242, vcc, 0x10000, v170
	s_nop 1
	v_addc_co_u32_e32 v243, vcc, 0, v171, vcc
	global_load_dwordx4 v[214:217], v[242:243], off offset:256
	v_add_co_u32_e32 v242, vcc, 0x20000, v170
	s_nop 1
	v_addc_co_u32_e32 v243, vcc, 0, v171, vcc
	global_load_dwordx4 v[218:221], v[242:243], off
	v_add_co_u32_e32 v242, vcc, 0x20000, v170
	s_nop 1
	v_addc_co_u32_e32 v243, vcc, 0, v171, vcc
	global_load_dwordx4 v[222:225], v[242:243], off offset:256
	v_add_co_u32_e32 v242, vcc, 0x30000, v170
	s_nop 1
	v_addc_co_u32_e32 v243, vcc, 0, v171, vcc
	global_load_dwordx4 v[226:229], v[242:243], off
	v_add_co_u32_e32 v242, vcc, 0x30000, v170
	s_nop 1
	v_addc_co_u32_e32 v243, vcc, 0, v171, vcc
	global_load_dwordx4 v[230:233], v[242:243], off offset:256
	v_add_co_u32_e32 v242, vcc, 0x80000, v170
	s_nop 1
	v_addc_co_u32_e32 v243, vcc, 0, v171, vcc
	global_load_dwordx4 v[234:237], v[242:243], off
	v_add_co_u32_e32 v242, vcc, 0x80000, v170
	s_nop 1
	v_addc_co_u32_e32 v243, vcc, 0, v171, vcc
	global_load_dwordx4 v[238:241], v[242:243], off offset:256
	v_add_co_u32_e32 v242, vcc, 0x90000, v170
	s_nop 1
	v_addc_co_u32_e32 v243, vcc, 0, v171, vcc
	global_load_dwordx4 v[244:247], v[242:243], off
	s_mov_b32 s1, 0x80000
	s_nop 1
	s_waitcnt vmcnt(10)
;     __device__ __forceinline__ void operator()(const f32x4 (&acc)[2][2][4][2], const pg8::Unit& u, int wr, int wc, int fr, int fq) const {
;     ...
;             for (int m = 0; m < 4; ++m) { const size_t ro = (size_t)(row0 + ai * 128 + m * 16) * DM + col0;
; #pragma unroll
;                 for (int bj = 0; bj < 2; ++bj) {
;                     f32x4 x0, x1;
;                     if (XF32) { x0 = *(const f32x4*)(xin + ro + bj * 128); x1 = *(const f32x4*)(xin + ro + bj * 128 + 4); }
;                     else { const h8 xh = *(const h8*)(H + ro + bj * 128); x0 = (f32x4){(float)xh[0], (float)xh[1], (float)xh[2], (float)xh[3]}; x1 = (f32x4){(float)xh[4], (float)xh[5], (float)xh[6], (float)xh[7]}; }
;                     const f32x4 y0 = x0 + gv[bj][0] * acc[ai][bj][m][0], y1 = x1 + gv[bj][1] * acc[ai][bj][m][1];
;                     h8 o; o[0] = (half_t)y0[0]; o[1] = (half_t)y0[1]; o[2] = (half_t)y0[2]; o[3] = (half_t)y0[3]; o[4] = (half_t)y1[0]; o[5] = (half_t)y1[1]; o[6] = (half_t)y1[2]; o[7] = (half_t)y1[3];
;                     *(h8*)(H + ro + bj * 128) = o; } }
	v_mov_b32_e32 v194, v202
	v_mov_b32_e32 v195, v203
	v_mov_b32_e32 v196, v204
	v_mov_b32_e32 v197, v205
	v_add_co_u32_e32 v242, vcc, 0x90000, v170
	s_nop 1
	v_addc_co_u32_e32 v243, vcc, 0, v171, vcc
	global_load_dwordx4 v[202:205], v[242:243], off offset:256
	s_mov_b64 s[12:13], 0x80000
	s_mov_b32 s51, s0
	s_mov_b32 s50, s6
	s_mov_b64 s[14:15], s[10:11]
	v_readlane_b32 s59, v251, 43
	s_nop 0
	v_cvt_f32_f16_e32 v198, v194
	v_cvt_f32_f16_sdwa v199, v194 dst_sel:DWORD dst_unused:UNUSED_PAD src0_sel:WORD_1
	v_cvt_f32_f16_e32 v194, v195
	v_cvt_f32_f16_sdwa v195, v195 dst_sel:DWORD dst_unused:UNUSED_PAD src0_sel:WORD_1
	v_cvt_f32_f16_e32 v200, v196
	v_cvt_f32_f16_sdwa v201, v196 dst_sel:DWORD dst_unused:UNUSED_PAD src0_sel:WORD_1
	v_cvt_f32_f16_e32 v196, v197
	v_cvt_f32_f16_sdwa v197, v197 dst_sel:DWORD dst_unused:UNUSED_PAD src0_sel:WORD_1
	v_pk_fma_f32 v[146:147], v[146:147], v[66:67], v[194:195]
	v_pk_fma_f32 v[144:145], v[144:145], v[64:65], v[198:199]
	v_pk_fma_f32 v[140:141], v[140:141], v[60:61], v[200:201]
	v_pk_fma_f32 v[142:143], v[142:143], v[62:63], v[196:197]
	s_nop 0
	v_cvt_pk_f16_f32 v143, v142, v143
	v_cvt_pk_f16_f32 v142, v140, v141
	v_cvt_pk_f16_f32 v141, v146, v147
	v_cvt_pk_f16_f32 v140, v144, v145
	global_store_dwordx4 v[170:171], v[140:143], off
	s_nop 1
	s_waitcnt vmcnt(10)
	v_mov_b32_e32 v140, v206
	v_mov_b32_e32 v141, v207
	v_mov_b32_e32 v142, v208
	v_mov_b32_e32 v143, v209
	v_add_co_u32_e32 v242, vcc, 0xa0000, v170
	s_nop 1
	v_addc_co_u32_e32 v243, vcc, 0, v171, vcc
	global_load_dwordx4 v[206:209], v[242:243], off
	s_nop 0
	v_cvt_f32_f16_e32 v144, v140
	v_cvt_f32_f16_sdwa v145, v140 dst_sel:DWORD dst_unused:UNUSED_PAD src0_sel:WORD_1
	v_cvt_f32_f16_e32 v140, v141
	v_cvt_f32_f16_sdwa v141, v141 dst_sel:DWORD dst_unused:UNUSED_PAD src0_sel:WORD_1
	v_cvt_f32_f16_e32 v146, v142
	v_cvt_f32_f16_sdwa v147, v142 dst_sel:DWORD dst_unused:UNUSED_PAD src0_sel:WORD_1
	v_cvt_f32_f16_e32 v142, v143
	v_cvt_f32_f16_sdwa v143, v143 dst_sel:DWORD dst_unused:UNUSED_PAD src0_sel:WORD_1
	v_pk_fma_f32 v[138:139], v[138:139], v[34:35], v[140:141]
	v_pk_fma_f32 v[136:137], v[136:137], v[32:33], v[144:145]
	v_pk_fma_f32 v[132:133], v[132:133], v[28:29], v[146:147]
	v_pk_fma_f32 v[134:135], v[134:135], v[30:31], v[142:143]
	s_nop 0
	v_cvt_pk_f16_f32 v135, v134, v135
	v_cvt_pk_f16_f32 v134, v132, v133
	v_cvt_pk_f16_f32 v133, v138, v139
	v_cvt_pk_f16_f32 v132, v136, v137
	global_store_dwordx4 v[170:171], v[132:135], off offset:256
	s_nop 1
	v_or_b32_e32 v132, 16, v172
	v_ashrrev_i32_e32 v133, 31, v132
	v_lshlrev_b64 v[132:133], 12, v[132:133]
	v_lshl_add_u64 v[132:133], s[16:17], 0, v[132:133]
	v_lshl_add_u64 v[136:137], v[132:133], 0, v[174:175]
	s_nop 1
	s_waitcnt vmcnt(10)
	v_mov_b32_e32 v132, v210
	v_mov_b32_e32 v133, v211
	v_mov_b32_e32 v134, v212
	v_mov_b32_e32 v135, v213
	v_add_co_u32_e32 v242, vcc, 0xa0000, v170
	s_nop 1
	v_addc_co_u32_e32 v243, vcc, 0, v171, vcc
	global_load_dwordx4 v[210:213], v[242:243], off offset:256
	s_nop 0
	v_cvt_f32_f16_e32 v138, v132
	v_cvt_f32_f16_sdwa v139, v132 dst_sel:DWORD dst_unused:UNUSED_PAD src0_sel:WORD_1
	v_cvt_f32_f16_e32 v132, v133
	v_cvt_f32_f16_sdwa v133, v133 dst_sel:DWORD dst_unused:UNUSED_PAD src0_sel:WORD_1
	v_cvt_f32_f16_e32 v140, v134
	v_cvt_f32_f16_sdwa v141, v134 dst_sel:DWORD dst_unused:UNUSED_PAD src0_sel:WORD_1
	v_cvt_f32_f16_e32 v134, v135
	v_cvt_f32_f16_sdwa v135, v135 dst_sel:DWORD dst_unused:UNUSED_PAD src0_sel:WORD_1
	v_pk_fma_f32 v[130:131], v[130:131], v[66:67], v[132:133]
	v_pk_fma_f32 v[128:129], v[128:129], v[64:65], v[138:139]
	v_pk_fma_f32 v[124:125], v[124:125], v[60:61], v[140:141]
	v_pk_fma_f32 v[126:127], v[126:127], v[62:63], v[134:135]
	s_nop 0
	v_cvt_pk_f16_f32 v127, v126, v127
	v_cvt_pk_f16_f32 v126, v124, v125
	v_cvt_pk_f16_f32 v125, v130, v131
	v_cvt_pk_f16_f32 v124, v128, v129
	global_store_dwordx4 v[136:137], v[124:127], off
	s_nop 1
	s_waitcnt vmcnt(10)
	v_mov_b32_e32 v124, v214
	v_mov_b32_e32 v125, v215
	v_mov_b32_e32 v126, v216
	v_mov_b32_e32 v127, v217
	v_add_co_u32_e32 v242, vcc, 0xb0000, v170
	s_nop 1
	v_addc_co_u32_e32 v243, vcc, 0, v171, vcc
	global_load_dwordx4 v[214:217], v[242:243], off
	s_nop 0
	v_cvt_f32_f16_e32 v128, v124
	v_cvt_f32_f16_sdwa v129, v124 dst_sel:DWORD dst_unused:UNUSED_PAD src0_sel:WORD_1
	v_cvt_f32_f16_e32 v124, v125
	v_cvt_f32_f16_sdwa v125, v125 dst_sel:DWORD dst_unused:UNUSED_PAD src0_sel:WORD_1
	v_cvt_f32_f16_e32 v130, v126
	v_cvt_f32_f16_sdwa v131, v126 dst_sel:DWORD dst_unused:UNUSED_PAD src0_sel:WORD_1
	v_cvt_f32_f16_e32 v126, v127
	v_cvt_f32_f16_sdwa v127, v127 dst_sel:DWORD dst_unused:UNUSED_PAD src0_sel:WORD_1
	v_pk_fma_f32 v[122:123], v[122:123], v[34:35], v[124:125]
	v_pk_fma_f32 v[120:121], v[120:121], v[32:33], v[128:129]
	v_pk_fma_f32 v[116:117], v[116:117], v[28:29], v[130:131]
	v_pk_fma_f32 v[118:119], v[118:119], v[30:31], v[126:127]
	s_nop 0
	v_cvt_pk_f16_f32 v119, v118, v119
	v_cvt_pk_f16_f32 v118, v116, v117
	v_cvt_pk_f16_f32 v117, v122, v123
	v_cvt_pk_f16_f32 v116, v120, v121
	global_store_dwordx4 v[136:137], v[116:119], off offset:256
	s_nop 1
	v_or_b32_e32 v116, 32, v172
	v_ashrrev_i32_e32 v117, 31, v116
	v_lshlrev_b64 v[116:117], 12, v[116:117]
	v_lshl_add_u64 v[116:117], s[16:17], 0, v[116:117]
	v_lshl_add_u64 v[120:121], v[116:117], 0, v[174:175]
	s_nop 1
	s_waitcnt vmcnt(10)
;     __device__ __forceinline__ void operator()(const f32x4 (&acc)[2][2][4][2], const pg8::Unit& u, int wr, int wc, int fr, int fq) const {
;     ...
;             for (int m = 0; m < 4; ++m) { const size_t ro = (size_t)(row0 + ai * 128 + m * 16) * DM + col0;
; #pragma unroll
;                 for (int bj = 0; bj < 2; ++bj) {
;                     f32x4 x0, x1;
;                     if (XF32) { x0 = *(const f32x4*)(xin + ro + bj * 128); x1 = *(const f32x4*)(xin + ro + bj * 128 + 4); }
;                     else { const h8 xh = *(const h8*)(H + ro + bj * 128); x0 = (f32x4){(float)xh[0], (float)xh[1], (float)xh[2], (float)xh[3]}; x1 = (f32x4){(float)xh[4], (float)xh[5], (float)xh[6], (float)xh[7]}; }
;                     const f32x4 y0 = x0 + gv[bj][0] * acc[ai][bj][m][0], y1 = x1 + gv[bj][1] * acc[ai][bj][m][1];
;                     h8 o; o[0] = (half_t)y0[0]; o[1] = (half_t)y0[1]; o[2] = (half_t)y0[2]; o[3] = (half_t)y0[3]; o[4] = (half_t)y1[0]; o[5] = (half_t)y1[1]; o[6] = (half_t)y1[2]; o[7] = (half_t)y1[3];
;                     *(h8*)(H + ro + bj * 128) = o; } }
	v_mov_b32_e32 v116, v218
	v_mov_b32_e32 v117, v219
	v_mov_b32_e32 v118, v220
	v_mov_b32_e32 v119, v221
	v_add_co_u32_e32 v242, vcc, 0xb0000, v170
	s_nop 1
	v_addc_co_u32_e32 v243, vcc, 0, v171, vcc
	global_load_dwordx4 v[218:221], v[242:243], off offset:256
	s_nop 0
	v_cvt_f32_f16_e32 v122, v116
	v_cvt_f32_f16_sdwa v123, v116 dst_sel:DWORD dst_unused:UNUSED_PAD src0_sel:WORD_1
	v_cvt_f32_f16_e32 v116, v117
	v_cvt_f32_f16_sdwa v117, v117 dst_sel:DWORD dst_unused:UNUSED_PAD src0_sel:WORD_1
	v_cvt_f32_f16_e32 v124, v118
	v_cvt_f32_f16_sdwa v125, v118 dst_sel:DWORD dst_unused:UNUSED_PAD src0_sel:WORD_1
	v_cvt_f32_f16_e32 v118, v119
	v_cvt_f32_f16_sdwa v119, v119 dst_sel:DWORD dst_unused:UNUSED_PAD src0_sel:WORD_1
	v_pk_fma_f32 v[114:115], v[114:115], v[66:67], v[116:117]
	v_pk_fma_f32 v[112:113], v[112:113], v[64:65], v[122:123]
	v_pk_fma_f32 v[108:109], v[108:109], v[60:61], v[124:125]
	v_pk_fma_f32 v[110:111], v[110:111], v[62:63], v[118:119]
	s_nop 0
	v_cvt_pk_f16_f32 v111, v110, v111
	v_cvt_pk_f16_f32 v110, v108, v109
	v_cvt_pk_f16_f32 v109, v114, v115
	v_cvt_pk_f16_f32 v108, v112, v113
	global_store_dwordx4 v[120:121], v[108:111], off
	s_nop 1
	s_waitcnt vmcnt(10)
	v_mov_b32_e32 v108, v222
	v_mov_b32_e32 v109, v223
	v_mov_b32_e32 v110, v224
	v_mov_b32_e32 v111, v225
	s_nop 0
	v_cvt_f32_f16_e32 v112, v108
	v_cvt_f32_f16_sdwa v113, v108 dst_sel:DWORD dst_unused:UNUSED_PAD src0_sel:WORD_1
	v_cvt_f32_f16_e32 v108, v109
	v_cvt_f32_f16_sdwa v109, v109 dst_sel:DWORD dst_unused:UNUSED_PAD src0_sel:WORD_1
	v_cvt_f32_f16_e32 v114, v110
	v_cvt_f32_f16_sdwa v115, v110 dst_sel:DWORD dst_unused:UNUSED_PAD src0_sel:WORD_1
	v_cvt_f32_f16_e32 v110, v111
	v_cvt_f32_f16_sdwa v111, v111 dst_sel:DWORD dst_unused:UNUSED_PAD src0_sel:WORD_1
	v_pk_fma_f32 v[106:107], v[106:107], v[34:35], v[108:109]
	v_pk_fma_f32 v[104:105], v[104:105], v[32:33], v[112:113]
	v_pk_fma_f32 v[100:101], v[100:101], v[28:29], v[114:115]
	v_pk_fma_f32 v[102:103], v[102:103], v[30:31], v[110:111]
	s_nop 0
	v_cvt_pk_f16_f32 v103, v102, v103
	v_cvt_pk_f16_f32 v102, v100, v101
	v_cvt_pk_f16_f32 v101, v106, v107
	v_cvt_pk_f16_f32 v100, v104, v105
	global_store_dwordx4 v[120:121], v[100:103], off offset:256
	s_nop 1
	v_or_b32_e32 v100, 48, v172
	v_ashrrev_i32_e32 v101, 31, v100
	v_lshlrev_b64 v[100:101], 12, v[100:101]
	v_lshl_add_u64 v[100:101], s[16:17], 0, v[100:101]
	v_lshl_add_u64 v[104:105], v[100:101], 0, v[174:175]
	s_nop 1
	s_waitcnt vmcnt(9)
	v_mov_b32_e32 v100, v226
	v_mov_b32_e32 v101, v227
	v_mov_b32_e32 v102, v228
	v_mov_b32_e32 v103, v229
	s_nop 0
	v_cvt_f32_f16_e32 v106, v100
	v_cvt_f32_f16_sdwa v107, v100 dst_sel:DWORD dst_unused:UNUSED_PAD src0_sel:WORD_1
	v_cvt_f32_f16_e32 v100, v101
	v_cvt_f32_f16_sdwa v101, v101 dst_sel:DWORD dst_unused:UNUSED_PAD src0_sel:WORD_1
	v_cvt_f32_f16_e32 v108, v102
	v_cvt_f32_f16_sdwa v109, v102 dst_sel:DWORD dst_unused:UNUSED_PAD src0_sel:WORD_1
	v_cvt_f32_f16_e32 v102, v103
	v_cvt_f32_f16_sdwa v103, v103 dst_sel:DWORD dst_unused:UNUSED_PAD src0_sel:WORD_1
	v_pk_fma_f32 v[98:99], v[98:99], v[66:67], v[100:101]
	v_pk_fma_f32 v[96:97], v[96:97], v[64:65], v[106:107]
	v_pk_fma_f32 v[92:93], v[92:93], v[60:61], v[108:109]
	v_pk_fma_f32 v[94:95], v[94:95], v[62:63], v[102:103]
	s_nop 0
	v_cvt_pk_f16_f32 v95, v94, v95
	v_cvt_pk_f16_f32 v94, v92, v93
	v_cvt_pk_f16_f32 v93, v98, v99
	v_cvt_pk_f16_f32 v92, v96, v97
	global_store_dwordx4 v[104:105], v[92:95], off
	s_nop 1
	s_waitcnt vmcnt(8)
	v_mov_b32_e32 v92, v230
	v_mov_b32_e32 v93, v231
	v_mov_b32_e32 v94, v232
	v_mov_b32_e32 v95, v233
	s_nop 0
	v_cvt_f32_f16_e32 v96, v92
	v_cvt_f32_f16_sdwa v97, v92 dst_sel:DWORD dst_unused:UNUSED_PAD src0_sel:WORD_1
	v_cvt_f32_f16_e32 v92, v93
	v_cvt_f32_f16_sdwa v93, v93 dst_sel:DWORD dst_unused:UNUSED_PAD src0_sel:WORD_1
	v_cvt_f32_f16_e32 v98, v94
	v_cvt_f32_f16_sdwa v99, v94 dst_sel:DWORD dst_unused:UNUSED_PAD src0_sel:WORD_1
	v_cvt_f32_f16_e32 v94, v95
	v_cvt_f32_f16_sdwa v95, v95 dst_sel:DWORD dst_unused:UNUSED_PAD src0_sel:WORD_1
	v_pk_fma_f32 v[90:91], v[90:91], v[34:35], v[92:93]
	v_pk_fma_f32 v[84:85], v[84:85], v[28:29], v[98:99]
	v_pk_fma_f32 v[88:89], v[88:89], v[32:33], v[96:97]
	v_pk_fma_f32 v[86:87], v[86:87], v[30:31], v[94:95]
	s_nop 0
	v_cvt_pk_f16_f32 v87, v86, v87
	v_cvt_pk_f16_f32 v86, v84, v85
	v_cvt_pk_f16_f32 v85, v90, v91
	v_add_co_u32_e32 v90, vcc, s1, v170
	v_cvt_pk_f16_f32 v84, v88, v89
	s_nop 0
	v_addc_co_u32_e32 v91, vcc, 0, v171, vcc
	global_store_dwordx4 v[104:105], v[84:87], off offset:256
	s_nop 1
	s_waitcnt vmcnt(7)
	v_mov_b32_e32 v86, v234
	v_mov_b32_e32 v87, v235
	v_mov_b32_e32 v88, v236
	v_mov_b32_e32 v89, v237
	s_mov_b32 s1, 0x90000
	v_lshl_add_u64 v[84:85], v[170:171], 0, s[12:13]
	s_mov_b64 s[12:13], 0x90000
	s_nop 0
	v_cvt_f32_f16_e32 v92, v86
	v_cvt_f32_f16_sdwa v93, v86 dst_sel:DWORD dst_unused:UNUSED_PAD src0_sel:WORD_1
	v_cvt_f32_f16_e32 v86, v87
	v_cvt_f32_f16_sdwa v87, v87 dst_sel:DWORD dst_unused:UNUSED_PAD src0_sel:WORD_1
	v_cvt_f32_f16_e32 v94, v88
	v_cvt_f32_f16_sdwa v95, v88 dst_sel:DWORD dst_unused:UNUSED_PAD src0_sel:WORD_1
	v_cvt_f32_f16_e32 v88, v89
	v_cvt_f32_f16_sdwa v89, v89 dst_sel:DWORD dst_unused:UNUSED_PAD src0_sel:WORD_1
	v_pk_fma_f32 v[82:83], v[82:83], v[66:67], v[86:87]
	v_pk_fma_f32 v[80:81], v[80:81], v[64:65], v[92:93]
	v_pk_fma_f32 v[76:77], v[76:77], v[60:61], v[94:95]
	v_pk_fma_f32 v[78:79], v[78:79], v[62:63], v[88:89]
	s_nop 0
	v_cvt_pk_f16_f32 v79, v78, v79
	v_cvt_pk_f16_f32 v78, v76, v77
	v_cvt_pk_f16_f32 v77, v82, v83
	v_cvt_pk_f16_f32 v76, v80, v81
	global_store_dwordx4 v[90:91], v[76:79], off
	s_nop 1
	s_waitcnt vmcnt(6)
;     __device__ __forceinline__ void operator()(const f32x4 (&acc)[2][2][4][2], const pg8::Unit& u, int wr, int wc, int fr, int fq) const {
;     ...
;             for (int m = 0; m < 4; ++m) { const size_t ro = (size_t)(row0 + ai * 128 + m * 16) * DM + col0;
; #pragma unroll
;                 for (int bj = 0; bj < 2; ++bj) {
;                     f32x4 x0, x1;
;                     if (XF32) { x0 = *(const f32x4*)(xin + ro + bj * 128); x1 = *(const f32x4*)(xin + ro + bj * 128 + 4); }
;                     else { const h8 xh = *(const h8*)(H + ro + bj * 128); x0 = (f32x4){(float)xh[0], (float)xh[1], (float)xh[2], (float)xh[3]}; x1 = (f32x4){(float)xh[4], (float)xh[5], (float)xh[6], (float)xh[7]}; }
;                     const f32x4 y0 = x0 + gv[bj][0] * acc[ai][bj][m][0], y1 = x1 + gv[bj][1] * acc[ai][bj][m][1];
;                     h8 o; o[0] = (half_t)y0[0]; o[1] = (half_t)y0[1]; o[2] = (half_t)y0[2]; o[3] = (half_t)y0[3]; o[4] = (half_t)y1[0]; o[5] = (half_t)y1[1]; o[6] = (half_t)y1[2]; o[7] = (half_t)y1[3];
;                     *(h8*)(H + ro + bj * 128) = o; } }
	v_mov_b32_e32 v76, v238
	v_mov_b32_e32 v77, v239
	v_mov_b32_e32 v78, v240
	v_mov_b32_e32 v79, v241
	s_nop 0
	v_cvt_f32_f16_e32 v80, v76
	v_cvt_f32_f16_sdwa v81, v76 dst_sel:DWORD dst_unused:UNUSED_PAD src0_sel:WORD_1
	v_cvt_f32_f16_e32 v76, v77
	v_cvt_f32_f16_sdwa v77, v77 dst_sel:DWORD dst_unused:UNUSED_PAD src0_sel:WORD_1
	v_cvt_f32_f16_e32 v82, v78
	v_cvt_f32_f16_sdwa v83, v78 dst_sel:DWORD dst_unused:UNUSED_PAD src0_sel:WORD_1
	v_cvt_f32_f16_e32 v78, v79
	v_cvt_f32_f16_sdwa v79, v79 dst_sel:DWORD dst_unused:UNUSED_PAD src0_sel:WORD_1
	v_pk_fma_f32 v[74:75], v[74:75], v[34:35], v[76:77]
	v_pk_fma_f32 v[68:69], v[68:69], v[28:29], v[82:83]
	v_pk_fma_f32 v[72:73], v[72:73], v[32:33], v[80:81]
	v_pk_fma_f32 v[70:71], v[70:71], v[30:31], v[78:79]
	s_nop 0
	v_cvt_pk_f16_f32 v71, v70, v71
	v_cvt_pk_f16_f32 v70, v68, v69
	v_cvt_pk_f16_f32 v69, v74, v75
	v_add_co_u32_e32 v74, vcc, s1, v170
	v_cvt_pk_f16_f32 v68, v72, v73
	s_nop 0
	v_addc_co_u32_e32 v75, vcc, 0, v171, vcc
	global_store_dwordx4 v[84:85], v[68:71], off offset:256
	s_nop 1
	s_waitcnt vmcnt(5)
	v_mov_b32_e32 v70, v244
	v_mov_b32_e32 v71, v245
	v_mov_b32_e32 v72, v246
	v_mov_b32_e32 v73, v247
	s_mov_b32 s1, 0xa0000
	v_lshl_add_u64 v[68:69], v[170:171], 0, s[12:13]
	s_mov_b64 s[12:13], 0xa0000
	s_nop 0
	v_cvt_f32_f16_e32 v76, v70
	v_cvt_f32_f16_sdwa v77, v70 dst_sel:DWORD dst_unused:UNUSED_PAD src0_sel:WORD_1
	v_cvt_f32_f16_e32 v70, v71
	v_cvt_f32_f16_sdwa v71, v71 dst_sel:DWORD dst_unused:UNUSED_PAD src0_sel:WORD_1
	v_cvt_f32_f16_e32 v78, v72
	v_cvt_f32_f16_sdwa v79, v72 dst_sel:DWORD dst_unused:UNUSED_PAD src0_sel:WORD_1
	v_cvt_f32_f16_e32 v72, v73
	v_cvt_f32_f16_sdwa v73, v73 dst_sel:DWORD dst_unused:UNUSED_PAD src0_sel:WORD_1
	v_pk_fma_f32 v[58:59], v[58:59], v[66:67], v[70:71]
	v_pk_fma_f32 v[56:57], v[56:57], v[64:65], v[76:77]
	v_pk_fma_f32 v[52:53], v[52:53], v[60:61], v[78:79]
	v_pk_fma_f32 v[54:55], v[54:55], v[62:63], v[72:73]
	s_nop 0
	v_cvt_pk_f16_f32 v55, v54, v55
	v_cvt_pk_f16_f32 v54, v52, v53
	v_cvt_pk_f16_f32 v53, v58, v59
	v_cvt_pk_f16_f32 v52, v56, v57
	global_store_dwordx4 v[74:75], v[52:55], off
	s_nop 1
	s_waitcnt vmcnt(4)
	v_mov_b32_e32 v52, v202
	v_mov_b32_e32 v53, v203
	v_mov_b32_e32 v54, v204
	v_mov_b32_e32 v55, v205
	s_nop 0
	v_cvt_f32_f16_e32 v56, v52
	v_cvt_f32_f16_sdwa v57, v52 dst_sel:DWORD dst_unused:UNUSED_PAD src0_sel:WORD_1
	v_cvt_f32_f16_e32 v52, v53
	v_cvt_f32_f16_sdwa v53, v53 dst_sel:DWORD dst_unused:UNUSED_PAD src0_sel:WORD_1
	v_cvt_f32_f16_e32 v58, v54
	v_cvt_f32_f16_sdwa v59, v54 dst_sel:DWORD dst_unused:UNUSED_PAD src0_sel:WORD_1
	v_cvt_f32_f16_e32 v54, v55
	v_cvt_f32_f16_sdwa v55, v55 dst_sel:DWORD dst_unused:UNUSED_PAD src0_sel:WORD_1
	v_pk_fma_f32 v[50:51], v[50:51], v[34:35], v[52:53]
	v_pk_fma_f32 v[44:45], v[44:45], v[28:29], v[58:59]
	v_pk_fma_f32 v[48:49], v[48:49], v[32:33], v[56:57]
	v_pk_fma_f32 v[46:47], v[46:47], v[30:31], v[54:55]
	s_nop 0
	v_cvt_pk_f16_f32 v47, v46, v47
	v_cvt_pk_f16_f32 v46, v44, v45
	v_cvt_pk_f16_f32 v45, v50, v51
	v_add_co_u32_e32 v50, vcc, s1, v170
	v_cvt_pk_f16_f32 v44, v48, v49
	s_nop 0
	v_addc_co_u32_e32 v51, vcc, 0, v171, vcc
	global_store_dwordx4 v[68:69], v[44:47], off offset:256
	s_nop 1
	s_waitcnt vmcnt(3)
	v_mov_b32_e32 v46, v206
	v_mov_b32_e32 v47, v207
	v_mov_b32_e32 v48, v208
	v_mov_b32_e32 v49, v209
	s_mov_b32 s1, 0xb0000
	v_lshl_add_u64 v[44:45], v[170:171], 0, s[12:13]
	s_mov_b64 s[12:13], 0xb0000
	s_nop 0
	v_cvt_f32_f16_e32 v52, v46
	v_cvt_f32_f16_sdwa v53, v46 dst_sel:DWORD dst_unused:UNUSED_PAD src0_sel:WORD_1
	v_cvt_f32_f16_e32 v46, v47
	v_cvt_f32_f16_sdwa v47, v47 dst_sel:DWORD dst_unused:UNUSED_PAD src0_sel:WORD_1
	v_cvt_f32_f16_e32 v54, v48
	v_cvt_f32_f16_sdwa v55, v48 dst_sel:DWORD dst_unused:UNUSED_PAD src0_sel:WORD_1
	v_cvt_f32_f16_e32 v48, v49
	v_cvt_f32_f16_sdwa v49, v49 dst_sel:DWORD dst_unused:UNUSED_PAD src0_sel:WORD_1
	v_pk_fma_f32 v[42:43], v[42:43], v[66:67], v[46:47]
	v_pk_fma_f32 v[40:41], v[40:41], v[64:65], v[52:53]
	v_pk_fma_f32 v[36:37], v[36:37], v[60:61], v[54:55]
	v_pk_fma_f32 v[38:39], v[38:39], v[62:63], v[48:49]
	s_nop 0
	v_cvt_pk_f16_f32 v39, v38, v39
	v_cvt_pk_f16_f32 v38, v36, v37
	v_cvt_pk_f16_f32 v37, v42, v43
	v_cvt_pk_f16_f32 v36, v40, v41
	global_store_dwordx4 v[50:51], v[36:39], off
	s_nop 1
	s_waitcnt vmcnt(2)
; #define PG8_WAIT_V(n) asm volatile("s_waitcnt vmcnt(" #n ")" ::: "memory")
; #define PG8_BAR __builtin_amdgcn_s_barrier()
; template <class Epi>
; __device__ __forceinline__ void gemm_phase(LAS unsigned char* lds, const Gemm g, const StaticOrder& S, const Epi& E, const int tid) {
;     ...
;         if (!has_next) break;
; #pragma unroll
;         for (int a = 0; a < 2; ++a)
; #pragma unroll
;             for (int b = 0; b < 2; ++b)
; #pragma unroll
;                 for (int m = 0; m < 4; ++m)
; #pragma unroll
;                     for (int n = 0; n < 2; ++n) acc[a][b][m][n] = (f32x4){0.f, 0.f, 0.f, 0.f};
;         cur = nxt; cA = nA; cB = nB; ++ui;
;     }
;     PG8_WAIT_V(0);
;     if (wr == 0) PG8_BAR;
;     PG8_BAR;
;     __device__ __forceinline__ void operator()(const f32x4 (&acc)[2][2][4][2], const pg8::Unit& u, int wr, int wc, int fr, int fq) const {
;     ...
;             for (int m = 0; m < 4; ++m) { const size_t ro = (size_t)(row0 + ai * 128 + m * 16) * DM + col0;
; #pragma unroll
;                 for (int bj = 0; bj < 2; ++bj) {
;                     f32x4 x0, x1;
;                     if (XF32) { x0 = *(const f32x4*)(xin + ro + bj * 128); x1 = *(const f32x4*)(xin + ro + bj * 128 + 4); }
;                     else { const h8 xh = *(const h8*)(H + ro + bj * 128); x0 = (f32x4){(float)xh[0], (float)xh[1], (float)xh[2], (float)xh[3]}; x1 = (f32x4){(float)xh[4], (float)xh[5], (float)xh[6], (float)xh[7]}; }
;                     const f32x4 y0 = x0 + gv[bj][0] * acc[ai][bj][m][0], y1 = x1 + gv[bj][1] * acc[ai][bj][m][1];
;                     h8 o; o[0] = (half_t)y0[0]; o[1] = (half_t)y0[1]; o[2] = (half_t)y0[2]; o[3] = (half_t)y0[3]; o[4] = (half_t)y1[0]; o[5] = (half_t)y1[1]; o[6] = (half_t)y1[2]; o[7] = (half_t)y1[3];
;                     *(h8*)(H + ro + bj * 128) = o; } }
	v_mov_b32_e32 v36, v210
	v_mov_b32_e32 v37, v211
	v_mov_b32_e32 v38, v212
	v_mov_b32_e32 v39, v213
	s_nop 0
	v_cvt_f32_f16_e32 v40, v36
	v_cvt_f32_f16_sdwa v41, v36 dst_sel:DWORD dst_unused:UNUSED_PAD src0_sel:WORD_1
	v_cvt_f32_f16_e32 v36, v37
	v_cvt_f32_f16_sdwa v37, v37 dst_sel:DWORD dst_unused:UNUSED_PAD src0_sel:WORD_1
	v_cvt_f32_f16_e32 v42, v38
	v_cvt_f32_f16_sdwa v43, v38 dst_sel:DWORD dst_unused:UNUSED_PAD src0_sel:WORD_1
	v_cvt_f32_f16_e32 v38, v39
	v_cvt_f32_f16_sdwa v39, v39 dst_sel:DWORD dst_unused:UNUSED_PAD src0_sel:WORD_1
	v_pk_fma_f32 v[26:27], v[26:27], v[34:35], v[36:37]
	v_pk_fma_f32 v[20:21], v[20:21], v[28:29], v[42:43]
	v_pk_fma_f32 v[24:25], v[24:25], v[32:33], v[40:41]
	v_pk_fma_f32 v[22:23], v[22:23], v[30:31], v[38:39]
	s_nop 0
	v_cvt_pk_f16_f32 v23, v22, v23
	v_cvt_pk_f16_f32 v22, v20, v21
	v_cvt_pk_f16_f32 v21, v26, v27
	v_add_co_u32_e32 v26, vcc, s1, v170
	v_cvt_pk_f16_f32 v20, v24, v25
	s_nop 0
	v_addc_co_u32_e32 v27, vcc, 0, v171, vcc
	global_store_dwordx4 v[44:45], v[20:23], off offset:256
	s_nop 1
	s_waitcnt vmcnt(1)
	v_mov_b32_e32 v22, v214
	v_mov_b32_e32 v23, v215
	v_mov_b32_e32 v24, v216
	v_mov_b32_e32 v25, v217
	s_and_b64 vcc, exec, s[4:5]
	v_lshl_add_u64 v[20:21], v[170:171], 0, s[12:13]
	s_mov_b64 s[12:13], s[8:9]
	s_nop 0
	v_cvt_f32_f16_e32 v36, v22
	v_cvt_f32_f16_sdwa v37, v22 dst_sel:DWORD dst_unused:UNUSED_PAD src0_sel:WORD_1
	v_cvt_f32_f16_e32 v22, v23
	v_cvt_f32_f16_sdwa v23, v23 dst_sel:DWORD dst_unused:UNUSED_PAD src0_sel:WORD_1
	v_cvt_f32_f16_e32 v38, v24
	v_cvt_f32_f16_sdwa v39, v24 dst_sel:DWORD dst_unused:UNUSED_PAD src0_sel:WORD_1
	v_cvt_f32_f16_e32 v24, v25
	v_cvt_f32_f16_sdwa v25, v25 dst_sel:DWORD dst_unused:UNUSED_PAD src0_sel:WORD_1
	v_pk_fma_f32 v[18:19], v[18:19], v[66:67], v[22:23]
	v_pk_fma_f32 v[16:17], v[16:17], v[64:65], v[36:37]
	v_pk_fma_f32 v[12:13], v[12:13], v[60:61], v[38:39]
	v_pk_fma_f32 v[14:15], v[14:15], v[62:63], v[24:25]
	s_nop 0
	v_cvt_pk_f16_f32 v15, v14, v15
	v_cvt_pk_f16_f32 v14, v12, v13
	v_cvt_pk_f16_f32 v13, v18, v19
	v_cvt_pk_f16_f32 v12, v16, v17
	global_store_dwordx4 v[26:27], v[12:15], off
	s_nop 1
	s_waitcnt vmcnt(0)
	v_mov_b32_e32 v12, v218
	v_mov_b32_e32 v13, v219
	v_mov_b32_e32 v14, v220
	v_mov_b32_e32 v15, v221
	s_nop 0
	v_cvt_f32_f16_e32 v16, v12
	v_cvt_f32_f16_sdwa v17, v12 dst_sel:DWORD dst_unused:UNUSED_PAD src0_sel:WORD_1
	v_cvt_f32_f16_e32 v12, v13
	v_cvt_f32_f16_sdwa v13, v13 dst_sel:DWORD dst_unused:UNUSED_PAD src0_sel:WORD_1
	v_cvt_f32_f16_e32 v18, v14
	v_cvt_f32_f16_sdwa v19, v14 dst_sel:DWORD dst_unused:UNUSED_PAD src0_sel:WORD_1
	v_cvt_f32_f16_e32 v14, v15
	v_cvt_f32_f16_sdwa v15, v15 dst_sel:DWORD dst_unused:UNUSED_PAD src0_sel:WORD_1
	v_pk_fma_f32 v[10:11], v[10:11], v[34:35], v[12:13]
	v_pk_fma_f32 v[8:9], v[8:9], v[32:33], v[16:17]
	v_pk_fma_f32 v[4:5], v[4:5], v[28:29], v[18:19]
	v_pk_fma_f32 v[6:7], v[6:7], v[30:31], v[14:15]
	s_nop 0
	v_cvt_pk_f16_f32 v7, v6, v7
	v_cvt_pk_f16_f32 v6, v4, v5
	v_cvt_pk_f16_f32 v5, v10, v11
	v_cvt_pk_f16_f32 v4, v8, v9
	global_store_dwordx4 v[20:21], v[4:7], off offset:256
	s_cbranch_vccz .LBB0_653
	s_waitcnt vmcnt(0)
	v_readlane_b32 s48, v251, 13
	s_cmpk_gt_u32 s25, 0xff
	v_readlane_b32 s49, v251, 14
	s_cbranch_scc1 .LBB0_664
	s_barrier

; #define PG8_STAGE(bufoff, gbase, voff) do { _Pragma("unroll") for (int _i = 0; _i < 2; ++_i) \
;         __builtin_amdgcn_global_load_lds((const unsigned*)((const char*)(gbase) + (voff)[_i]), (LAS unsigned*)(lds + (bufoff) + ldsw + _i * 8192), 16, 0, 0); } while (0)
; #define PG8_LDA(dst, b, h) do { _Pragma("unroll") for (int m = 0; m < 4; ++m) _Pragma("unroll") for (int k = 0; k < 2; ++k) dst[m][k] = *(const LAS h8*)(lds + PG8_SA(b, h) + aoff + m * 2048 + k * 1024); } while (0)
; #define PG8_LDB(dst, b, h) do { _Pragma("unroll") for (int n = 0; n < 2; ++n) _Pragma("unroll") for (int k = 0; k < 2; ++k) dst[n][k] = *(const LAS h8*)(lds + PG8_SB(b, h) + boff + n * 2048 + k * 1024); } while (0)
; #define PG8_WAIT_L(n) asm volatile("s_waitcnt lgkmcnt(" #n ")" ::: "memory")
; #define PG8_BAR __builtin_amdgcn_s_barrier()
; #define PG8_SCHED __builtin_amdgcn_sched_barrier(0)
; template <class Epi>
; __device__ __forceinline__ void gemm_phase(LAS unsigned char* lds, const Gemm g, const StaticOrder& S, const Epi& E, const int tid) {
;     ...
;         const bool has_next = S.next(ui + 1, nxt);
;         const char* nA = has_next ? (const char*)g.A + (size_t)nxt.pm * tstep : cA; const char* nB = has_next ? (const char*)g.Bt + (size_t)nxt.pn * tstep : cB;
;         for (int t = 0; t < nt; t += 2) {
;             const bool last = (t == nt - 2);
;             const char* a1 = cA + (size_t)(t + 1) * kstep;
;             const char* a2 = last ? nA : cA + (size_t)(t + 2) * kstep; const char* b2 = last ? nB : cB + (size_t)(t + 2) * kstep;
;             const char* a3 = a2 + kstep; const char* b3 = b2 + kstep;
;             if constexpr (Epi::HAS_MID) { if (t == (nt >> 1)) E.mid(acc, cur, wr, wc, fr, fq); }
;             PG8_LDB(B0, 0, 0); PG8_SCHED; PG8_LDA(At, 0, 0); PG8_STAGE(PG8_SA(1, 1), a1 + hstep, voffA);
;             PG8_WAIT_L(8); PG8_BAR; PG8_WAIT_L(0); PG8_MMA(0, 0, At, B0); PG8_BAR; PG8_SCHED;
;             PG8_LDB(B1, 0, 1); PG8_STAGE(PG8_SB(0, 0), b2, voffB);
;             PG8_BAR; PG8_WAIT_L(0); PG8_MMA(0, 1, At, B1); PG8_BAR;
;             PG8_LDA(At, 0, 1); PG8_STAGE(PG8_SA(0, 0), a2, voffA);
;             PG8_BAR; PG8_WAIT_L(0); PG8_MMA(1, 0, At, B0); PG8_BAR; PG8_SCHED;
.LBB0_678:
	s_add_u32 s14, s12, 0xfff80080
	s_addc_u32 s15, s13, -1
	s_add_i32 s55, 0, 0x10000
	v_add_u32_e32 v88, s55, v176
	ds_read_b128 v[68:71], v88
	ds_read_b128 v[72:75], v88 offset:1024
	ds_read_b128 v[84:87], v88 offset:2048
	ds_read_b128 v[88:91], v88 offset:3072
	s_cmp_eq_u32 s54, 28
	s_cselect_b32 s19, s7, s15
	s_cselect_b32 s18, s50, s14
	s_cselect_b32 s15, s1, s53
	s_cselect_b32 s14, s51, s52
	s_add_i32 m0, s39, 0xc000
	ds_read_b128 v[170:173], v177
	ds_read_b128 v[190:193], v177 offset:1024
	ds_read_b128 v[194:197], v177 offset:2048
	ds_read_b128 v[198:201], v177 offset:3072
	ds_read_b128 v[202:205], v177 offset:4096
	ds_read_b128 v[206:209], v177 offset:5120
	ds_read_b128 v[210:213], v177 offset:6144
	ds_read_b128 v[214:217], v177 offset:7168
	global_load_lds_dwordx4 v166, s[12:13]
	v_lshl_add_u64 v[174:175], s[12:13], 0, v[168:169]
	s_add_i32 m0, s39, 0xe000
	s_nop 0
	global_load_lds_dwordx4 v[174:175], off
	s_waitcnt lgkmcnt(8)
	s_barrier
	s_waitcnt lgkmcnt(0)
	s_waitcnt lgkmcnt(0)
	v_mfma_f32_16x16x32_bf16 v[144:147], v[68:71], v[170:173], v[144:147]
	v_mfma_f32_16x16x32_bf16 v[140:143], v[84:87], v[170:173], v[140:143]
	v_mfma_f32_16x16x32_bf16 v[128:131], v[68:71], v[194:197], v[128:131]
	v_mfma_f32_16x16x32_bf16 v[124:127], v[84:87], v[194:197], v[124:127]
	v_mfma_f32_16x16x32_bf16 v[112:115], v[68:71], v[202:205], v[112:115]
	v_mfma_f32_16x16x32_bf16 v[108:111], v[84:87], v[202:205], v[108:111]
	v_mfma_f32_16x16x32_bf16 v[96:99], v[68:71], v[210:213], v[96:99]
	v_mfma_f32_16x16x32_bf16 v[92:95], v[84:87], v[210:213], v[92:95]
	v_mfma_f32_16x16x32_bf16 v[144:147], v[72:75], v[190:193], v[144:147]
	v_mfma_f32_16x16x32_bf16 v[140:143], v[88:91], v[190:193], v[140:143]
	v_mfma_f32_16x16x32_bf16 v[128:131], v[72:75], v[198:201], v[128:131]
	v_mfma_f32_16x16x32_bf16 v[124:127], v[88:91], v[198:201], v[124:127]
	v_mfma_f32_16x16x32_bf16 v[112:115], v[72:75], v[206:209], v[112:115]
	v_mfma_f32_16x16x32_bf16 v[108:111], v[88:91], v[206:209], v[108:111]
	v_mfma_f32_16x16x32_bf16 v[96:99], v[72:75], v[214:217], v[96:99]
	v_mfma_f32_16x16x32_bf16 v[92:95], v[88:91], v[214:217], v[92:95]
	s_barrier
	s_add_i32 s58, 0, 0x14000
	v_add_u32_e32 v174, s58, v176
	s_add_i32 s55, s55, s38
	ds_read_b128 v[218:221], v174
	ds_read_b128 v[222:225], v174 offset:1024
	ds_read_b128 v[226:229], v174 offset:2048
	ds_read_b128 v[230:233], v174 offset:3072
	v_lshl_add_u64 v[174:175], s[14:15], 0, v[2:3]
	s_mov_b32 m0, s55
	v_lshl_add_u64 v[234:235], s[14:15], 0, v[0:1]
	global_load_lds_dwordx4 v[174:175], off
	s_add_i32 m0, s55, 0x2000
	s_nop 0
	global_load_lds_dwordx4 v[234:235], off
	s_barrier
	s_waitcnt lgkmcnt(0)
	s_waitcnt lgkmcnt(0)
	v_mfma_f32_16x16x32_bf16 v[136:139], v[218:221], v[170:173], v[136:139]
	v_mfma_f32_16x16x32_bf16 v[132:135], v[226:229], v[170:173], v[132:135]
	v_mfma_f32_16x16x32_bf16 v[120:123], v[218:221], v[194:197], v[120:123]
	v_mfma_f32_16x16x32_bf16 v[116:119], v[226:229], v[194:197], v[116:119]
	v_mfma_f32_16x16x32_bf16 v[104:107], v[218:221], v[202:205], v[104:107]
	v_mfma_f32_16x16x32_bf16 v[100:103], v[226:229], v[202:205], v[100:103]
	v_mfma_f32_16x16x32_bf16 v[80:83], v[218:221], v[210:213], v[80:83]
	v_mfma_f32_16x16x32_bf16 v[76:79], v[226:229], v[210:213], v[76:79]
	v_mfma_f32_16x16x32_bf16 v[136:139], v[222:225], v[190:193], v[136:139]
	v_mfma_f32_16x16x32_bf16 v[132:135], v[230:233], v[190:193], v[132:135]
	v_mfma_f32_16x16x32_bf16 v[120:123], v[222:225], v[198:201], v[120:123]
	v_mfma_f32_16x16x32_bf16 v[116:119], v[230:233], v[198:201], v[116:119]
	v_mfma_f32_16x16x32_bf16 v[104:107], v[222:225], v[206:209], v[104:107]
	v_mfma_f32_16x16x32_bf16 v[100:103], v[230:233], v[206:209], v[100:103]
	v_mfma_f32_16x16x32_bf16 v[80:83], v[222:225], v[214:217], v[80:83]
	v_mfma_f32_16x16x32_bf16 v[76:79], v[230:233], v[214:217], v[76:79]
	s_mov_b32 m0, s39
	v_lshl_add_u64 v[236:237], s[18:19], 0, v[164:165]
	s_barrier
	ds_read_b128 v[170:173], v177 offset:16384
	ds_read_b128 v[190:193], v177 offset:17408
	ds_read_b128 v[194:197], v177 offset:18432
	ds_read_b128 v[198:201], v177 offset:19456
	ds_read_b128 v[202:205], v177 offset:20480
	ds_read_b128 v[206:209], v177 offset:21504
	ds_read_b128 v[210:213], v177 offset:22528
	ds_read_b128 v[214:217], v177 offset:23552
	global_load_lds_dwordx4 v[236:237], off
	v_lshl_add_u64 v[238:239], s[18:19], 0, v[162:163]
	s_mov_b32 m0, s40
	s_nop 0
	global_load_lds_dwordx4 v[238:239], off
	s_barrier
	s_waitcnt lgkmcnt(0)
	s_waitcnt lgkmcnt(0)
	v_mfma_f32_16x16x32_bf16 v[64:67], v[68:71], v[170:173], v[64:67]
	v_mfma_f32_16x16x32_bf16 v[60:63], v[84:87], v[170:173], v[60:63]
	v_mfma_f32_16x16x32_bf16 v[48:51], v[68:71], v[194:197], v[48:51]
	v_mfma_f32_16x16x32_bf16 v[44:47], v[84:87], v[194:197], v[44:47]
	v_mfma_f32_16x16x32_bf16 v[32:35], v[68:71], v[202:205], v[32:35]
	v_mfma_f32_16x16x32_bf16 v[28:31], v[84:87], v[202:205], v[28:31]
	v_mfma_f32_16x16x32_bf16 v[16:19], v[68:71], v[210:213], v[16:19]
	v_mfma_f32_16x16x32_bf16 v[12:15], v[84:87], v[210:213], v[12:15]
	v_mfma_f32_16x16x32_bf16 v[64:67], v[72:75], v[190:193], v[64:67]
	v_mfma_f32_16x16x32_bf16 v[60:63], v[88:91], v[190:193], v[60:63]
	v_mfma_f32_16x16x32_bf16 v[48:51], v[72:75], v[198:201], v[48:51]
	v_mfma_f32_16x16x32_bf16 v[44:47], v[88:91], v[198:201], v[44:47]
	v_mfma_f32_16x16x32_bf16 v[32:35], v[72:75], v[206:209], v[32:35]
	v_mfma_f32_16x16x32_bf16 v[28:31], v[88:91], v[206:209], v[28:31]
	v_mfma_f32_16x16x32_bf16 v[16:19], v[72:75], v[214:217], v[16:19]
	v_mfma_f32_16x16x32_bf16 v[12:15], v[88:91], v[214:217], v[12:15]
	s_barrier
; #define PG8_STAGE(bufoff, gbase, voff) do { _Pragma("unroll") for (int _i = 0; _i < 2; ++_i) \
;         __builtin_amdgcn_global_load_lds((const unsigned*)((const char*)(gbase) + (voff)[_i]), (LAS unsigned*)(lds + (bufoff) + ldsw + _i * 8192), 16, 0, 0); } while (0)
; #define PG8_LDA(dst, b, h) do { _Pragma("unroll") for (int m = 0; m < 4; ++m) _Pragma("unroll") for (int k = 0; k < 2; ++k) dst[m][k] = *(const LAS h8*)(lds + PG8_SA(b, h) + aoff + m * 2048 + k * 1024); } while (0)
; #define PG8_LDB(dst, b, h) do { _Pragma("unroll") for (int n = 0; n < 2; ++n) _Pragma("unroll") for (int k = 0; k < 2; ++k) dst[n][k] = *(const LAS h8*)(lds + PG8_SB(b, h) + boff + n * 2048 + k * 1024); } while (0)
; #define PG8_WAIT_V(n) asm volatile("s_waitcnt vmcnt(" #n ")" ::: "memory")
; #define PG8_WAIT_L(n) asm volatile("s_waitcnt lgkmcnt(" #n ")" ::: "memory")
; #define PG8_BAR __builtin_amdgcn_s_barrier()
; #define PG8_SCHED __builtin_amdgcn_sched_barrier(0)
; template <class Epi>
; __device__ __forceinline__ void gemm_phase(LAS unsigned char* lds, const Gemm g, const StaticOrder& S, const Epi& E, const int tid) {
;     ...
;             PG8_STAGE(PG8_SB(0, 1), b2 + hstepB, voffB);
;             PG8_WAIT_V(6); PG8_BAR; PG8_MMA(1, 1, At, B1); PG8_BAR;
;             PG8_LDB(B0, 1, 0); PG8_SCHED; PG8_LDA(At, 1, 0); PG8_STAGE(PG8_SA(0, 1), a2 + hstep, voffA);
;             PG8_WAIT_L(8); PG8_BAR; PG8_WAIT_L(0); PG8_MMA(0, 0, At, B0); PG8_BAR; PG8_SCHED;
;             PG8_LDB(B1, 1, 1); PG8_STAGE(PG8_SB(1, 0), b3, voffB);
;             PG8_BAR; PG8_WAIT_L(0); PG8_MMA(0, 1, At, B1); PG8_BAR;
;             PG8_LDA(At, 1, 1); PG8_STAGE(PG8_SA(1, 0), a3, voffA);
	s_add_u32 s56, s14, 0x80000
	s_addc_u32 s57, s15, 0
	s_add_i32 s55, s58, s38
	s_mov_b32 m0, s55
	s_nop 0
	global_load_lds_dwordx4 v2, s[56:57]
	s_add_i32 m0, s55, 0x2000
	s_nop 0
	global_load_lds_dwordx4 v0, s[56:57]
	s_waitcnt vmcnt(6)
	s_barrier
	v_mfma_f32_16x16x32_bf16 v[56:59], v[218:221], v[170:173], v[56:59]
	v_mfma_f32_16x16x32_bf16 v[52:55], v[226:229], v[170:173], v[52:55]
	v_mfma_f32_16x16x32_bf16 v[40:43], v[218:221], v[194:197], v[40:43]
	v_mfma_f32_16x16x32_bf16 v[36:39], v[226:229], v[194:197], v[36:39]
	v_mfma_f32_16x16x32_bf16 v[24:27], v[218:221], v[202:205], v[24:27]
	v_mfma_f32_16x16x32_bf16 v[20:23], v[226:229], v[202:205], v[20:23]
	v_mfma_f32_16x16x32_bf16 v[8:11], v[218:221], v[210:213], v[8:11]
	v_mfma_f32_16x16x32_bf16 v[4:7], v[226:229], v[210:213], v[4:7]
	v_mfma_f32_16x16x32_bf16 v[56:59], v[222:225], v[190:193], v[56:59]
	v_mfma_f32_16x16x32_bf16 v[52:55], v[230:233], v[190:193], v[52:55]
	v_mfma_f32_16x16x32_bf16 v[40:43], v[222:225], v[198:201], v[40:43]
	v_mfma_f32_16x16x32_bf16 v[36:39], v[230:233], v[198:201], v[36:39]
	v_mfma_f32_16x16x32_bf16 v[24:27], v[222:225], v[206:209], v[24:27]
	v_mfma_f32_16x16x32_bf16 v[20:23], v[230:233], v[206:209], v[20:23]
	v_mfma_f32_16x16x32_bf16 v[8:11], v[222:225], v[214:217], v[8:11]
	v_mfma_f32_16x16x32_bf16 v[4:7], v[230:233], v[214:217], v[4:7]
	s_add_i32 s55, 0, 0x18000
	v_add_u32_e32 v88, s55, v176
	s_barrier
	ds_read_b128 v[68:71], v88
	ds_read_b128 v[72:75], v88 offset:1024
	ds_read_b128 v[84:87], v88 offset:2048
	ds_read_b128 v[88:91], v88 offset:3072
	s_add_u32 s18, s18, 0x80000
	s_addc_u32 s19, s19, 0
	s_mov_b32 m0, s41
	ds_read_b128 v[170:173], v177 offset:32768
	ds_read_b128 v[190:193], v177 offset:33792
	ds_read_b128 v[194:197], v177 offset:34816
	ds_read_b128 v[198:201], v177 offset:35840
	ds_read_b128 v[202:205], v177 offset:36864
	ds_read_b128 v[206:209], v177 offset:37888
	ds_read_b128 v[210:213], v177 offset:38912
	ds_read_b128 v[214:217], v177 offset:39936
	global_load_lds_dwordx4 v164, s[18:19]
	s_mov_b32 m0, s42
	s_nop 0
	global_load_lds_dwordx4 v162, s[18:19]
	s_waitcnt lgkmcnt(8)
	s_barrier
	s_waitcnt lgkmcnt(0)
	s_waitcnt lgkmcnt(0)
	v_mfma_f32_16x16x32_bf16 v[144:147], v[68:71], v[170:173], v[144:147]
	v_mfma_f32_16x16x32_bf16 v[140:143], v[84:87], v[170:173], v[140:143]
	v_mfma_f32_16x16x32_bf16 v[128:131], v[68:71], v[194:197], v[128:131]
	v_mfma_f32_16x16x32_bf16 v[124:127], v[84:87], v[194:197], v[124:127]
	v_mfma_f32_16x16x32_bf16 v[112:115], v[68:71], v[202:205], v[112:115]
	v_mfma_f32_16x16x32_bf16 v[108:111], v[84:87], v[202:205], v[108:111]
	v_mfma_f32_16x16x32_bf16 v[96:99], v[68:71], v[210:213], v[96:99]
	v_mfma_f32_16x16x32_bf16 v[92:95], v[84:87], v[210:213], v[92:95]
	v_mfma_f32_16x16x32_bf16 v[144:147], v[72:75], v[190:193], v[144:147]
	v_mfma_f32_16x16x32_bf16 v[140:143], v[88:91], v[190:193], v[140:143]
	v_mfma_f32_16x16x32_bf16 v[128:131], v[72:75], v[198:201], v[128:131]
	v_mfma_f32_16x16x32_bf16 v[124:127], v[88:91], v[198:201], v[124:127]
	v_mfma_f32_16x16x32_bf16 v[112:115], v[72:75], v[206:209], v[112:115]
	v_mfma_f32_16x16x32_bf16 v[108:111], v[88:91], v[206:209], v[108:111]
	v_mfma_f32_16x16x32_bf16 v[96:99], v[72:75], v[214:217], v[96:99]
	v_mfma_f32_16x16x32_bf16 v[92:95], v[88:91], v[214:217], v[92:95]
	s_barrier
	s_add_i32 s18, 0, 0x1c000
	s_add_i32 s19, s55, s38
	v_add_u32_e32 v178, s18, v176
	v_lshl_add_u64 v[174:175], v[174:175], 0, s[30:31]
	s_mov_b32 m0, s19
	ds_read_b128 v[218:221], v178
	ds_read_b128 v[222:225], v178 offset:1024
	ds_read_b128 v[226:229], v178 offset:2048
	ds_read_b128 v[230:233], v178 offset:3072
	global_load_lds_dwordx4 v[174:175], off
	v_lshl_add_u64 v[174:175], v[234:235], 0, s[30:31]
	s_add_i32 m0, s19, 0x2000
	s_nop 0
	global_load_lds_dwordx4 v[174:175], off
	s_barrier
	s_waitcnt lgkmcnt(0)
	s_waitcnt lgkmcnt(0)
	v_mfma_f32_16x16x32_bf16 v[136:139], v[218:221], v[170:173], v[136:139]
	v_mfma_f32_16x16x32_bf16 v[132:135], v[226:229], v[170:173], v[132:135]
	v_mfma_f32_16x16x32_bf16 v[120:123], v[218:221], v[194:197], v[120:123]
	v_mfma_f32_16x16x32_bf16 v[116:119], v[226:229], v[194:197], v[116:119]
	v_mfma_f32_16x16x32_bf16 v[104:107], v[218:221], v[202:205], v[104:107]
	v_mfma_f32_16x16x32_bf16 v[100:103], v[226:229], v[202:205], v[100:103]
	v_mfma_f32_16x16x32_bf16 v[80:83], v[218:221], v[210:213], v[80:83]
	v_mfma_f32_16x16x32_bf16 v[76:79], v[226:229], v[210:213], v[76:79]
	v_mfma_f32_16x16x32_bf16 v[136:139], v[222:225], v[190:193], v[136:139]
	v_mfma_f32_16x16x32_bf16 v[132:135], v[230:233], v[190:193], v[132:135]
	v_mfma_f32_16x16x32_bf16 v[120:123], v[222:225], v[198:201], v[120:123]
	v_mfma_f32_16x16x32_bf16 v[116:119], v[230:233], v[198:201], v[116:119]
	v_mfma_f32_16x16x32_bf16 v[104:107], v[222:225], v[206:209], v[104:107]
	v_mfma_f32_16x16x32_bf16 v[100:103], v[230:233], v[206:209], v[100:103]
	v_mfma_f32_16x16x32_bf16 v[80:83], v[222:225], v[214:217], v[80:83]
	v_mfma_f32_16x16x32_bf16 v[76:79], v[230:233], v[214:217], v[76:79]
	s_mov_b32 m0, s43
	v_lshl_add_u64 v[174:175], v[236:237], 0, s[30:31]
	s_barrier
	ds_read_b128 v[170:173], v177 offset:49152
	ds_read_b128 v[190:193], v177 offset:50176
	ds_read_b128 v[194:197], v177 offset:51200
	ds_read_b128 v[198:201], v177 offset:52224
	ds_read_b128 v[202:205], v177 offset:53248
	ds_read_b128 v[206:209], v177 offset:54272
	ds_read_b128 v[210:213], v177 offset:55296
	ds_read_b128 v[214:217], v177 offset:56320
	global_load_lds_dwordx4 v[174:175], off
	v_lshl_add_u64 v[174:175], v[238:239], 0, s[30:31]
	s_mov_b32 m0, s46
	s_nop 0
	global_load_lds_dwordx4 v[174:175], off
	s_barrier
; #define PG8_STAGE(bufoff, gbase, voff) do { _Pragma("unroll") for (int _i = 0; _i < 2; ++_i) \
;         __builtin_amdgcn_global_load_lds((const unsigned*)((const char*)(gbase) + (voff)[_i]), (LAS unsigned*)(lds + (bufoff) + ldsw + _i * 8192), 16, 0, 0); } while (0)
; #define PG8_WAIT_V(n) asm volatile("s_waitcnt vmcnt(" #n ")" ::: "memory")
; #define PG8_WAIT_L(n) asm volatile("s_waitcnt lgkmcnt(" #n ")" ::: "memory")
; #define PG8_BAR __builtin_amdgcn_s_barrier()
; template <class Epi>
; __device__ __forceinline__ void gemm_phase(LAS unsigned char* lds, const Gemm g, const StaticOrder& S, const Epi& E, const int tid) {
;     ...
;             PG8_BAR; PG8_WAIT_L(0); PG8_MMA(1, 0, At, B0); PG8_BAR; PG8_SCHED;
;             PG8_STAGE(PG8_SB(1, 1), b3 + hstepB, voffB);
;             PG8_WAIT_V(6); PG8_BAR; PG8_MMA(1, 1, At, B1); PG8_BAR;
;     __device__ __forceinline__ void operator()(const f32x4 (&acc)[2][2][4][2], const pg8::Unit& u, int wr, int wc, int fr, int fq) const {
;         const int row0 = u.pm * 256 + wr * 64 + fr, col0 = u.pn * 256 + wc * 32 + 8 * fq;
;         const float* gp = gate + (size_t)((u.pm * 256) >> 12) * 6144 + col0;
;         f32x4 gv[2][2];
; #pragma unroll
;         for (int bj = 0; bj < 2; ++bj)
; #pragma unroll
;             for (int n = 0; n < 2; ++n) gv[bj][n] = *(const f32x4*)(gp + bj * 128 + 4 * n);
; #pragma unroll
;         for (int ai = 0; ai < 2; ++ai)
; #pragma unroll
;             for (int m = 0; m < 4; ++m) { const size_t ro = (size_t)(row0 + ai * 128 + m * 16) * DM + col0;
; #pragma unroll
;                 for (int bj = 0; bj < 2; ++bj) {
;                     f32x4 x0, x1;
;                     if (XF32) { x0 = *(const f32x4*)(xin + ro + bj * 128); x1 = *(const f32x4*)(xin + ro + bj * 128 + 4); }
;                     else { const h8 xh = *(const h8*)(H + ro + bj * 128); x0 = (f32x4){(float)xh[0], (float)xh[1], (float)xh[2], (float)xh[3]}; x1 = (f32x4){(float)xh[4], (float)xh[5], (float)xh[6], (float)xh[7]}; }
;                     const f32x4 y0 = x0 + gv[bj][0] * acc[ai][bj][m][0], y1 = x1 + gv[bj][1] * acc[ai][bj][m][1];
;                     h8 o; o[0] = (half_t)y0[0]; o[1] = (half_t)y0[1]; o[2] = (half_t)y0[2]; o[3] = (half_t)y0[3]; o[4] = (half_t)y1[0]; o[5] = (half_t)y1[1]; o[6] = (half_t)y1[2]; o[7] = (half_t)y1[3];
;                     *(h8*)(H + ro + bj * 128) = o; } }
	s_waitcnt lgkmcnt(0)
	s_waitcnt lgkmcnt(0)
	v_mfma_f32_16x16x32_bf16 v[64:67], v[68:71], v[170:173], v[64:67]
	v_mfma_f32_16x16x32_bf16 v[60:63], v[84:87], v[170:173], v[60:63]
	v_mfma_f32_16x16x32_bf16 v[48:51], v[68:71], v[194:197], v[48:51]
	v_mfma_f32_16x16x32_bf16 v[44:47], v[84:87], v[194:197], v[44:47]
	v_mfma_f32_16x16x32_bf16 v[32:35], v[68:71], v[202:205], v[32:35]
	v_mfma_f32_16x16x32_bf16 v[28:31], v[84:87], v[202:205], v[28:31]
	v_mfma_f32_16x16x32_bf16 v[16:19], v[68:71], v[210:213], v[16:19]
	v_mfma_f32_16x16x32_bf16 v[12:15], v[84:87], v[210:213], v[12:15]
	v_mfma_f32_16x16x32_bf16 v[64:67], v[72:75], v[190:193], v[64:67]
	v_mfma_f32_16x16x32_bf16 v[60:63], v[88:91], v[190:193], v[60:63]
	v_mfma_f32_16x16x32_bf16 v[48:51], v[72:75], v[198:201], v[48:51]
	v_mfma_f32_16x16x32_bf16 v[44:47], v[88:91], v[198:201], v[44:47]
	v_mfma_f32_16x16x32_bf16 v[32:35], v[72:75], v[206:209], v[32:35]
	v_mfma_f32_16x16x32_bf16 v[28:31], v[88:91], v[206:209], v[28:31]
	v_mfma_f32_16x16x32_bf16 v[16:19], v[72:75], v[214:217], v[16:19]
	v_mfma_f32_16x16x32_bf16 v[12:15], v[88:91], v[214:217], v[12:15]
	s_barrier
	s_add_u32 s14, s14, 0x80080
	s_addc_u32 s15, s15, 0
	s_add_i32 s18, s18, s38
	s_mov_b32 m0, s18
	s_nop 0
	global_load_lds_dwordx4 v2, s[14:15]
	v_lshl_add_u64 v[68:69], s[14:15], 0, v[0:1]
	s_add_i32 m0, s18, 0x2000
	s_nop 0
	global_load_lds_dwordx4 v[68:69], off
	s_waitcnt vmcnt(6)
	s_barrier
	v_mfma_f32_16x16x32_bf16 v[56:59], v[218:221], v[170:173], v[56:59]
	v_mfma_f32_16x16x32_bf16 v[52:55], v[226:229], v[170:173], v[52:55]
	v_mfma_f32_16x16x32_bf16 v[40:43], v[218:221], v[194:197], v[40:43]
	v_mfma_f32_16x16x32_bf16 v[36:39], v[226:229], v[194:197], v[36:39]
	v_mfma_f32_16x16x32_bf16 v[24:27], v[218:221], v[202:205], v[24:27]
	v_mfma_f32_16x16x32_bf16 v[20:23], v[226:229], v[202:205], v[20:23]
	v_mfma_f32_16x16x32_bf16 v[8:11], v[218:221], v[210:213], v[8:11]
	v_mfma_f32_16x16x32_bf16 v[4:7], v[226:229], v[210:213], v[4:7]
	v_mfma_f32_16x16x32_bf16 v[56:59], v[222:225], v[190:193], v[56:59]
	v_mfma_f32_16x16x32_bf16 v[52:55], v[230:233], v[190:193], v[52:55]
	v_mfma_f32_16x16x32_bf16 v[40:43], v[222:225], v[198:201], v[40:43]
	v_mfma_f32_16x16x32_bf16 v[36:39], v[230:233], v[198:201], v[36:39]
	v_mfma_f32_16x16x32_bf16 v[24:27], v[222:225], v[206:209], v[24:27]
	v_mfma_f32_16x16x32_bf16 v[20:23], v[230:233], v[206:209], v[20:23]
	v_mfma_f32_16x16x32_bf16 v[8:11], v[222:225], v[214:217], v[8:11]
	v_mfma_f32_16x16x32_bf16 v[4:7], v[230:233], v[214:217], v[4:7]
	s_add_i32 s54, s54, 2
	s_add_u32 s12, s12, 0x100
	s_addc_u32 s13, s13, 0
	s_add_u32 s52, s52, 0x100
	s_addc_u32 s53, s53, 0
	s_cmp_gt_u32 s54, 29
	s_barrier
	s_cbranch_scc0 .LBB0_678
	s_ashr_i32 s1, s48, 4
	v_lshl_add_u32 v174, s48, 8, v179
	v_lshl_or_b32 v172, s49, 8, v157
	s_mul_hi_i32 s7, s1, 0x6000
	s_mulk_i32 s1, 0x6000
	v_ashrrev_i32_e32 v175, 31, v174
	s_add_u32 s12, s23, s1
	v_ashrrev_i32_e32 v173, 31, v172
	v_lshlrev_b64 v[170:171], 11, v[174:175]
	s_addc_u32 s13, s24, s7
	v_lshl_add_u64 v[170:171], v[170:171], 0, v[172:173]
	v_lshl_add_u64 v[72:73], v[172:173], 2, s[12:13]
	v_lshl_add_u64 v[198:199], v[170:171], 2, s[80:81]
	global_load_dwordx4 v[84:87], v[72:73], off offset:16
	global_load_dwordx4 v[88:91], v[72:73], off
	global_load_dwordx4 v[68:71], v[72:73], off offset:528
	s_nop 0
	global_load_dwordx4 v[72:75], v[72:73], off offset:512
	s_mov_b64 s[98:99], 0x0
	v_lshl_add_u64 v[248:249], v[198:199], 0, s[98:99]
	global_load_dwordx4 v[200:203], v[248:249], off offset:16
	global_load_dwordx4 v[204:207], v[248:249], off
	s_mov_b64 s[98:99], 0x0
	v_lshl_add_u64 v[248:249], v[198:199], 0, s[98:99]
	global_load_dwordx4 v[208:211], v[248:249], off offset:528
	global_load_dwordx4 v[212:215], v[248:249], off offset:512
	s_mov_b64 s[98:99], 0x20000
	v_lshl_add_u64 v[248:249], v[198:199], 0, s[98:99]
	global_load_dwordx4 v[216:219], v[248:249], off offset:16
	global_load_dwordx4 v[220:223], v[248:249], off
	s_mov_b64 s[98:99], 0x20000
	v_lshl_add_u64 v[248:249], v[198:199], 0, s[98:99]
	global_load_dwordx4 v[224:227], v[248:249], off offset:528
	global_load_dwordx4 v[228:231], v[248:249], off offset:512
	s_mov_b64 s[98:99], 0x40000
	v_lshl_add_u64 v[248:249], v[198:199], 0, s[98:99]
	global_load_dwordx4 v[232:235], v[248:249], off offset:16
	global_load_dwordx4 v[236:239], v[248:249], off
	s_mov_b64 s[98:99], 0x40000
	v_lshl_add_u64 v[248:249], v[198:199], 0, s[98:99]
	global_load_dwordx4 v[240:243], v[248:249], off offset:528
	global_load_dwordx4 v[244:247], v[248:249], off offset:512
	s_nop 0
	s_nop 1
	s_waitcnt vmcnt(10)
	v_mov_b32_e32 v190, v200
	v_mov_b32_e32 v191, v201
	v_mov_b32_e32 v192, v202
	v_mov_b32_e32 v193, v203
	s_nop 1
	v_mov_b32_e32 v194, v204
	v_mov_b32_e32 v195, v205
	v_mov_b32_e32 v196, v206
	v_mov_b32_e32 v197, v207
	s_mov_b64 s[98:99], 0x60000
	v_lshl_add_u64 v[248:249], v[198:199], 0, s[98:99]
	global_load_dwordx4 v[200:203], v[248:249], off offset:16
	global_load_dwordx4 v[204:207], v[248:249], off
	s_mov_b64 s[12:13], 0x40000
	s_and_b64 vcc, exec, s[4:5]
	s_mov_b32 s49, s0
	s_mov_b32 s48, s6
	s_mov_b64 s[14:15], s[10:11]
	s_nop 0
	v_pk_fma_f32 v[142:143], v[142:143], v[86:87], v[192:193]
	v_pk_fma_f32 v[146:147], v[146:147], v[90:91], v[196:197]
	v_pk_fma_f32 v[144:145], v[144:145], v[88:89], v[194:195]
	v_pk_fma_f32 v[190:191], v[140:141], v[84:85], v[190:191]
	v_cvt_pk_f16_f32 v143, v142, v143
	v_cvt_pk_f16_f32 v141, v146, v147
	v_cvt_pk_f16_f32 v142, v190, v191
	v_cvt_pk_f16_f32 v140, v144, v145
	v_lshl_add_u64 v[190:191], v[170:171], 1, s[16:17]
	global_store_dwordx4 v[190:191], v[140:143], off
	s_nop 1
	s_waitcnt vmcnt(10)
;     __device__ __forceinline__ void operator()(const f32x4 (&acc)[2][2][4][2], const pg8::Unit& u, int wr, int wc, int fr, int fq) const {
;     ...
;         for (int ai = 0; ai < 2; ++ai)
; #pragma unroll
;             for (int m = 0; m < 4; ++m) { const size_t ro = (size_t)(row0 + ai * 128 + m * 16) * DM + col0;
; #pragma unroll
;                 for (int bj = 0; bj < 2; ++bj) {
;                     f32x4 x0, x1;
;                     if (XF32) { x0 = *(const f32x4*)(xin + ro + bj * 128); x1 = *(const f32x4*)(xin + ro + bj * 128 + 4); }
;                     else { const h8 xh = *(const h8*)(H + ro + bj * 128); x0 = (f32x4){(float)xh[0], (float)xh[1], (float)xh[2], (float)xh[3]}; x1 = (f32x4){(float)xh[4], (float)xh[5], (float)xh[6], (float)xh[7]}; }
;                     const f32x4 y0 = x0 + gv[bj][0] * acc[ai][bj][m][0], y1 = x1 + gv[bj][1] * acc[ai][bj][m][1];
;                     h8 o; o[0] = (half_t)y0[0]; o[1] = (half_t)y0[1]; o[2] = (half_t)y0[2]; o[3] = (half_t)y0[3]; o[4] = (half_t)y1[0]; o[5] = (half_t)y1[1]; o[6] = (half_t)y1[2]; o[7] = (half_t)y1[3];
;                     *(h8*)(H + ro + bj * 128) = o; } }
	v_mov_b32_e32 v140, v208
	v_mov_b32_e32 v141, v209
	v_mov_b32_e32 v142, v210
	v_mov_b32_e32 v143, v211
	s_nop 0
	s_nop 1
	v_mov_b32_e32 v144, v212
	v_mov_b32_e32 v145, v213
	v_mov_b32_e32 v146, v214
	v_mov_b32_e32 v147, v215
	s_mov_b64 s[98:99], 0x60000
	v_lshl_add_u64 v[248:249], v[198:199], 0, s[98:99]
	global_load_dwordx4 v[208:211], v[248:249], off offset:528
	global_load_dwordx4 v[212:215], v[248:249], off offset:512
	s_nop 0
	v_pk_fma_f32 v[134:135], v[134:135], v[70:71], v[142:143]
	v_pk_fma_f32 v[138:139], v[138:139], v[74:75], v[146:147]
	v_pk_fma_f32 v[136:137], v[136:137], v[72:73], v[144:145]
	v_pk_fma_f32 v[140:141], v[132:133], v[68:69], v[140:141]
	v_cvt_pk_f16_f32 v135, v134, v135
	v_cvt_pk_f16_f32 v133, v138, v139
	v_cvt_pk_f16_f32 v134, v140, v141
	v_cvt_pk_f16_f32 v132, v136, v137
	global_store_dwordx4 v[190:191], v[132:135], off offset:256
	s_nop 1
	v_or_b32_e32 v132, 16, v174
	v_ashrrev_i32_e32 v133, 31, v132
	v_lshlrev_b64 v[132:133], 11, v[132:133]
	v_lshl_add_u64 v[140:141], v[132:133], 0, v[172:173]
	v_lshl_add_u64 v[142:143], v[140:141], 2, s[80:81]
	s_nop 1
	s_waitcnt vmcnt(10)
	v_mov_b32_e32 v132, v216
	v_mov_b32_e32 v133, v217
	v_mov_b32_e32 v134, v218
	v_mov_b32_e32 v135, v219
	s_nop 1
	v_mov_b32_e32 v136, v220
	v_mov_b32_e32 v137, v221
	v_mov_b32_e32 v138, v222
	v_mov_b32_e32 v139, v223
	s_mov_b64 s[98:99], 0x100000
	v_lshl_add_u64 v[248:249], v[198:199], 0, s[98:99]
	global_load_dwordx4 v[216:219], v[248:249], off offset:16
	global_load_dwordx4 v[220:223], v[248:249], off
	s_nop 0
	v_pk_fma_f32 v[126:127], v[126:127], v[86:87], v[134:135]
	v_pk_fma_f32 v[130:131], v[130:131], v[90:91], v[138:139]
	v_pk_fma_f32 v[128:129], v[128:129], v[88:89], v[136:137]
	v_pk_fma_f32 v[132:133], v[124:125], v[84:85], v[132:133]
	v_cvt_pk_f16_f32 v127, v126, v127
	v_cvt_pk_f16_f32 v125, v130, v131
	v_cvt_pk_f16_f32 v126, v132, v133
	v_cvt_pk_f16_f32 v124, v128, v129
	v_lshl_add_u64 v[132:133], v[140:141], 1, s[16:17]
	global_store_dwordx4 v[132:133], v[124:127], off
	s_nop 1
	s_waitcnt vmcnt(10)
	v_mov_b32_e32 v124, v224
	v_mov_b32_e32 v125, v225
	v_mov_b32_e32 v126, v226
	v_mov_b32_e32 v127, v227
	s_nop 0
	s_nop 1
	v_mov_b32_e32 v128, v228
	v_mov_b32_e32 v129, v229
	v_mov_b32_e32 v130, v230
	v_mov_b32_e32 v131, v231
	s_mov_b64 s[98:99], 0x100000
	v_lshl_add_u64 v[248:249], v[198:199], 0, s[98:99]
	global_load_dwordx4 v[224:227], v[248:249], off offset:528
	global_load_dwordx4 v[228:231], v[248:249], off offset:512
	s_nop 0
	v_pk_fma_f32 v[118:119], v[118:119], v[70:71], v[126:127]
	v_pk_fma_f32 v[122:123], v[122:123], v[74:75], v[130:131]
	v_pk_fma_f32 v[120:121], v[120:121], v[72:73], v[128:129]
	v_pk_fma_f32 v[124:125], v[116:117], v[68:69], v[124:125]
	v_cvt_pk_f16_f32 v119, v118, v119
	v_cvt_pk_f16_f32 v117, v122, v123
	v_cvt_pk_f16_f32 v118, v124, v125
	v_cvt_pk_f16_f32 v116, v120, v121
	global_store_dwordx4 v[132:133], v[116:119], off offset:256
	s_nop 1
	v_or_b32_e32 v116, 32, v174
	v_ashrrev_i32_e32 v117, 31, v116
	v_lshlrev_b64 v[116:117], 11, v[116:117]
	v_lshl_add_u64 v[124:125], v[116:117], 0, v[172:173]
	v_lshl_add_u64 v[126:127], v[124:125], 2, s[80:81]
	s_nop 1
	s_waitcnt vmcnt(10)
	v_mov_b32_e32 v116, v232
	v_mov_b32_e32 v117, v233
	v_mov_b32_e32 v118, v234
	v_mov_b32_e32 v119, v235
	s_nop 1
	v_mov_b32_e32 v120, v236
	v_mov_b32_e32 v121, v237
	v_mov_b32_e32 v122, v238
	v_mov_b32_e32 v123, v239
	s_mov_b64 s[98:99], 0x120000
	v_lshl_add_u64 v[248:249], v[198:199], 0, s[98:99]
	global_load_dwordx4 v[232:235], v[248:249], off offset:16
	global_load_dwordx4 v[236:239], v[248:249], off
	s_nop 0
	v_pk_fma_f32 v[110:111], v[110:111], v[86:87], v[118:119]
	v_pk_fma_f32 v[114:115], v[114:115], v[90:91], v[122:123]
	v_pk_fma_f32 v[112:113], v[112:113], v[88:89], v[120:121]
	v_pk_fma_f32 v[116:117], v[108:109], v[84:85], v[116:117]
	v_cvt_pk_f16_f32 v111, v110, v111
	v_cvt_pk_f16_f32 v109, v114, v115
	v_cvt_pk_f16_f32 v110, v116, v117
	v_cvt_pk_f16_f32 v108, v112, v113
	v_lshl_add_u64 v[116:117], v[124:125], 1, s[16:17]
	global_store_dwordx4 v[116:117], v[108:111], off
	s_nop 1
	s_waitcnt vmcnt(10)
	v_mov_b32_e32 v108, v240
	v_mov_b32_e32 v109, v241
	v_mov_b32_e32 v110, v242
	v_mov_b32_e32 v111, v243
	s_nop 0
	s_nop 1
	v_mov_b32_e32 v112, v244
	v_mov_b32_e32 v113, v245
	v_mov_b32_e32 v114, v246
	v_mov_b32_e32 v115, v247
	s_mov_b64 s[98:99], 0x120000
	v_lshl_add_u64 v[248:249], v[198:199], 0, s[98:99]
	global_load_dwordx4 v[240:243], v[248:249], off offset:528
	global_load_dwordx4 v[244:247], v[248:249], off offset:512
	s_nop 0
	v_pk_fma_f32 v[102:103], v[102:103], v[70:71], v[110:111]
	v_pk_fma_f32 v[106:107], v[106:107], v[74:75], v[114:115]
	v_pk_fma_f32 v[104:105], v[104:105], v[72:73], v[112:113]
	v_pk_fma_f32 v[108:109], v[100:101], v[68:69], v[108:109]
	v_cvt_pk_f16_f32 v103, v102, v103
	v_cvt_pk_f16_f32 v101, v106, v107
	v_cvt_pk_f16_f32 v102, v108, v109
	v_cvt_pk_f16_f32 v100, v104, v105
	global_store_dwordx4 v[116:117], v[100:103], off offset:256
	s_nop 1
	v_or_b32_e32 v100, 48, v174
	v_ashrrev_i32_e32 v101, 31, v100
	v_lshlrev_b64 v[100:101], 11, v[100:101]
	v_lshl_add_u64 v[108:109], v[100:101], 0, v[172:173]
	v_lshl_add_u64 v[110:111], v[108:109], 2, s[80:81]
	s_nop 1
	s_waitcnt vmcnt(10)
;     __device__ __forceinline__ void operator()(const f32x4 (&acc)[2][2][4][2], const pg8::Unit& u, int wr, int wc, int fr, int fq) const {
;     ...
;         for (int ai = 0; ai < 2; ++ai)
; #pragma unroll
;             for (int m = 0; m < 4; ++m) { const size_t ro = (size_t)(row0 + ai * 128 + m * 16) * DM + col0;
; #pragma unroll
;                 for (int bj = 0; bj < 2; ++bj) {
;                     f32x4 x0, x1;
;                     if (XF32) { x0 = *(const f32x4*)(xin + ro + bj * 128); x1 = *(const f32x4*)(xin + ro + bj * 128 + 4); }
;                     else { const h8 xh = *(const h8*)(H + ro + bj * 128); x0 = (f32x4){(float)xh[0], (float)xh[1], (float)xh[2], (float)xh[3]}; x1 = (f32x4){(float)xh[4], (float)xh[5], (float)xh[6], (float)xh[7]}; }
;                     const f32x4 y0 = x0 + gv[bj][0] * acc[ai][bj][m][0], y1 = x1 + gv[bj][1] * acc[ai][bj][m][1];
;                     h8 o; o[0] = (half_t)y0[0]; o[1] = (half_t)y0[1]; o[2] = (half_t)y0[2]; o[3] = (half_t)y0[3]; o[4] = (half_t)y1[0]; o[5] = (half_t)y1[1]; o[6] = (half_t)y1[2]; o[7] = (half_t)y1[3];
;                     *(h8*)(H + ro + bj * 128) = o; } }
	v_mov_b32_e32 v100, v200
	v_mov_b32_e32 v101, v201
	v_mov_b32_e32 v102, v202
	v_mov_b32_e32 v103, v203
	s_nop 1
	v_mov_b32_e32 v104, v204
	v_mov_b32_e32 v105, v205
	v_mov_b32_e32 v106, v206
	v_mov_b32_e32 v107, v207
	s_mov_b64 s[98:99], 0x140000
	v_lshl_add_u64 v[248:249], v[198:199], 0, s[98:99]
	global_load_dwordx4 v[200:203], v[248:249], off offset:16
	global_load_dwordx4 v[204:207], v[248:249], off
	s_nop 0
	v_pk_fma_f32 v[94:95], v[94:95], v[86:87], v[102:103]
	v_pk_fma_f32 v[98:99], v[98:99], v[90:91], v[106:107]
	v_pk_fma_f32 v[96:97], v[96:97], v[88:89], v[104:105]
	v_pk_fma_f32 v[100:101], v[92:93], v[84:85], v[100:101]
	v_cvt_pk_f16_f32 v95, v94, v95
	v_cvt_pk_f16_f32 v93, v98, v99
	v_cvt_pk_f16_f32 v94, v100, v101
	v_cvt_pk_f16_f32 v92, v96, v97
	v_lshl_add_u64 v[100:101], v[108:109], 1, s[16:17]
	global_store_dwordx4 v[100:101], v[92:95], off
	s_nop 1
	s_waitcnt vmcnt(10)
	v_mov_b32_e32 v92, v208
	v_mov_b32_e32 v93, v209
	v_mov_b32_e32 v94, v210
	v_mov_b32_e32 v95, v211
	s_nop 0
	s_nop 1
	v_mov_b32_e32 v96, v212
	v_mov_b32_e32 v97, v213
	v_mov_b32_e32 v98, v214
	v_mov_b32_e32 v99, v215
	s_mov_b64 s[98:99], 0x140000
	v_lshl_add_u64 v[248:249], v[198:199], 0, s[98:99]
	global_load_dwordx4 v[208:211], v[248:249], off offset:528
	global_load_dwordx4 v[212:215], v[248:249], off offset:512
	s_nop 0
	v_pk_fma_f32 v[78:79], v[78:79], v[70:71], v[94:95]
	v_pk_fma_f32 v[82:83], v[82:83], v[74:75], v[98:99]
	v_pk_fma_f32 v[80:81], v[80:81], v[72:73], v[96:97]
	v_pk_fma_f32 v[92:93], v[76:77], v[68:69], v[92:93]
	v_cvt_pk_f16_f32 v79, v78, v79
	v_cvt_pk_f16_f32 v77, v82, v83
	v_cvt_pk_f16_f32 v78, v92, v93
	v_cvt_pk_f16_f32 v76, v80, v81
	v_lshl_add_u64 v[92:93], v[170:171], 0, s[12:13]
	global_store_dwordx4 v[100:101], v[76:79], off offset:256
	v_lshl_add_u64 v[94:95], v[92:93], 2, s[80:81]
	s_nop 1
	s_waitcnt vmcnt(10)
	v_mov_b32_e32 v76, v216
	v_mov_b32_e32 v77, v217
	v_mov_b32_e32 v78, v218
	v_mov_b32_e32 v79, v219
	s_nop 1
	v_mov_b32_e32 v80, v220
	v_mov_b32_e32 v81, v221
	v_mov_b32_e32 v82, v222
	v_mov_b32_e32 v83, v223
	s_mov_b64 s[98:99], 0x160000
	v_lshl_add_u64 v[248:249], v[198:199], 0, s[98:99]
	global_load_dwordx4 v[216:219], v[248:249], off offset:16
	global_load_dwordx4 v[220:223], v[248:249], off
	s_mov_b64 s[12:13], 0x48000
	s_nop 0
	v_pk_fma_f32 v[62:63], v[62:63], v[86:87], v[78:79]
	v_pk_fma_f32 v[66:67], v[66:67], v[90:91], v[82:83]
	v_pk_fma_f32 v[64:65], v[64:65], v[88:89], v[80:81]
	v_pk_fma_f32 v[76:77], v[60:61], v[84:85], v[76:77]
	v_cvt_pk_f16_f32 v63, v62, v63
	v_cvt_pk_f16_f32 v61, v66, v67
	v_cvt_pk_f16_f32 v62, v76, v77
	v_cvt_pk_f16_f32 v60, v64, v65
	v_lshl_add_u64 v[76:77], v[92:93], 1, s[16:17]
	global_store_dwordx4 v[76:77], v[60:63], off
	s_nop 1
	s_waitcnt vmcnt(10)
	v_mov_b32_e32 v60, v224
	v_mov_b32_e32 v61, v225
	v_mov_b32_e32 v62, v226
	v_mov_b32_e32 v63, v227
	s_nop 0
	s_nop 1
	v_mov_b32_e32 v64, v228
	v_mov_b32_e32 v65, v229
	v_mov_b32_e32 v66, v230
	v_mov_b32_e32 v67, v231
	s_mov_b64 s[98:99], 0x160000
	v_lshl_add_u64 v[248:249], v[198:199], 0, s[98:99]
	global_load_dwordx4 v[224:227], v[248:249], off offset:528
	global_load_dwordx4 v[228:231], v[248:249], off offset:512
	s_nop 0
	v_pk_fma_f32 v[54:55], v[54:55], v[70:71], v[62:63]
	v_pk_fma_f32 v[58:59], v[58:59], v[74:75], v[66:67]
	v_pk_fma_f32 v[56:57], v[56:57], v[72:73], v[64:65]
	v_pk_fma_f32 v[60:61], v[52:53], v[68:69], v[60:61]
	v_cvt_pk_f16_f32 v55, v54, v55
	v_cvt_pk_f16_f32 v53, v58, v59
	v_cvt_pk_f16_f32 v54, v60, v61
	v_cvt_pk_f16_f32 v52, v56, v57
	v_lshl_add_u64 v[60:61], v[170:171], 0, s[12:13]
	global_store_dwordx4 v[76:77], v[52:55], off offset:256
	v_lshl_add_u64 v[62:63], v[60:61], 2, s[80:81]
	s_nop 1
	s_waitcnt vmcnt(10)
	v_mov_b32_e32 v52, v232
	v_mov_b32_e32 v53, v233
	v_mov_b32_e32 v54, v234
	v_mov_b32_e32 v55, v235
	s_nop 1
	v_mov_b32_e32 v56, v236
	v_mov_b32_e32 v57, v237
	v_mov_b32_e32 v58, v238
	v_mov_b32_e32 v59, v239
	s_mov_b64 s[12:13], 0x50000
	s_nop 0
	v_pk_fma_f32 v[46:47], v[46:47], v[86:87], v[54:55]
	v_pk_fma_f32 v[50:51], v[50:51], v[90:91], v[58:59]
	v_pk_fma_f32 v[48:49], v[48:49], v[88:89], v[56:57]
	v_pk_fma_f32 v[52:53], v[44:45], v[84:85], v[52:53]
	v_cvt_pk_f16_f32 v47, v46, v47
	v_cvt_pk_f16_f32 v45, v50, v51
	v_cvt_pk_f16_f32 v46, v52, v53
	v_cvt_pk_f16_f32 v44, v48, v49
	v_lshl_add_u64 v[52:53], v[60:61], 1, s[16:17]
	global_store_dwordx4 v[52:53], v[44:47], off
	s_nop 1
	s_waitcnt vmcnt(8)
; #define PG8_WAIT_V(n) asm volatile("s_waitcnt vmcnt(" #n ")" ::: "memory")
; #define PG8_BAR __builtin_amdgcn_s_barrier()
; template <class Epi>
; __device__ __forceinline__ void gemm_phase(LAS unsigned char* lds, const Gemm g, const StaticOrder& S, const Epi& E, const int tid) {
;     ...
;         if (!has_next) break;
; #pragma unroll
;         for (int a = 0; a < 2; ++a)
; #pragma unroll
;             for (int b = 0; b < 2; ++b)
; #pragma unroll
;                 for (int m = 0; m < 4; ++m)
; #pragma unroll
;                     for (int n = 0; n < 2; ++n) acc[a][b][m][n] = (f32x4){0.f, 0.f, 0.f, 0.f};
;         cur = nxt; cA = nA; cB = nB; ++ui;
;     }
;     PG8_WAIT_V(0);
;     if (wr == 0) PG8_BAR;
;     PG8_BAR;
;     __device__ __forceinline__ void operator()(const f32x4 (&acc)[2][2][4][2], const pg8::Unit& u, int wr, int wc, int fr, int fq) const {
;     ...
;         for (int ai = 0; ai < 2; ++ai)
; #pragma unroll
;             for (int m = 0; m < 4; ++m) { const size_t ro = (size_t)(row0 + ai * 128 + m * 16) * DM + col0;
; #pragma unroll
;                 for (int bj = 0; bj < 2; ++bj) {
;                     f32x4 x0, x1;
;                     if (XF32) { x0 = *(const f32x4*)(xin + ro + bj * 128); x1 = *(const f32x4*)(xin + ro + bj * 128 + 4); }
;                     else { const h8 xh = *(const h8*)(H + ro + bj * 128); x0 = (f32x4){(float)xh[0], (float)xh[1], (float)xh[2], (float)xh[3]}; x1 = (f32x4){(float)xh[4], (float)xh[5], (float)xh[6], (float)xh[7]}; }
;                     const f32x4 y0 = x0 + gv[bj][0] * acc[ai][bj][m][0], y1 = x1 + gv[bj][1] * acc[ai][bj][m][1];
;                     h8 o; o[0] = (half_t)y0[0]; o[1] = (half_t)y0[1]; o[2] = (half_t)y0[2]; o[3] = (half_t)y0[3]; o[4] = (half_t)y1[0]; o[5] = (half_t)y1[1]; o[6] = (half_t)y1[2]; o[7] = (half_t)y1[3];
;                     *(h8*)(H + ro + bj * 128) = o; } }
	v_mov_b32_e32 v44, v240
	v_mov_b32_e32 v45, v241
	v_mov_b32_e32 v46, v242
	v_mov_b32_e32 v47, v243
	s_nop 0
	s_nop 1
	v_mov_b32_e32 v48, v244
	v_mov_b32_e32 v49, v245
	v_mov_b32_e32 v50, v246
	v_mov_b32_e32 v51, v247
	s_nop 0
	v_pk_fma_f32 v[38:39], v[38:39], v[70:71], v[46:47]
	v_pk_fma_f32 v[42:43], v[42:43], v[74:75], v[50:51]
	v_pk_fma_f32 v[40:41], v[40:41], v[72:73], v[48:49]
	v_pk_fma_f32 v[44:45], v[36:37], v[68:69], v[44:45]
	v_cvt_pk_f16_f32 v39, v38, v39
	v_cvt_pk_f16_f32 v37, v42, v43
	v_cvt_pk_f16_f32 v38, v44, v45
	v_cvt_pk_f16_f32 v36, v40, v41
	v_lshl_add_u64 v[44:45], v[170:171], 0, s[12:13]
	global_store_dwordx4 v[52:53], v[36:39], off offset:256
	v_lshl_add_u64 v[46:47], v[44:45], 2, s[80:81]
	s_nop 1
	s_waitcnt vmcnt(6)
	v_mov_b32_e32 v36, v200
	v_mov_b32_e32 v37, v201
	v_mov_b32_e32 v38, v202
	v_mov_b32_e32 v39, v203
	s_nop 1
	v_mov_b32_e32 v40, v204
	v_mov_b32_e32 v41, v205
	v_mov_b32_e32 v42, v206
	v_mov_b32_e32 v43, v207
	s_mov_b64 s[12:13], 0x58000
	s_nop 0
	v_pk_fma_f32 v[30:31], v[30:31], v[86:87], v[38:39]
	v_pk_fma_f32 v[34:35], v[34:35], v[90:91], v[42:43]
	v_pk_fma_f32 v[32:33], v[32:33], v[88:89], v[40:41]
	v_pk_fma_f32 v[36:37], v[28:29], v[84:85], v[36:37]
	v_cvt_pk_f16_f32 v31, v30, v31
	v_cvt_pk_f16_f32 v29, v34, v35
	v_cvt_pk_f16_f32 v30, v36, v37
	v_cvt_pk_f16_f32 v28, v32, v33
	v_lshl_add_u64 v[36:37], v[44:45], 1, s[16:17]
	global_store_dwordx4 v[36:37], v[28:31], off
	s_nop 1
	s_waitcnt vmcnt(4)
	v_mov_b32_e32 v28, v208
	v_mov_b32_e32 v29, v209
	v_mov_b32_e32 v30, v210
	v_mov_b32_e32 v31, v211
	s_nop 0
	s_nop 1
	v_mov_b32_e32 v32, v212
	v_mov_b32_e32 v33, v213
	v_mov_b32_e32 v34, v214
	v_mov_b32_e32 v35, v215
	s_nop 0
	v_pk_fma_f32 v[22:23], v[22:23], v[70:71], v[30:31]
	v_pk_fma_f32 v[26:27], v[26:27], v[74:75], v[34:35]
	v_pk_fma_f32 v[24:25], v[24:25], v[72:73], v[32:33]
	v_pk_fma_f32 v[28:29], v[20:21], v[68:69], v[28:29]
	v_cvt_pk_f16_f32 v23, v22, v23
	v_cvt_pk_f16_f32 v21, v26, v27
	v_cvt_pk_f16_f32 v22, v28, v29
	v_cvt_pk_f16_f32 v20, v24, v25
	v_lshl_add_u64 v[28:29], v[170:171], 0, s[12:13]
	global_store_dwordx4 v[36:37], v[20:23], off offset:256
	v_lshl_add_u64 v[30:31], v[28:29], 2, s[80:81]
	s_nop 1
	s_waitcnt vmcnt(2)
	v_mov_b32_e32 v20, v216
	v_mov_b32_e32 v21, v217
	v_mov_b32_e32 v22, v218
	v_mov_b32_e32 v23, v219
	s_nop 1
	v_mov_b32_e32 v24, v220
	v_mov_b32_e32 v25, v221
	v_mov_b32_e32 v26, v222
	v_mov_b32_e32 v27, v223
	s_mov_b64 s[12:13], s[8:9]
	s_nop 0
	v_pk_fma_f32 v[14:15], v[14:15], v[86:87], v[22:23]
	v_pk_fma_f32 v[18:19], v[18:19], v[90:91], v[26:27]
	v_pk_fma_f32 v[16:17], v[16:17], v[88:89], v[24:25]
	v_pk_fma_f32 v[20:21], v[12:13], v[84:85], v[20:21]
	v_cvt_pk_f16_f32 v15, v14, v15
	v_cvt_pk_f16_f32 v13, v18, v19
	v_cvt_pk_f16_f32 v14, v20, v21
	v_cvt_pk_f16_f32 v12, v16, v17
	v_lshl_add_u64 v[20:21], v[28:29], 1, s[16:17]
	global_store_dwordx4 v[20:21], v[12:15], off
	s_nop 1
	s_waitcnt vmcnt(0)
	v_mov_b32_e32 v12, v224
	v_mov_b32_e32 v13, v225
	v_mov_b32_e32 v14, v226
	v_mov_b32_e32 v15, v227
	s_nop 0
	s_nop 1
	v_mov_b32_e32 v16, v228
	v_mov_b32_e32 v17, v229
	v_mov_b32_e32 v18, v230
	v_mov_b32_e32 v19, v231
	s_nop 0
	v_pk_fma_f32 v[6:7], v[6:7], v[70:71], v[14:15]
	v_pk_fma_f32 v[10:11], v[10:11], v[74:75], v[18:19]
	v_pk_fma_f32 v[8:9], v[8:9], v[72:73], v[16:17]
	v_pk_fma_f32 v[12:13], v[4:5], v[68:69], v[12:13]
	v_cvt_pk_f16_f32 v7, v6, v7
	v_cvt_pk_f16_f32 v5, v10, v11
	v_cvt_pk_f16_f32 v6, v12, v13
	v_cvt_pk_f16_f32 v4, v8, v9
	global_store_dwordx4 v[20:21], v[4:7], off offset:256
	s_cbranch_vccz .LBB0_671
	s_waitcnt vmcnt(0)
	v_readlane_b32 s42, v251, 7
	v_readlane_b32 s46, v251, 9
	v_readlane_b32 s48, v251, 13
	s_cmpk_gt_u32 s25, 0xff
	v_readlane_b32 s43, v251, 8
	v_readlane_b32 s47, v251, 10
	v_readlane_b32 s49, v251, 14
	s_cbranch_scc1 .LBB0_682
	s_barrier
